# GEMM K-loops: the back-to-back s_setprio 0 / s_setprio 1 pair between the two 8-MFMA groups of every phase deleted (8 scalar issue slots per iteration), on top of the kept version
# speedup vs baseline: 1.0015x; 1.0015x over previous
; #define PG8_STAGE(bufoff, gbase, voff) do { _Pragma("unroll") for (int _i = 0; _i < 2; ++_i) \
;         __builtin_amdgcn_global_load_lds((const unsigned*)((const char*)(gbase) + (voff)[_i]), (LAS unsigned*)(lds + (bufoff) + ldsw + _i * 8192), 16, 0, 0); } while (0)
; #define PG8_LDA(dst, b, h) do { _Pragma("unroll") for (int m = 0; m < 4; ++m) _Pragma("unroll") for (int k = 0; k < 2; ++k) dst[m][k] = *(const LAS bf16x8*)(lds + PG8_SA(b, h) + aoff + m * 2048 + k * 1024); } while (0)
; #define PG8_LDB(dst, b, h) do { _Pragma("unroll") for (int n = 0; n < 2; ++n) _Pragma("unroll") for (int k = 0; k < 2; ++k) dst[n][k] = *(const LAS bf16x8*)(lds + PG8_SB(b, h) + boff + n * 2048 + k * 1024); } while (0)
; #define PG8_WAIT_V(n) asm volatile("s_waitcnt vmcnt(" #n ")" ::: "memory")
; #define PG8_BAR __builtin_amdgcn_s_barrier()
; template <class Epi, bool ALIGN_EPI = PG8_ALIGN>
; __device__ __forceinline__ void gemm_phase(LAS unsigned char* lds, const Gemm g, const StaticOrder& S, const Epi& E) {
;     ...
;         for (int t = 0; t < nt; t += 2) {
;             const bool last = (t == nt - 2);
;             const char* a1 = cA + (size_t)(t + 1) * kstep;
;             const char* a2 = last ? nA : cA + (size_t)(t + 2) * kstep; const char* b2 = last ? nB : cB + (size_t)(t + 2) * kstep;
;             const char* a3 = a2 + kstep; const char* b3 = b2 + kstep;
;             PG8_LDB(B0, 0, 0); PG8_LDB(B1, 0, 1); PG8_SCHED; PG8_LDA(At, 0, 0); PG8_STAGE(PG8_SA(1, 1), a1 + hstepA, voffA);
;             PG8_WAIT_V(8); PG8_WAIT_L(0); PG8_BAR; PG8_MMA(0, 0, At, B0); PG8_MMA(0, 1, At, B1); PG8_BAR; PG8_SCHED;
;             PG8_LDA(At, 0, 1); PG8_STAGE(PG8_SB(0, 0), b2, voffB); PG8_STAGE(PG8_SB(0, 1), b2 + hstepB, voffB); PG8_STAGE(PG8_SA(0, 0), a2, voffA);
;             PG8_WAIT_V(8); PG8_WAIT_L(0); PG8_BAR; PG8_MMA(1, 0, At, B0); PG8_MMA(1, 1, At, B1); PG8_BAR; PG8_SCHED;
;             PG8_LDB(B0, 1, 0); PG8_LDB(B1, 1, 1); PG8_SCHED; PG8_LDA(At, 1, 0); PG8_STAGE(PG8_SA(0, 1), a2 + hstepA, voffA);
;             PG8_WAIT_V(8); PG8_WAIT_L(0); PG8_BAR; PG8_MMA(0, 0, At, B0); PG8_MMA(0, 1, At, B1); PG8_BAR; PG8_SCHED;
;             PG8_LDA(At, 1, 1); PG8_STAGE(PG8_SB(1, 0), b3, voffB); PG8_STAGE(PG8_SB(1, 1), b3 + hstepB, voffB); PG8_STAGE(PG8_SA(1, 0), a3, voffA);
;             PG8_WAIT_V(8); PG8_WAIT_L(0); PG8_BAR; PG8_MMA(1, 0, At, B0); PG8_MMA(1, 1, At, B1); PG8_BAR; PG8_SCHED;
.LBB0_219:
	s_add_i32 s49, s24, 2
	s_add_u32 s20, s2, 0xfff80080
	s_addc_u32 s21, s3, -1
	s_add_i32 s22, 16, 0x10000
	s_cmp_eq_u32 s46, s24
	s_cselect_b32 s25, s15, s21
	s_cselect_b32 s24, s34, s20
	s_cselect_b32 s51, s17, s37
	s_cselect_b32 s50, s16, s36
	s_add_i32 s20, 16, 0x14000
	v_add_u32_e32 v154, s22, v139
	v_add_u32_e32 v170, s20, v139
	ds_read_b128 v[142:145], v154
	ds_read_b128 v[146:149], v154 offset:1024
	ds_read_b128 v[150:153], v154 offset:2048
	ds_read_b128 v[154:157], v154 offset:3072
	ds_read_b128 v[158:161], v170
	ds_read_b128 v[162:165], v170 offset:1024
	ds_read_b128 v[166:169], v170 offset:2048
	ds_read_b128 v[170:173], v170 offset:3072
	v_lshl_add_u64 v[174:175], s[2:3], 0, v[134:135]
	s_add_i32 m0, s29, 0xc000
	ds_read_b128 v[184:187], v141
	ds_read_b128 v[188:191], v141 offset:1024
	ds_read_b128 v[192:195], v141 offset:2048
	ds_read_b128 v[196:199], v141 offset:3072
	ds_read_b128 v[200:203], v141 offset:4096
	ds_read_b128 v[204:207], v141 offset:5120
	ds_read_b128 v[208:211], v141 offset:6144
	ds_read_b128 v[212:215], v141 offset:7168
	global_load_lds_dwordx4 v[174:175], off
	v_lshl_add_u64 v[174:175], s[2:3], 0, v[136:137]
	s_add_i32 m0, s29, 0xe000
	s_nop 0
	global_load_lds_dwordx4 v[174:175], off
	s_waitcnt vmcnt(8)
	s_waitcnt lgkmcnt(0)
	s_barrier
	s_setprio 1
	s_waitcnt lgkmcnt(0)
	v_mfma_f32_16x16x32_bf16 v[124:127], v[142:145], v[184:187], v[124:127]
	v_mfma_f32_16x16x32_bf16 v[116:119], v[150:153], v[184:187], v[116:119]
	v_mfma_f32_16x16x32_bf16 v[108:111], v[142:145], v[192:195], v[108:111]
	v_mfma_f32_16x16x32_bf16 v[100:103], v[150:153], v[192:195], v[100:103]
	v_mfma_f32_16x16x32_bf16 v[92:95], v[142:145], v[200:203], v[92:95]
	v_mfma_f32_16x16x32_bf16 v[84:87], v[150:153], v[200:203], v[84:87]
	v_mfma_f32_16x16x32_bf16 v[76:79], v[142:145], v[208:211], v[76:79]
	v_mfma_f32_16x16x32_bf16 v[68:71], v[150:153], v[208:211], v[68:71]
	v_mfma_f32_16x16x32_bf16 v[124:127], v[146:149], v[188:191], v[124:127]
	v_mfma_f32_16x16x32_bf16 v[116:119], v[154:157], v[188:191], v[116:119]
	v_mfma_f32_16x16x32_bf16 v[108:111], v[146:149], v[196:199], v[108:111]
	v_mfma_f32_16x16x32_bf16 v[100:103], v[154:157], v[196:199], v[100:103]
	v_mfma_f32_16x16x32_bf16 v[92:95], v[146:149], v[204:207], v[92:95]
	v_mfma_f32_16x16x32_bf16 v[84:87], v[154:157], v[204:207], v[84:87]
	v_mfma_f32_16x16x32_bf16 v[76:79], v[146:149], v[212:215], v[76:79]
	v_mfma_f32_16x16x32_bf16 v[68:71], v[154:157], v[212:215], v[68:71]
	v_mfma_f32_16x16x32_bf16 v[120:123], v[158:161], v[184:187], v[120:123]
	v_mfma_f32_16x16x32_bf16 v[112:115], v[166:169], v[184:187], v[112:115]
	v_mfma_f32_16x16x32_bf16 v[104:107], v[158:161], v[192:195], v[104:107]
	v_mfma_f32_16x16x32_bf16 v[96:99], v[166:169], v[192:195], v[96:99]
	v_mfma_f32_16x16x32_bf16 v[88:91], v[158:161], v[200:203], v[88:91]
	v_mfma_f32_16x16x32_bf16 v[80:83], v[166:169], v[200:203], v[80:83]
	v_mfma_f32_16x16x32_bf16 v[72:75], v[158:161], v[208:211], v[72:75]
	v_mfma_f32_16x16x32_bf16 v[64:67], v[166:169], v[208:211], v[64:67]
	v_mfma_f32_16x16x32_bf16 v[120:123], v[162:165], v[188:191], v[120:123]
	v_mfma_f32_16x16x32_bf16 v[112:115], v[170:173], v[188:191], v[112:115]
	v_mfma_f32_16x16x32_bf16 v[104:107], v[162:165], v[196:199], v[104:107]
	v_mfma_f32_16x16x32_bf16 v[96:99], v[170:173], v[196:199], v[96:99]
	v_mfma_f32_16x16x32_bf16 v[88:91], v[162:165], v[204:207], v[88:91]
	v_mfma_f32_16x16x32_bf16 v[80:83], v[170:173], v[204:207], v[80:83]
	v_mfma_f32_16x16x32_bf16 v[72:75], v[162:165], v[212:215], v[72:75]
	v_mfma_f32_16x16x32_bf16 v[64:67], v[170:173], v[212:215], v[64:67]
	s_setprio 0
	s_barrier
	s_add_i32 s21, s22, s18
	v_lshl_add_u64 v[174:175], s[50:51], 0, v[176:177]
	s_mov_b32 m0, s21
	ds_read_b128 v[184:187], v141 offset:16384
	ds_read_b128 v[188:191], v141 offset:17408
	ds_read_b128 v[192:195], v141 offset:18432
	ds_read_b128 v[196:199], v141 offset:19456
	ds_read_b128 v[200:203], v141 offset:20480
	ds_read_b128 v[204:207], v141 offset:21504
	ds_read_b128 v[208:211], v141 offset:22528
	ds_read_b128 v[212:215], v141 offset:23552
	global_load_lds_dwordx4 v[174:175], off
	s_add_i32 m0, s21, 0x2000
	v_lshl_add_u64 v[216:217], s[50:51], 0, v[128:129]
	s_add_u32 s50, s50, s4
	s_addc_u32 s51, s51, s5
	s_add_i32 s20, s20, s18
	global_load_lds_dwordx4 v[216:217], off
	v_lshl_add_u64 v[218:219], s[50:51], 0, v[176:177]
	s_mov_b32 m0, s20
	v_lshl_add_u64 v[220:221], s[50:51], 0, v[128:129]
	global_load_lds_dwordx4 v[218:219], off
	s_add_i32 m0, s20, 0x2000
	v_lshl_add_u64 v[222:223], s[24:25], 0, v[132:133]
	global_load_lds_dwordx4 v[220:221], off
	s_mov_b32 m0, s29
	v_lshl_add_u64 v[224:225], s[24:25], 0, v[130:131]
	global_load_lds_dwordx4 v[222:223], off
	s_mov_b32 m0, s30
	s_nop 0
	global_load_lds_dwordx4 v[224:225], off
	s_waitcnt vmcnt(8)
	s_waitcnt lgkmcnt(0)
	s_barrier
; #define PG8_STAGE(bufoff, gbase, voff) do { _Pragma("unroll") for (int _i = 0; _i < 2; ++_i) \
;         __builtin_amdgcn_global_load_lds((const unsigned*)((const char*)(gbase) + (voff)[_i]), (LAS unsigned*)(lds + (bufoff) + ldsw + _i * 8192), 16, 0, 0); } while (0)
; #define PG8_LDA(dst, b, h) do { _Pragma("unroll") for (int m = 0; m < 4; ++m) _Pragma("unroll") for (int k = 0; k < 2; ++k) dst[m][k] = *(const LAS bf16x8*)(lds + PG8_SA(b, h) + aoff + m * 2048 + k * 1024); } while (0)
; #define PG8_LDB(dst, b, h) do { _Pragma("unroll") for (int n = 0; n < 2; ++n) _Pragma("unroll") for (int k = 0; k < 2; ++k) dst[n][k] = *(const LAS bf16x8*)(lds + PG8_SB(b, h) + boff + n * 2048 + k * 1024); } while (0)
; #define PG8_WAIT_V(n) asm volatile("s_waitcnt vmcnt(" #n ")" ::: "memory")
; #define PG8_BAR __builtin_amdgcn_s_barrier()
; template <class Epi, bool ALIGN_EPI = PG8_ALIGN>
; __device__ __forceinline__ void gemm_phase(LAS unsigned char* lds, const Gemm g, const StaticOrder& S, const Epi& E) {
;     ...
;         for (int t = 0; t < nt; t += 2) {
;             const bool last = (t == nt - 2);
;             const char* a1 = cA + (size_t)(t + 1) * kstep;
;             const char* a2 = last ? nA : cA + (size_t)(t + 2) * kstep; const char* b2 = last ? nB : cB + (size_t)(t + 2) * kstep;
;             const char* a3 = a2 + kstep; const char* b3 = b2 + kstep;
;             PG8_LDB(B0, 0, 0); PG8_LDB(B1, 0, 1); PG8_SCHED; PG8_LDA(At, 0, 0); PG8_STAGE(PG8_SA(1, 1), a1 + hstepA, voffA);
;             PG8_WAIT_V(8); PG8_WAIT_L(0); PG8_BAR; PG8_MMA(0, 0, At, B0); PG8_MMA(0, 1, At, B1); PG8_BAR; PG8_SCHED;
;             PG8_LDA(At, 0, 1); PG8_STAGE(PG8_SB(0, 0), b2, voffB); PG8_STAGE(PG8_SB(0, 1), b2 + hstepB, voffB); PG8_STAGE(PG8_SA(0, 0), a2, voffA);
;             PG8_WAIT_V(8); PG8_WAIT_L(0); PG8_BAR; PG8_MMA(1, 0, At, B0); PG8_MMA(1, 1, At, B1); PG8_BAR; PG8_SCHED;
;             PG8_LDB(B0, 1, 0); PG8_LDB(B1, 1, 1); PG8_SCHED; PG8_LDA(At, 1, 0); PG8_STAGE(PG8_SA(0, 1), a2 + hstepA, voffA);
;             PG8_WAIT_V(8); PG8_WAIT_L(0); PG8_BAR; PG8_MMA(0, 0, At, B0); PG8_MMA(0, 1, At, B1); PG8_BAR; PG8_SCHED;
;             PG8_LDA(At, 1, 1); PG8_STAGE(PG8_SB(1, 0), b3, voffB); PG8_STAGE(PG8_SB(1, 1), b3 + hstepB, voffB); PG8_STAGE(PG8_SA(1, 0), a3, voffA);
;             PG8_WAIT_V(8); PG8_WAIT_L(0); PG8_BAR; PG8_MMA(1, 0, At, B0); PG8_MMA(1, 1, At, B1); PG8_BAR; PG8_SCHED;
	s_setprio 1
	s_waitcnt lgkmcnt(0)
	v_mfma_f32_16x16x32_bf16 v[60:63], v[142:145], v[184:187], v[60:63]
	v_mfma_f32_16x16x32_bf16 v[52:55], v[150:153], v[184:187], v[52:55]
	v_mfma_f32_16x16x32_bf16 v[44:47], v[142:145], v[192:195], v[44:47]
	v_mfma_f32_16x16x32_bf16 v[36:39], v[150:153], v[192:195], v[36:39]
	v_mfma_f32_16x16x32_bf16 v[28:31], v[142:145], v[200:203], v[28:31]
	v_mfma_f32_16x16x32_bf16 v[20:23], v[150:153], v[200:203], v[20:23]
	v_mfma_f32_16x16x32_bf16 v[12:15], v[142:145], v[208:211], v[12:15]
	v_mfma_f32_16x16x32_bf16 v[4:7], v[150:153], v[208:211], v[4:7]
	v_mfma_f32_16x16x32_bf16 v[60:63], v[146:149], v[188:191], v[60:63]
	v_mfma_f32_16x16x32_bf16 v[52:55], v[154:157], v[188:191], v[52:55]
	v_mfma_f32_16x16x32_bf16 v[44:47], v[146:149], v[196:199], v[44:47]
	v_mfma_f32_16x16x32_bf16 v[36:39], v[154:157], v[196:199], v[36:39]
	v_mfma_f32_16x16x32_bf16 v[28:31], v[146:149], v[204:207], v[28:31]
	v_mfma_f32_16x16x32_bf16 v[20:23], v[154:157], v[204:207], v[20:23]
	v_mfma_f32_16x16x32_bf16 v[12:15], v[146:149], v[212:215], v[12:15]
	v_mfma_f32_16x16x32_bf16 v[4:7], v[154:157], v[212:215], v[4:7]
	v_mfma_f32_16x16x32_bf16 v[56:59], v[158:161], v[184:187], v[56:59]
	v_mfma_f32_16x16x32_bf16 v[48:51], v[166:169], v[184:187], v[48:51]
	v_mfma_f32_16x16x32_bf16 v[40:43], v[158:161], v[192:195], v[40:43]
	v_mfma_f32_16x16x32_bf16 v[32:35], v[166:169], v[192:195], v[32:35]
	v_mfma_f32_16x16x32_bf16 v[24:27], v[158:161], v[200:203], v[24:27]
	v_mfma_f32_16x16x32_bf16 v[16:19], v[166:169], v[200:203], v[16:19]
	v_mfma_f32_16x16x32_bf16 v[8:11], v[158:161], v[208:211], v[8:11]
	v_mfma_f32_16x16x32_bf16 v[0:3], v[166:169], v[208:211], v[0:3]
	v_mfma_f32_16x16x32_bf16 v[56:59], v[162:165], v[188:191], v[56:59]
	v_mfma_f32_16x16x32_bf16 v[48:51], v[170:173], v[188:191], v[48:51]
	v_mfma_f32_16x16x32_bf16 v[40:43], v[162:165], v[196:199], v[40:43]
	v_mfma_f32_16x16x32_bf16 v[32:35], v[170:173], v[196:199], v[32:35]
	v_mfma_f32_16x16x32_bf16 v[24:27], v[162:165], v[204:207], v[24:27]
	v_mfma_f32_16x16x32_bf16 v[16:19], v[170:173], v[204:207], v[16:19]
	v_mfma_f32_16x16x32_bf16 v[8:11], v[162:165], v[212:215], v[8:11]
	v_mfma_f32_16x16x32_bf16 v[0:3], v[170:173], v[212:215], v[0:3]
	s_setprio 0
	s_barrier
	s_add_i32 s20, 16, 0x18000
	s_add_i32 s21, 16, 0x1c000
	v_add_u32_e32 v154, s20, v139
	v_add_u32_e32 v170, s21, v139
	ds_read_b128 v[142:145], v154
	ds_read_b128 v[146:149], v154 offset:1024
	ds_read_b128 v[150:153], v154 offset:2048
	ds_read_b128 v[154:157], v154 offset:3072
	ds_read_b128 v[158:161], v170
	ds_read_b128 v[162:165], v170 offset:1024
	ds_read_b128 v[166:169], v170 offset:2048
	ds_read_b128 v[170:173], v170 offset:3072
	s_add_u32 s24, s24, 0x80000
	s_addc_u32 s25, s25, 0
	s_mov_b32 m0, s31
	v_lshl_add_u64 v[226:227], s[24:25], 0, v[132:133]
	ds_read_b128 v[184:187], v141 offset:32768
	ds_read_b128 v[188:191], v141 offset:33792
	ds_read_b128 v[192:195], v141 offset:34816
	ds_read_b128 v[196:199], v141 offset:35840
	ds_read_b128 v[200:203], v141 offset:36864
	ds_read_b128 v[204:207], v141 offset:37888
	ds_read_b128 v[208:211], v141 offset:38912
	ds_read_b128 v[212:215], v141 offset:39936
	global_load_lds_dwordx4 v[226:227], off
	v_lshl_add_u64 v[226:227], s[24:25], 0, v[130:131]
	s_mov_b32 m0, s42
	s_nop 0
	global_load_lds_dwordx4 v[226:227], off
	s_waitcnt vmcnt(8)
	s_waitcnt lgkmcnt(0)
	s_barrier
	s_setprio 1
	s_waitcnt lgkmcnt(0)
	v_mfma_f32_16x16x32_bf16 v[124:127], v[142:145], v[184:187], v[124:127]
	v_mfma_f32_16x16x32_bf16 v[116:119], v[150:153], v[184:187], v[116:119]
	v_mfma_f32_16x16x32_bf16 v[108:111], v[142:145], v[192:195], v[108:111]
	v_mfma_f32_16x16x32_bf16 v[100:103], v[150:153], v[192:195], v[100:103]
	v_mfma_f32_16x16x32_bf16 v[92:95], v[142:145], v[200:203], v[92:95]
	v_mfma_f32_16x16x32_bf16 v[84:87], v[150:153], v[200:203], v[84:87]
	v_mfma_f32_16x16x32_bf16 v[76:79], v[142:145], v[208:211], v[76:79]
	v_mfma_f32_16x16x32_bf16 v[68:71], v[150:153], v[208:211], v[68:71]
	v_mfma_f32_16x16x32_bf16 v[124:127], v[146:149], v[188:191], v[124:127]
	v_mfma_f32_16x16x32_bf16 v[116:119], v[154:157], v[188:191], v[116:119]
	v_mfma_f32_16x16x32_bf16 v[108:111], v[146:149], v[196:199], v[108:111]
	v_mfma_f32_16x16x32_bf16 v[100:103], v[154:157], v[196:199], v[100:103]
	v_mfma_f32_16x16x32_bf16 v[92:95], v[146:149], v[204:207], v[92:95]
	v_mfma_f32_16x16x32_bf16 v[84:87], v[154:157], v[204:207], v[84:87]
	v_mfma_f32_16x16x32_bf16 v[76:79], v[146:149], v[212:215], v[76:79]
	v_mfma_f32_16x16x32_bf16 v[68:71], v[154:157], v[212:215], v[68:71]
	v_mfma_f32_16x16x32_bf16 v[120:123], v[158:161], v[184:187], v[120:123]
	v_mfma_f32_16x16x32_bf16 v[112:115], v[166:169], v[184:187], v[112:115]
	v_mfma_f32_16x16x32_bf16 v[104:107], v[158:161], v[192:195], v[104:107]
	v_mfma_f32_16x16x32_bf16 v[96:99], v[166:169], v[192:195], v[96:99]
	v_mfma_f32_16x16x32_bf16 v[88:91], v[158:161], v[200:203], v[88:91]
	v_mfma_f32_16x16x32_bf16 v[80:83], v[166:169], v[200:203], v[80:83]
	v_mfma_f32_16x16x32_bf16 v[72:75], v[158:161], v[208:211], v[72:75]
	v_mfma_f32_16x16x32_bf16 v[64:67], v[166:169], v[208:211], v[64:67]
	v_mfma_f32_16x16x32_bf16 v[120:123], v[162:165], v[188:191], v[120:123]
	v_mfma_f32_16x16x32_bf16 v[112:115], v[170:173], v[188:191], v[112:115]
	v_mfma_f32_16x16x32_bf16 v[104:107], v[162:165], v[196:199], v[104:107]
	v_mfma_f32_16x16x32_bf16 v[96:99], v[170:173], v[196:199], v[96:99]
	v_mfma_f32_16x16x32_bf16 v[88:91], v[162:165], v[204:207], v[88:91]
	v_mfma_f32_16x16x32_bf16 v[80:83], v[170:173], v[204:207], v[80:83]
	v_mfma_f32_16x16x32_bf16 v[72:75], v[162:165], v[212:215], v[72:75]
	v_mfma_f32_16x16x32_bf16 v[64:67], v[170:173], v[212:215], v[64:67]
	s_setprio 0
	s_barrier
; #define PG8_STAGE(bufoff, gbase, voff) do { _Pragma("unroll") for (int _i = 0; _i < 2; ++_i) \
;         __builtin_amdgcn_global_load_lds((const unsigned*)((const char*)(gbase) + (voff)[_i]), (LAS unsigned*)(lds + (bufoff) + ldsw + _i * 8192), 16, 0, 0); } while (0)
; #define PG8_LDA(dst, b, h) do { _Pragma("unroll") for (int m = 0; m < 4; ++m) _Pragma("unroll") for (int k = 0; k < 2; ++k) dst[m][k] = *(const LAS bf16x8*)(lds + PG8_SA(b, h) + aoff + m * 2048 + k * 1024); } while (0)
; #define PG8_LDB(dst, b, h) do { _Pragma("unroll") for (int n = 0; n < 2; ++n) _Pragma("unroll") for (int k = 0; k < 2; ++k) dst[n][k] = *(const LAS bf16x8*)(lds + PG8_SB(b, h) + boff + n * 2048 + k * 1024); } while (0)
; #define PG8_WAIT_V(n) asm volatile("s_waitcnt vmcnt(" #n ")" ::: "memory")
; #define PG8_BAR __builtin_amdgcn_s_barrier()
; template <class Epi, bool ALIGN_EPI = PG8_ALIGN>
; __device__ __forceinline__ void gemm_phase(LAS unsigned char* lds, const Gemm g, const StaticOrder& S, const Epi& E) {
;     ...
;         for (int t = 0; t < nt; t += 2) {
;             const bool last = (t == nt - 2);
;             const char* a1 = cA + (size_t)(t + 1) * kstep;
;             const char* a2 = last ? nA : cA + (size_t)(t + 2) * kstep; const char* b2 = last ? nB : cB + (size_t)(t + 2) * kstep;
;             const char* a3 = a2 + kstep; const char* b3 = b2 + kstep;
;             PG8_LDB(B0, 0, 0); PG8_LDB(B1, 0, 1); PG8_SCHED; PG8_LDA(At, 0, 0); PG8_STAGE(PG8_SA(1, 1), a1 + hstepA, voffA);
;             PG8_WAIT_V(8); PG8_WAIT_L(0); PG8_BAR; PG8_MMA(0, 0, At, B0); PG8_MMA(0, 1, At, B1); PG8_BAR; PG8_SCHED;
;             PG8_LDA(At, 0, 1); PG8_STAGE(PG8_SB(0, 0), b2, voffB); PG8_STAGE(PG8_SB(0, 1), b2 + hstepB, voffB); PG8_STAGE(PG8_SA(0, 0), a2, voffA);
;             PG8_WAIT_V(8); PG8_WAIT_L(0); PG8_BAR; PG8_MMA(1, 0, At, B0); PG8_MMA(1, 1, At, B1); PG8_BAR; PG8_SCHED;
;             PG8_LDB(B0, 1, 0); PG8_LDB(B1, 1, 1); PG8_SCHED; PG8_LDA(At, 1, 0); PG8_STAGE(PG8_SA(0, 1), a2 + hstepA, voffA);
;             PG8_WAIT_V(8); PG8_WAIT_L(0); PG8_BAR; PG8_MMA(0, 0, At, B0); PG8_MMA(0, 1, At, B1); PG8_BAR; PG8_SCHED;
;             PG8_LDA(At, 1, 1); PG8_STAGE(PG8_SB(1, 0), b3, voffB); PG8_STAGE(PG8_SB(1, 1), b3 + hstepB, voffB); PG8_STAGE(PG8_SA(1, 0), a3, voffA);
;             PG8_WAIT_V(8); PG8_WAIT_L(0); PG8_BAR; PG8_MMA(1, 0, At, B0); PG8_MMA(1, 1, At, B1); PG8_BAR; PG8_SCHED;
	s_add_i32 s20, s20, s18
	v_lshl_add_u64 v[174:175], v[174:175], 0, s[0:1]
	s_mov_b32 m0, s20
	ds_read_b128 v[184:187], v141 offset:49152
	ds_read_b128 v[188:191], v141 offset:50176
	ds_read_b128 v[192:195], v141 offset:51200
	ds_read_b128 v[196:199], v141 offset:52224
	ds_read_b128 v[200:203], v141 offset:53248
	ds_read_b128 v[204:207], v141 offset:54272
	ds_read_b128 v[208:211], v141 offset:55296
	ds_read_b128 v[212:215], v141 offset:56320
	global_load_lds_dwordx4 v[174:175], off
	v_lshl_add_u64 v[174:175], v[216:217], 0, s[0:1]
	s_add_i32 m0, s20, 0x2000
	s_add_i32 s20, s21, s18
	global_load_lds_dwordx4 v[174:175], off
	v_lshl_add_u64 v[174:175], v[218:219], 0, s[0:1]
	s_mov_b32 m0, s20
	s_nop 0
	global_load_lds_dwordx4 v[174:175], off
	v_lshl_add_u64 v[174:175], v[220:221], 0, s[0:1]
	s_add_i32 m0, s20, 0x2000
	s_nop 0
	global_load_lds_dwordx4 v[174:175], off
	v_lshl_add_u64 v[174:175], v[222:223], 0, s[0:1]
	s_mov_b32 m0, s43
	s_nop 0
	global_load_lds_dwordx4 v[174:175], off
	v_lshl_add_u64 v[174:175], v[224:225], 0, s[0:1]
	s_mov_b32 m0, s44
	s_nop 0
	global_load_lds_dwordx4 v[174:175], off
	s_waitcnt vmcnt(8)
	s_waitcnt lgkmcnt(0)
	s_barrier
	s_setprio 1
	s_waitcnt lgkmcnt(0)
	v_mfma_f32_16x16x32_bf16 v[60:63], v[142:145], v[184:187], v[60:63]
	v_mfma_f32_16x16x32_bf16 v[52:55], v[150:153], v[184:187], v[52:55]
	v_mfma_f32_16x16x32_bf16 v[44:47], v[142:145], v[192:195], v[44:47]
	v_mfma_f32_16x16x32_bf16 v[36:39], v[150:153], v[192:195], v[36:39]
	v_mfma_f32_16x16x32_bf16 v[28:31], v[142:145], v[200:203], v[28:31]
	v_mfma_f32_16x16x32_bf16 v[20:23], v[150:153], v[200:203], v[20:23]
	v_mfma_f32_16x16x32_bf16 v[12:15], v[142:145], v[208:211], v[12:15]
	v_mfma_f32_16x16x32_bf16 v[4:7], v[150:153], v[208:211], v[4:7]
	v_mfma_f32_16x16x32_bf16 v[60:63], v[146:149], v[188:191], v[60:63]
	v_mfma_f32_16x16x32_bf16 v[52:55], v[154:157], v[188:191], v[52:55]
	v_mfma_f32_16x16x32_bf16 v[44:47], v[146:149], v[196:199], v[44:47]
	v_mfma_f32_16x16x32_bf16 v[36:39], v[154:157], v[196:199], v[36:39]
	v_mfma_f32_16x16x32_bf16 v[28:31], v[146:149], v[204:207], v[28:31]
	v_mfma_f32_16x16x32_bf16 v[20:23], v[154:157], v[204:207], v[20:23]
	v_mfma_f32_16x16x32_bf16 v[12:15], v[146:149], v[212:215], v[12:15]
	v_mfma_f32_16x16x32_bf16 v[4:7], v[154:157], v[212:215], v[4:7]
	v_mfma_f32_16x16x32_bf16 v[56:59], v[158:161], v[184:187], v[56:59]
	v_mfma_f32_16x16x32_bf16 v[48:51], v[166:169], v[184:187], v[48:51]
	v_mfma_f32_16x16x32_bf16 v[40:43], v[158:161], v[192:195], v[40:43]
	v_mfma_f32_16x16x32_bf16 v[32:35], v[166:169], v[192:195], v[32:35]
	v_mfma_f32_16x16x32_bf16 v[24:27], v[158:161], v[200:203], v[24:27]
	v_mfma_f32_16x16x32_bf16 v[16:19], v[166:169], v[200:203], v[16:19]
	v_mfma_f32_16x16x32_bf16 v[8:11], v[158:161], v[208:211], v[8:11]
	v_mfma_f32_16x16x32_bf16 v[0:3], v[166:169], v[208:211], v[0:3]
	v_mfma_f32_16x16x32_bf16 v[56:59], v[162:165], v[188:191], v[56:59]
	v_mfma_f32_16x16x32_bf16 v[48:51], v[170:173], v[188:191], v[48:51]
	v_mfma_f32_16x16x32_bf16 v[40:43], v[162:165], v[196:199], v[40:43]
	v_mfma_f32_16x16x32_bf16 v[32:35], v[170:173], v[196:199], v[32:35]
	v_mfma_f32_16x16x32_bf16 v[24:27], v[162:165], v[204:207], v[24:27]
	v_mfma_f32_16x16x32_bf16 v[16:19], v[170:173], v[204:207], v[16:19]
	v_mfma_f32_16x16x32_bf16 v[8:11], v[162:165], v[212:215], v[8:11]
	v_mfma_f32_16x16x32_bf16 v[0:3], v[170:173], v[212:215], v[0:3]
	s_setprio 0
	s_barrier
	s_add_u32 s2, s2, 0x100
	s_addc_u32 s3, s3, 0
	s_add_u32 s36, s36, 0x100
	s_addc_u32 s37, s37, 0
	s_cmp_ge_i32 s49, s45
	s_mov_b32 s24, s49
	s_cbranch_scc0 .LBB0_219

; #define PG8_STAGE(bufoff, gbase, voff) do { _Pragma("unroll") for (int _i = 0; _i < 2; ++_i) \
;         __builtin_amdgcn_global_load_lds((const unsigned*)((const char*)(gbase) + (voff)[_i]), (LAS unsigned*)(lds + (bufoff) + ldsw + _i * 8192), 16, 0, 0); } while (0)
; #define PG8_LDA(dst, b, h) do { _Pragma("unroll") for (int m = 0; m < 4; ++m) _Pragma("unroll") for (int k = 0; k < 2; ++k) dst[m][k] = *(const LAS bf16x8*)(lds + PG8_SA(b, h) + aoff + m * 2048 + k * 1024); } while (0)
; #define PG8_LDB(dst, b, h) do { _Pragma("unroll") for (int n = 0; n < 2; ++n) _Pragma("unroll") for (int k = 0; k < 2; ++k) dst[n][k] = *(const LAS bf16x8*)(lds + PG8_SB(b, h) + boff + n * 2048 + k * 1024); } while (0)
; #define PG8_WAIT_V(n) asm volatile("s_waitcnt vmcnt(" #n ")" ::: "memory")
; #define PG8_BAR __builtin_amdgcn_s_barrier()
; template <class Epi, bool ALIGN_EPI = PG8_ALIGN>
; __device__ __forceinline__ void gemm_phase(LAS unsigned char* lds, const Gemm g, const StaticOrder& S, const Epi& E) {
;     ...
;         for (int t = 0; t < nt; t += 2) {
;             const bool last = (t == nt - 2);
;             const char* a1 = cA + (size_t)(t + 1) * kstep;
;             const char* a2 = last ? nA : cA + (size_t)(t + 2) * kstep; const char* b2 = last ? nB : cB + (size_t)(t + 2) * kstep;
;             const char* a3 = a2 + kstep; const char* b3 = b2 + kstep;
;             PG8_LDB(B0, 0, 0); PG8_LDB(B1, 0, 1); PG8_SCHED; PG8_LDA(At, 0, 0); PG8_STAGE(PG8_SA(1, 1), a1 + hstepA, voffA);
;             PG8_WAIT_V(8); PG8_WAIT_L(0); PG8_BAR; PG8_MMA(0, 0, At, B0); PG8_MMA(0, 1, At, B1); PG8_BAR; PG8_SCHED;
;             PG8_LDA(At, 0, 1); PG8_STAGE(PG8_SB(0, 0), b2, voffB); PG8_STAGE(PG8_SB(0, 1), b2 + hstepB, voffB); PG8_STAGE(PG8_SA(0, 0), a2, voffA);
;             PG8_WAIT_V(8); PG8_WAIT_L(0); PG8_BAR; PG8_MMA(1, 0, At, B0); PG8_MMA(1, 1, At, B1); PG8_BAR; PG8_SCHED;
;             PG8_LDB(B0, 1, 0); PG8_LDB(B1, 1, 1); PG8_SCHED; PG8_LDA(At, 1, 0); PG8_STAGE(PG8_SA(0, 1), a2 + hstepA, voffA);
;             PG8_WAIT_V(8); PG8_WAIT_L(0); PG8_BAR; PG8_MMA(0, 0, At, B0); PG8_MMA(0, 1, At, B1); PG8_BAR; PG8_SCHED;
;             PG8_LDA(At, 1, 1); PG8_STAGE(PG8_SB(1, 0), b3, voffB); PG8_STAGE(PG8_SB(1, 1), b3 + hstepB, voffB); PG8_STAGE(PG8_SA(1, 0), a3, voffA);
;             PG8_WAIT_V(8); PG8_WAIT_L(0); PG8_BAR; PG8_MMA(1, 0, At, B0); PG8_MMA(1, 1, At, B1); PG8_BAR; PG8_SCHED;
.LBB0_295:
	s_add_i32 s53, s38, 2
	s_add_u32 s36, s24, 0x100
	s_addc_u32 s37, s25, 0
	s_add_i32 s20, 16, 0x10000
	s_cmp_eq_u32 s26, s38
	s_cselect_b32 s39, s3, s37
	s_cselect_b32 s38, s2, s36
	s_cselect_b32 s55, s17, s52
	s_cselect_b32 s54, s16, s51
	s_add_i32 s21, 16, 0x14000
	v_add_u32_e32 v154, s20, v147
	v_add_u32_e32 v170, s21, v147
	ds_read_b128 v[138:141], v154
	ds_read_b128 v[142:145], v154 offset:1024
	ds_read_b128 v[150:153], v154 offset:2048
	ds_read_b128 v[154:157], v154 offset:3072
	ds_read_b128 v[158:161], v170
	ds_read_b128 v[162:165], v170 offset:1024
	ds_read_b128 v[166:169], v170 offset:2048
	ds_read_b128 v[170:173], v170 offset:3072
	v_lshl_add_u64 v[174:175], s[24:25], 0, v[134:135]
	s_add_i32 m0, s31, 0xc000
	ds_read_b128 v[184:187], v149
	ds_read_b128 v[188:191], v149 offset:1024
	ds_read_b128 v[192:195], v149 offset:2048
	ds_read_b128 v[196:199], v149 offset:3072
	ds_read_b128 v[200:203], v149 offset:4096
	ds_read_b128 v[204:207], v149 offset:5120
	ds_read_b128 v[208:211], v149 offset:6144
	ds_read_b128 v[212:215], v149 offset:7168
	global_load_lds_dwordx4 v[174:175], off
	v_lshl_add_u64 v[174:175], s[24:25], 0, v[136:137]
	s_add_i32 m0, s31, 0xe000
	s_nop 0
	global_load_lds_dwordx4 v[174:175], off
	s_waitcnt vmcnt(8)
	s_waitcnt lgkmcnt(0)
	s_barrier
	s_setprio 1
	s_waitcnt lgkmcnt(0)
	v_mfma_f32_16x16x32_bf16 v[124:127], v[138:141], v[184:187], v[124:127]
	v_mfma_f32_16x16x32_bf16 v[120:123], v[150:153], v[184:187], v[120:123]
	v_mfma_f32_16x16x32_bf16 v[116:119], v[138:141], v[192:195], v[116:119]
	v_mfma_f32_16x16x32_bf16 v[112:115], v[150:153], v[192:195], v[112:115]
	v_mfma_f32_16x16x32_bf16 v[104:107], v[138:141], v[200:203], v[104:107]
	v_mfma_f32_16x16x32_bf16 v[96:99], v[150:153], v[200:203], v[96:99]
	v_mfma_f32_16x16x32_bf16 v[88:91], v[138:141], v[208:211], v[88:91]
	v_mfma_f32_16x16x32_bf16 v[80:83], v[150:153], v[208:211], v[80:83]
	v_mfma_f32_16x16x32_bf16 v[124:127], v[142:145], v[188:191], v[124:127]
	v_mfma_f32_16x16x32_bf16 v[120:123], v[154:157], v[188:191], v[120:123]
	v_mfma_f32_16x16x32_bf16 v[116:119], v[142:145], v[196:199], v[116:119]
	v_mfma_f32_16x16x32_bf16 v[112:115], v[154:157], v[196:199], v[112:115]
	v_mfma_f32_16x16x32_bf16 v[104:107], v[142:145], v[204:207], v[104:107]
	v_mfma_f32_16x16x32_bf16 v[96:99], v[154:157], v[204:207], v[96:99]
	v_mfma_f32_16x16x32_bf16 v[88:91], v[142:145], v[212:215], v[88:91]
	v_mfma_f32_16x16x32_bf16 v[80:83], v[154:157], v[212:215], v[80:83]
	v_mfma_f32_16x16x32_bf16 v[108:111], v[158:161], v[184:187], v[108:111]
	v_mfma_f32_16x16x32_bf16 v[100:103], v[166:169], v[184:187], v[100:103]
	v_mfma_f32_16x16x32_bf16 v[92:95], v[158:161], v[192:195], v[92:95]
	v_mfma_f32_16x16x32_bf16 v[84:87], v[166:169], v[192:195], v[84:87]
	v_mfma_f32_16x16x32_bf16 v[76:79], v[158:161], v[200:203], v[76:79]
	v_mfma_f32_16x16x32_bf16 v[72:75], v[166:169], v[200:203], v[72:75]
	v_mfma_f32_16x16x32_bf16 v[68:71], v[158:161], v[208:211], v[68:71]
	v_mfma_f32_16x16x32_bf16 v[64:67], v[166:169], v[208:211], v[64:67]
	v_mfma_f32_16x16x32_bf16 v[108:111], v[162:165], v[188:191], v[108:111]
	v_mfma_f32_16x16x32_bf16 v[100:103], v[170:173], v[188:191], v[100:103]
	v_mfma_f32_16x16x32_bf16 v[92:95], v[162:165], v[196:199], v[92:95]
	v_mfma_f32_16x16x32_bf16 v[84:87], v[170:173], v[196:199], v[84:87]
	v_mfma_f32_16x16x32_bf16 v[76:79], v[162:165], v[204:207], v[76:79]
	v_mfma_f32_16x16x32_bf16 v[72:75], v[170:173], v[204:207], v[72:75]
	v_mfma_f32_16x16x32_bf16 v[68:71], v[162:165], v[212:215], v[68:71]
	v_mfma_f32_16x16x32_bf16 v[64:67], v[170:173], v[212:215], v[64:67]
	s_setprio 0
	s_barrier
	s_add_i32 s20, s20, s18
	v_lshl_add_u64 v[174:175], s[54:55], 0, v[176:177]
	s_mov_b32 m0, s20
	ds_read_b128 v[184:187], v149 offset:16384
	ds_read_b128 v[188:191], v149 offset:17408
	ds_read_b128 v[192:195], v149 offset:18432
	ds_read_b128 v[196:199], v149 offset:19456
	ds_read_b128 v[200:203], v149 offset:20480
	ds_read_b128 v[204:207], v149 offset:21504
	ds_read_b128 v[208:211], v149 offset:22528
	ds_read_b128 v[212:215], v149 offset:23552
	global_load_lds_dwordx4 v[174:175], off
	s_add_i32 m0, s20, 0x2000
	s_add_u32 s24, s54, s6
	v_lshl_add_u64 v[216:217], s[54:55], 0, v[128:129]
	s_addc_u32 s25, s55, s7
	s_add_i32 s20, s21, s18
	global_load_lds_dwordx4 v[216:217], off
	v_lshl_add_u64 v[218:219], s[24:25], 0, v[176:177]
	s_mov_b32 m0, s20
	v_lshl_add_u64 v[220:221], s[24:25], 0, v[128:129]
	global_load_lds_dwordx4 v[218:219], off
	s_add_i32 m0, s20, 0x2000
	v_lshl_add_u64 v[222:223], s[38:39], 0, v[132:133]
	global_load_lds_dwordx4 v[220:221], off
	s_mov_b32 m0, s31
	v_lshl_add_u64 v[224:225], s[38:39], 0, v[130:131]
	global_load_lds_dwordx4 v[222:223], off
	s_mov_b32 m0, s40
	s_nop 0
	global_load_lds_dwordx4 v[224:225], off
	s_waitcnt vmcnt(8)
	s_waitcnt lgkmcnt(0)
	s_barrier
; #define PG8_STAGE(bufoff, gbase, voff) do { _Pragma("unroll") for (int _i = 0; _i < 2; ++_i) \
;         __builtin_amdgcn_global_load_lds((const unsigned*)((const char*)(gbase) + (voff)[_i]), (LAS unsigned*)(lds + (bufoff) + ldsw + _i * 8192), 16, 0, 0); } while (0)
; #define PG8_LDA(dst, b, h) do { _Pragma("unroll") for (int m = 0; m < 4; ++m) _Pragma("unroll") for (int k = 0; k < 2; ++k) dst[m][k] = *(const LAS bf16x8*)(lds + PG8_SA(b, h) + aoff + m * 2048 + k * 1024); } while (0)
; #define PG8_LDB(dst, b, h) do { _Pragma("unroll") for (int n = 0; n < 2; ++n) _Pragma("unroll") for (int k = 0; k < 2; ++k) dst[n][k] = *(const LAS bf16x8*)(lds + PG8_SB(b, h) + boff + n * 2048 + k * 1024); } while (0)
; #define PG8_WAIT_V(n) asm volatile("s_waitcnt vmcnt(" #n ")" ::: "memory")
; #define PG8_BAR __builtin_amdgcn_s_barrier()
; template <class Epi, bool ALIGN_EPI = PG8_ALIGN>
; __device__ __forceinline__ void gemm_phase(LAS unsigned char* lds, const Gemm g, const StaticOrder& S, const Epi& E) {
;     ...
;         for (int t = 0; t < nt; t += 2) {
;             const bool last = (t == nt - 2);
;             const char* a1 = cA + (size_t)(t + 1) * kstep;
;             const char* a2 = last ? nA : cA + (size_t)(t + 2) * kstep; const char* b2 = last ? nB : cB + (size_t)(t + 2) * kstep;
;             const char* a3 = a2 + kstep; const char* b3 = b2 + kstep;
;             PG8_LDB(B0, 0, 0); PG8_LDB(B1, 0, 1); PG8_SCHED; PG8_LDA(At, 0, 0); PG8_STAGE(PG8_SA(1, 1), a1 + hstepA, voffA);
;             PG8_WAIT_V(8); PG8_WAIT_L(0); PG8_BAR; PG8_MMA(0, 0, At, B0); PG8_MMA(0, 1, At, B1); PG8_BAR; PG8_SCHED;
;             PG8_LDA(At, 0, 1); PG8_STAGE(PG8_SB(0, 0), b2, voffB); PG8_STAGE(PG8_SB(0, 1), b2 + hstepB, voffB); PG8_STAGE(PG8_SA(0, 0), a2, voffA);
;             PG8_WAIT_V(8); PG8_WAIT_L(0); PG8_BAR; PG8_MMA(1, 0, At, B0); PG8_MMA(1, 1, At, B1); PG8_BAR; PG8_SCHED;
;             PG8_LDB(B0, 1, 0); PG8_LDB(B1, 1, 1); PG8_SCHED; PG8_LDA(At, 1, 0); PG8_STAGE(PG8_SA(0, 1), a2 + hstepA, voffA);
;             PG8_WAIT_V(8); PG8_WAIT_L(0); PG8_BAR; PG8_MMA(0, 0, At, B0); PG8_MMA(0, 1, At, B1); PG8_BAR; PG8_SCHED;
;             PG8_LDA(At, 1, 1); PG8_STAGE(PG8_SB(1, 0), b3, voffB); PG8_STAGE(PG8_SB(1, 1), b3 + hstepB, voffB); PG8_STAGE(PG8_SA(1, 0), a3, voffA);
;             PG8_WAIT_V(8); PG8_WAIT_L(0); PG8_BAR; PG8_MMA(1, 0, At, B0); PG8_MMA(1, 1, At, B1); PG8_BAR; PG8_SCHED;
	s_setprio 1
	s_waitcnt lgkmcnt(0)
	v_mfma_f32_16x16x32_bf16 v[60:63], v[138:141], v[184:187], v[60:63]
	v_mfma_f32_16x16x32_bf16 v[56:59], v[150:153], v[184:187], v[56:59]
	v_mfma_f32_16x16x32_bf16 v[52:55], v[138:141], v[192:195], v[52:55]
	v_mfma_f32_16x16x32_bf16 v[48:51], v[150:153], v[192:195], v[48:51]
	v_mfma_f32_16x16x32_bf16 v[40:43], v[138:141], v[200:203], v[40:43]
	v_mfma_f32_16x16x32_bf16 v[32:35], v[150:153], v[200:203], v[32:35]
	v_mfma_f32_16x16x32_bf16 v[24:27], v[138:141], v[208:211], v[24:27]
	v_mfma_f32_16x16x32_bf16 v[16:19], v[150:153], v[208:211], v[16:19]
	v_mfma_f32_16x16x32_bf16 v[60:63], v[142:145], v[188:191], v[60:63]
	v_mfma_f32_16x16x32_bf16 v[56:59], v[154:157], v[188:191], v[56:59]
	v_mfma_f32_16x16x32_bf16 v[52:55], v[142:145], v[196:199], v[52:55]
	v_mfma_f32_16x16x32_bf16 v[48:51], v[154:157], v[196:199], v[48:51]
	v_mfma_f32_16x16x32_bf16 v[40:43], v[142:145], v[204:207], v[40:43]
	v_mfma_f32_16x16x32_bf16 v[32:35], v[154:157], v[204:207], v[32:35]
	v_mfma_f32_16x16x32_bf16 v[24:27], v[142:145], v[212:215], v[24:27]
	v_mfma_f32_16x16x32_bf16 v[16:19], v[154:157], v[212:215], v[16:19]
	v_mfma_f32_16x16x32_bf16 v[44:47], v[158:161], v[184:187], v[44:47]
	v_mfma_f32_16x16x32_bf16 v[36:39], v[166:169], v[184:187], v[36:39]
	v_mfma_f32_16x16x32_bf16 v[28:31], v[158:161], v[192:195], v[28:31]
	v_mfma_f32_16x16x32_bf16 v[20:23], v[166:169], v[192:195], v[20:23]
	v_mfma_f32_16x16x32_bf16 v[12:15], v[158:161], v[200:203], v[12:15]
	v_mfma_f32_16x16x32_bf16 v[8:11], v[166:169], v[200:203], v[8:11]
	v_mfma_f32_16x16x32_bf16 v[4:7], v[158:161], v[208:211], v[4:7]
	v_mfma_f32_16x16x32_bf16 v[0:3], v[166:169], v[208:211], v[0:3]
	v_mfma_f32_16x16x32_bf16 v[44:47], v[162:165], v[188:191], v[44:47]
	v_mfma_f32_16x16x32_bf16 v[36:39], v[170:173], v[188:191], v[36:39]
	v_mfma_f32_16x16x32_bf16 v[28:31], v[162:165], v[196:199], v[28:31]
	v_mfma_f32_16x16x32_bf16 v[20:23], v[170:173], v[196:199], v[20:23]
	v_mfma_f32_16x16x32_bf16 v[12:15], v[162:165], v[204:207], v[12:15]
	v_mfma_f32_16x16x32_bf16 v[8:11], v[170:173], v[204:207], v[8:11]
	v_mfma_f32_16x16x32_bf16 v[4:7], v[162:165], v[212:215], v[4:7]
	v_mfma_f32_16x16x32_bf16 v[0:3], v[170:173], v[212:215], v[0:3]
	s_setprio 0
	s_barrier
	s_add_i32 s20, 16, 0x18000
	s_add_i32 s21, 16, 0x1c000
	v_add_u32_e32 v154, s20, v147
	v_add_u32_e32 v170, s21, v147
	ds_read_b128 v[138:141], v154
	ds_read_b128 v[142:145], v154 offset:1024
	ds_read_b128 v[150:153], v154 offset:2048
	ds_read_b128 v[154:157], v154 offset:3072
	ds_read_b128 v[158:161], v170
	ds_read_b128 v[162:165], v170 offset:1024
	ds_read_b128 v[166:169], v170 offset:2048
	ds_read_b128 v[170:173], v170 offset:3072
	s_add_u32 s24, s38, 0x160000
	s_addc_u32 s25, s39, 0
	s_mov_b32 m0, s41
	v_lshl_add_u64 v[226:227], s[24:25], 0, v[132:133]
	ds_read_b128 v[184:187], v149 offset:32768
	ds_read_b128 v[188:191], v149 offset:33792
	ds_read_b128 v[192:195], v149 offset:34816
	ds_read_b128 v[196:199], v149 offset:35840
	ds_read_b128 v[200:203], v149 offset:36864
	ds_read_b128 v[204:207], v149 offset:37888
	ds_read_b128 v[208:211], v149 offset:38912
	ds_read_b128 v[212:215], v149 offset:39936
	global_load_lds_dwordx4 v[226:227], off
	v_lshl_add_u64 v[226:227], s[24:25], 0, v[130:131]
	s_mov_b32 m0, s44
	s_nop 0
	global_load_lds_dwordx4 v[226:227], off
	s_waitcnt vmcnt(8)
	s_waitcnt lgkmcnt(0)
	s_barrier
	s_setprio 1
	s_waitcnt lgkmcnt(0)
	v_mfma_f32_16x16x32_bf16 v[124:127], v[138:141], v[184:187], v[124:127]
	v_mfma_f32_16x16x32_bf16 v[120:123], v[150:153], v[184:187], v[120:123]
	v_mfma_f32_16x16x32_bf16 v[116:119], v[138:141], v[192:195], v[116:119]
	v_mfma_f32_16x16x32_bf16 v[112:115], v[150:153], v[192:195], v[112:115]
	v_mfma_f32_16x16x32_bf16 v[104:107], v[138:141], v[200:203], v[104:107]
	v_mfma_f32_16x16x32_bf16 v[96:99], v[150:153], v[200:203], v[96:99]
	v_mfma_f32_16x16x32_bf16 v[88:91], v[138:141], v[208:211], v[88:91]
	v_mfma_f32_16x16x32_bf16 v[80:83], v[150:153], v[208:211], v[80:83]
	v_mfma_f32_16x16x32_bf16 v[124:127], v[142:145], v[188:191], v[124:127]
	v_mfma_f32_16x16x32_bf16 v[120:123], v[154:157], v[188:191], v[120:123]
	v_mfma_f32_16x16x32_bf16 v[116:119], v[142:145], v[196:199], v[116:119]
	v_mfma_f32_16x16x32_bf16 v[112:115], v[154:157], v[196:199], v[112:115]
	v_mfma_f32_16x16x32_bf16 v[104:107], v[142:145], v[204:207], v[104:107]
	v_mfma_f32_16x16x32_bf16 v[96:99], v[154:157], v[204:207], v[96:99]
	v_mfma_f32_16x16x32_bf16 v[88:91], v[142:145], v[212:215], v[88:91]
	v_mfma_f32_16x16x32_bf16 v[80:83], v[154:157], v[212:215], v[80:83]
	v_mfma_f32_16x16x32_bf16 v[108:111], v[158:161], v[184:187], v[108:111]
	v_mfma_f32_16x16x32_bf16 v[100:103], v[166:169], v[184:187], v[100:103]
	v_mfma_f32_16x16x32_bf16 v[92:95], v[158:161], v[192:195], v[92:95]
	v_mfma_f32_16x16x32_bf16 v[84:87], v[166:169], v[192:195], v[84:87]
	v_mfma_f32_16x16x32_bf16 v[76:79], v[158:161], v[200:203], v[76:79]
	v_mfma_f32_16x16x32_bf16 v[72:75], v[166:169], v[200:203], v[72:75]
	v_mfma_f32_16x16x32_bf16 v[68:71], v[158:161], v[208:211], v[68:71]
	v_mfma_f32_16x16x32_bf16 v[64:67], v[166:169], v[208:211], v[64:67]
	v_mfma_f32_16x16x32_bf16 v[108:111], v[162:165], v[188:191], v[108:111]
	v_mfma_f32_16x16x32_bf16 v[100:103], v[170:173], v[188:191], v[100:103]
	v_mfma_f32_16x16x32_bf16 v[92:95], v[162:165], v[196:199], v[92:95]
	v_mfma_f32_16x16x32_bf16 v[84:87], v[170:173], v[196:199], v[84:87]
	v_mfma_f32_16x16x32_bf16 v[76:79], v[162:165], v[204:207], v[76:79]
	v_mfma_f32_16x16x32_bf16 v[72:75], v[170:173], v[204:207], v[72:75]
	v_mfma_f32_16x16x32_bf16 v[68:71], v[162:165], v[212:215], v[68:71]
	v_mfma_f32_16x16x32_bf16 v[64:67], v[170:173], v[212:215], v[64:67]
	s_setprio 0
	s_barrier
; #define PG8_STAGE(bufoff, gbase, voff) do { _Pragma("unroll") for (int _i = 0; _i < 2; ++_i) \
;         __builtin_amdgcn_global_load_lds((const unsigned*)((const char*)(gbase) + (voff)[_i]), (LAS unsigned*)(lds + (bufoff) + ldsw + _i * 8192), 16, 0, 0); } while (0)
; #define PG8_LDA(dst, b, h) do { _Pragma("unroll") for (int m = 0; m < 4; ++m) _Pragma("unroll") for (int k = 0; k < 2; ++k) dst[m][k] = *(const LAS bf16x8*)(lds + PG8_SA(b, h) + aoff + m * 2048 + k * 1024); } while (0)
; #define PG8_LDB(dst, b, h) do { _Pragma("unroll") for (int n = 0; n < 2; ++n) _Pragma("unroll") for (int k = 0; k < 2; ++k) dst[n][k] = *(const LAS bf16x8*)(lds + PG8_SB(b, h) + boff + n * 2048 + k * 1024); } while (0)
; #define PG8_WAIT_V(n) asm volatile("s_waitcnt vmcnt(" #n ")" ::: "memory")
; #define PG8_BAR __builtin_amdgcn_s_barrier()
; template <class Epi, bool ALIGN_EPI = PG8_ALIGN>
; __device__ __forceinline__ void gemm_phase(LAS unsigned char* lds, const Gemm g, const StaticOrder& S, const Epi& E) {
;     ...
;         for (int t = 0; t < nt; t += 2) {
;             const bool last = (t == nt - 2);
;             const char* a1 = cA + (size_t)(t + 1) * kstep;
;             const char* a2 = last ? nA : cA + (size_t)(t + 2) * kstep; const char* b2 = last ? nB : cB + (size_t)(t + 2) * kstep;
;             const char* a3 = a2 + kstep; const char* b3 = b2 + kstep;
;             PG8_LDB(B0, 0, 0); PG8_LDB(B1, 0, 1); PG8_SCHED; PG8_LDA(At, 0, 0); PG8_STAGE(PG8_SA(1, 1), a1 + hstepA, voffA);
;             PG8_WAIT_V(8); PG8_WAIT_L(0); PG8_BAR; PG8_MMA(0, 0, At, B0); PG8_MMA(0, 1, At, B1); PG8_BAR; PG8_SCHED;
;             PG8_LDA(At, 0, 1); PG8_STAGE(PG8_SB(0, 0), b2, voffB); PG8_STAGE(PG8_SB(0, 1), b2 + hstepB, voffB); PG8_STAGE(PG8_SA(0, 0), a2, voffA);
;             PG8_WAIT_V(8); PG8_WAIT_L(0); PG8_BAR; PG8_MMA(1, 0, At, B0); PG8_MMA(1, 1, At, B1); PG8_BAR; PG8_SCHED;
;             PG8_LDB(B0, 1, 0); PG8_LDB(B1, 1, 1); PG8_SCHED; PG8_LDA(At, 1, 0); PG8_STAGE(PG8_SA(0, 1), a2 + hstepA, voffA);
;             PG8_WAIT_V(8); PG8_WAIT_L(0); PG8_BAR; PG8_MMA(0, 0, At, B0); PG8_MMA(0, 1, At, B1); PG8_BAR; PG8_SCHED;
;             PG8_LDA(At, 1, 1); PG8_STAGE(PG8_SB(1, 0), b3, voffB); PG8_STAGE(PG8_SB(1, 1), b3 + hstepB, voffB); PG8_STAGE(PG8_SA(1, 0), a3, voffA);
;             PG8_WAIT_V(8); PG8_WAIT_L(0); PG8_BAR; PG8_MMA(1, 0, At, B0); PG8_MMA(1, 1, At, B1); PG8_BAR; PG8_SCHED;
	s_add_i32 s20, s20, s18
	v_lshl_add_u64 v[174:175], v[174:175], 0, s[0:1]
	s_mov_b32 m0, s20
	ds_read_b128 v[184:187], v149 offset:49152
	ds_read_b128 v[188:191], v149 offset:50176
	ds_read_b128 v[192:195], v149 offset:51200
	ds_read_b128 v[196:199], v149 offset:52224
	ds_read_b128 v[200:203], v149 offset:53248
	ds_read_b128 v[204:207], v149 offset:54272
	ds_read_b128 v[208:211], v149 offset:55296
	ds_read_b128 v[212:215], v149 offset:56320
	global_load_lds_dwordx4 v[174:175], off
	v_lshl_add_u64 v[174:175], v[216:217], 0, s[0:1]
	s_add_i32 m0, s20, 0x2000
	s_add_i32 s20, s21, s18
	global_load_lds_dwordx4 v[174:175], off
	v_lshl_add_u64 v[174:175], v[218:219], 0, s[0:1]
	s_mov_b32 m0, s20
	s_nop 0
	global_load_lds_dwordx4 v[174:175], off
	v_lshl_add_u64 v[174:175], v[220:221], 0, s[0:1]
	s_add_i32 m0, s20, 0x2000
	s_nop 0
	global_load_lds_dwordx4 v[174:175], off
	v_lshl_add_u64 v[174:175], v[222:223], 0, s[0:1]
	s_mov_b32 m0, s45
	s_nop 0
	global_load_lds_dwordx4 v[174:175], off
	v_lshl_add_u64 v[174:175], v[224:225], 0, s[0:1]
	s_mov_b32 m0, s46
	s_nop 0
	global_load_lds_dwordx4 v[174:175], off
	s_waitcnt vmcnt(8)
	s_waitcnt lgkmcnt(0)
	s_barrier
	s_setprio 1
	s_waitcnt lgkmcnt(0)
	v_mfma_f32_16x16x32_bf16 v[60:63], v[138:141], v[184:187], v[60:63]
	v_mfma_f32_16x16x32_bf16 v[56:59], v[150:153], v[184:187], v[56:59]
	v_mfma_f32_16x16x32_bf16 v[52:55], v[138:141], v[192:195], v[52:55]
	v_mfma_f32_16x16x32_bf16 v[48:51], v[150:153], v[192:195], v[48:51]
	v_mfma_f32_16x16x32_bf16 v[40:43], v[138:141], v[200:203], v[40:43]
	v_mfma_f32_16x16x32_bf16 v[32:35], v[150:153], v[200:203], v[32:35]
	v_mfma_f32_16x16x32_bf16 v[24:27], v[138:141], v[208:211], v[24:27]
	v_mfma_f32_16x16x32_bf16 v[16:19], v[150:153], v[208:211], v[16:19]
	v_mfma_f32_16x16x32_bf16 v[60:63], v[142:145], v[188:191], v[60:63]
	v_mfma_f32_16x16x32_bf16 v[56:59], v[154:157], v[188:191], v[56:59]
	v_mfma_f32_16x16x32_bf16 v[52:55], v[142:145], v[196:199], v[52:55]
	v_mfma_f32_16x16x32_bf16 v[48:51], v[154:157], v[196:199], v[48:51]
	v_mfma_f32_16x16x32_bf16 v[40:43], v[142:145], v[204:207], v[40:43]
	v_mfma_f32_16x16x32_bf16 v[32:35], v[154:157], v[204:207], v[32:35]
	v_mfma_f32_16x16x32_bf16 v[24:27], v[142:145], v[212:215], v[24:27]
	v_mfma_f32_16x16x32_bf16 v[16:19], v[154:157], v[212:215], v[16:19]
	v_mfma_f32_16x16x32_bf16 v[44:47], v[158:161], v[184:187], v[44:47]
	v_mfma_f32_16x16x32_bf16 v[36:39], v[166:169], v[184:187], v[36:39]
	v_mfma_f32_16x16x32_bf16 v[28:31], v[158:161], v[192:195], v[28:31]
	v_mfma_f32_16x16x32_bf16 v[20:23], v[166:169], v[192:195], v[20:23]
	v_mfma_f32_16x16x32_bf16 v[12:15], v[158:161], v[200:203], v[12:15]
	v_mfma_f32_16x16x32_bf16 v[8:11], v[166:169], v[200:203], v[8:11]
	v_mfma_f32_16x16x32_bf16 v[4:7], v[158:161], v[208:211], v[4:7]
	v_mfma_f32_16x16x32_bf16 v[0:3], v[166:169], v[208:211], v[0:3]
	v_mfma_f32_16x16x32_bf16 v[44:47], v[162:165], v[188:191], v[44:47]
	v_mfma_f32_16x16x32_bf16 v[36:39], v[170:173], v[188:191], v[36:39]
	v_mfma_f32_16x16x32_bf16 v[28:31], v[162:165], v[196:199], v[28:31]
	v_mfma_f32_16x16x32_bf16 v[20:23], v[170:173], v[196:199], v[20:23]
	v_mfma_f32_16x16x32_bf16 v[12:15], v[162:165], v[204:207], v[12:15]
	v_mfma_f32_16x16x32_bf16 v[8:11], v[170:173], v[204:207], v[8:11]
	v_mfma_f32_16x16x32_bf16 v[4:7], v[162:165], v[212:215], v[4:7]
	v_mfma_f32_16x16x32_bf16 v[0:3], v[170:173], v[212:215], v[0:3]
	s_setprio 0
	s_barrier
	s_add_u32 s51, s51, 0x100
	s_addc_u32 s52, s52, 0
	s_cmp_ge_i32 s53, s47
	s_mov_b64 s[24:25], s[36:37]
	s_mov_b32 s38, s53
	s_cbranch_scc0 .LBB0_295
; __device__ __forceinline__ unsigned cvt_pk(float lo, float hi) { f32x2_t v = {lo, hi}; bf16x2_t b = __builtin_convertvector(v, bf16x2_t); return __builtin_bit_cast(unsigned, b); }
;     __device__ __forceinline__ void operator()(const f32x4 (&acc)[2][2][4][2], const Unit& u, int wr, int wc, int fr, int fq) const {
;         const int row0 = u.pm * BM + wr * 64 + fr, col0 = u.pn * BM + wc * 32 + 8 * fq;
;         float scv[2][4];
; #pragma unroll
;         for (int ai = 0; ai < 2; ++ai)
; #pragma unroll
;             for (int m = 0; m < 4; ++m) scv[ai][m] = rs ? rs[(size_t)(row0 + ai * HALF + m * 16) * rs_stride] * cs : cs;
; #pragma unroll
;         for (int ai = 0; ai < 2; ++ai)
; #pragma unroll
;             for (int m = 0; m < 4; ++m) {
;                 const int row = row0 + ai * HALF + m * 16; const float sc = scv[ai][m];
;                 bf16_t* rowp = O + (size_t)row * ldc + col0;
; #pragma unroll
;                 for (int bj = 0; bj < 2; ++bj) { const f32x4 v0 = acc[ai][bj][m][0] * sc, v1 = acc[ai][bj][m][1] * sc;
;                     u32x4 w; w.x = cvt_pk(v0[0], v0[1]); w.y = cvt_pk(v0[2], v0[3]); w.z = cvt_pk(v1[0], v1[1]); w.w = cvt_pk(v1[2], v1[3]);
;                     *(u32x4*)(rowp + bj * HALF) = w; }
;             }
;     }
	v_pk_mul_f32 v[126:127], v[126:127], 0.5 op_sel_hi:[1,0]
	v_pk_mul_f32 v[124:125], v[124:125], 0.5 op_sel_hi:[1,0]
	v_pk_mul_f32 v[122:123], v[122:123], 0.5 op_sel_hi:[1,0]
	v_pk_mul_f32 v[120:121], v[120:121], 0.5 op_sel_hi:[1,0]
	v_pk_mul_f32 v[138:139], v[110:111], 0.5 op_sel_hi:[1,0]
	v_pk_mul_f32 v[140:141], v[108:109], 0.5 op_sel_hi:[1,0]
	v_pk_mul_f32 v[142:143], v[102:103], 0.5 op_sel_hi:[1,0]
	v_pk_mul_f32 v[144:145], v[100:101], 0.5 op_sel_hi:[1,0]
	v_pk_mul_f32 v[100:101], v[118:119], 0.5 op_sel_hi:[1,0]
	v_pk_mul_f32 v[102:103], v[116:117], 0.5 op_sel_hi:[1,0]
	v_pk_mul_f32 v[108:109], v[114:115], 0.5 op_sel_hi:[1,0]
	v_pk_mul_f32 v[110:111], v[112:113], 0.5 op_sel_hi:[1,0]
	v_pk_mul_f32 v[112:113], v[94:95], 0.5 op_sel_hi:[1,0]
	v_pk_mul_f32 v[114:115], v[92:93], 0.5 op_sel_hi:[1,0]
	v_pk_mul_f32 v[116:117], v[86:87], 0.5 op_sel_hi:[1,0]
	v_pk_mul_f32 v[118:119], v[84:85], 0.5 op_sel_hi:[1,0]
	v_pk_mul_f32 v[84:85], v[106:107], 0.5 op_sel_hi:[1,0]
	v_pk_mul_f32 v[86:87], v[104:105], 0.5 op_sel_hi:[1,0]
	v_pk_mul_f32 v[92:93], v[98:99], 0.5 op_sel_hi:[1,0]
	v_pk_mul_f32 v[94:95], v[96:97], 0.5 op_sel_hi:[1,0]
	v_pk_mul_f32 v[96:97], v[78:79], 0.5 op_sel_hi:[1,0]
	v_pk_mul_f32 v[98:99], v[76:77], 0.5 op_sel_hi:[1,0]
	v_pk_mul_f32 v[104:105], v[74:75], 0.5 op_sel_hi:[1,0]
	v_pk_mul_f32 v[106:107], v[72:73], 0.5 op_sel_hi:[1,0]
	v_pk_mul_f32 v[72:73], v[90:91], 0.5 op_sel_hi:[1,0]
	v_pk_mul_f32 v[74:75], v[88:89], 0.5 op_sel_hi:[1,0]
	v_pk_mul_f32 v[76:77], v[82:83], 0.5 op_sel_hi:[1,0]
	v_pk_mul_f32 v[78:79], v[80:81], 0.5 op_sel_hi:[1,0]
	v_pk_mul_f32 v[70:71], v[70:71], 0.5 op_sel_hi:[1,0]
	v_pk_mul_f32 v[68:69], v[68:69], 0.5 op_sel_hi:[1,0]
	v_pk_mul_f32 v[66:67], v[66:67], 0.5 op_sel_hi:[1,0]
	v_pk_mul_f32 v[64:65], v[64:65], 0.5 op_sel_hi:[1,0]
	v_pk_mul_f32 v[62:63], v[62:63], 0.5 op_sel_hi:[1,0]
	v_pk_mul_f32 v[60:61], v[60:61], 0.5 op_sel_hi:[1,0]
	v_pk_mul_f32 v[58:59], v[58:59], 0.5 op_sel_hi:[1,0]
	v_pk_mul_f32 v[56:57], v[56:57], 0.5 op_sel_hi:[1,0]
	v_pk_mul_f32 v[80:81], v[46:47], 0.5 op_sel_hi:[1,0]
	v_pk_mul_f32 v[82:83], v[44:45], 0.5 op_sel_hi:[1,0]
	v_pk_mul_f32 v[88:89], v[38:39], 0.5 op_sel_hi:[1,0]
	v_pk_mul_f32 v[90:91], v[36:37], 0.5 op_sel_hi:[1,0]
	v_pk_mul_f32 v[36:37], v[54:55], 0.5 op_sel_hi:[1,0]
	v_pk_mul_f32 v[38:39], v[52:53], 0.5 op_sel_hi:[1,0]
	v_pk_mul_f32 v[44:45], v[50:51], 0.5 op_sel_hi:[1,0]
	v_pk_mul_f32 v[46:47], v[48:49], 0.5 op_sel_hi:[1,0]
	v_pk_mul_f32 v[48:49], v[30:31], 0.5 op_sel_hi:[1,0]
	v_pk_mul_f32 v[50:51], v[28:29], 0.5 op_sel_hi:[1,0]
	v_pk_mul_f32 v[52:53], v[22:23], 0.5 op_sel_hi:[1,0]
	v_pk_mul_f32 v[54:55], v[20:21], 0.5 op_sel_hi:[1,0]
	v_pk_mul_f32 v[20:21], v[42:43], 0.5 op_sel_hi:[1,0]
	v_pk_mul_f32 v[22:23], v[40:41], 0.5 op_sel_hi:[1,0]
	v_pk_mul_f32 v[28:29], v[34:35], 0.5 op_sel_hi:[1,0]
	v_pk_mul_f32 v[30:31], v[32:33], 0.5 op_sel_hi:[1,0]
	v_pk_mul_f32 v[32:33], v[14:15], 0.5 op_sel_hi:[1,0]
	v_pk_mul_f32 v[34:35], v[12:13], 0.5 op_sel_hi:[1,0]
	v_pk_mul_f32 v[40:41], v[10:11], 0.5 op_sel_hi:[1,0]
	v_pk_mul_f32 v[42:43], v[8:9], 0.5 op_sel_hi:[1,0]
	v_pk_mul_f32 v[8:9], v[26:27], 0.5 op_sel_hi:[1,0]
	v_pk_mul_f32 v[10:11], v[24:25], 0.5 op_sel_hi:[1,0]
	v_pk_mul_f32 v[12:13], v[18:19], 0.5 op_sel_hi:[1,0]
	v_pk_mul_f32 v[14:15], v[16:17], 0.5 op_sel_hi:[1,0]
	v_pk_mul_f32 v[6:7], v[6:7], 0.5 op_sel_hi:[1,0]
	v_pk_mul_f32 v[4:5], v[4:5], 0.5 op_sel_hi:[1,0]
	v_pk_mul_f32 v[2:3], v[2:3], 0.5 op_sel_hi:[1,0]
	v_pk_mul_f32 v[0:1], v[0:1], 0.5 op_sel_hi:[1,0]

; #define PG8_STAGE(bufoff, gbase, voff) do { _Pragma("unroll") for (int _i = 0; _i < 2; ++_i) \
;         __builtin_amdgcn_global_load_lds((const unsigned*)((const char*)(gbase) + (voff)[_i]), (LAS unsigned*)(lds + (bufoff) + ldsw + _i * 8192), 16, 0, 0); } while (0)
; #define PG8_LDA(dst, b, h) do { _Pragma("unroll") for (int m = 0; m < 4; ++m) _Pragma("unroll") for (int k = 0; k < 2; ++k) dst[m][k] = *(const LAS bf16x8*)(lds + PG8_SA(b, h) + aoff + m * 2048 + k * 1024); } while (0)
; #define PG8_LDB(dst, b, h) do { _Pragma("unroll") for (int n = 0; n < 2; ++n) _Pragma("unroll") for (int k = 0; k < 2; ++k) dst[n][k] = *(const LAS bf16x8*)(lds + PG8_SB(b, h) + boff + n * 2048 + k * 1024); } while (0)
; #define PG8_WAIT_V(n) asm volatile("s_waitcnt vmcnt(" #n ")" ::: "memory")
; #define PG8_BAR __builtin_amdgcn_s_barrier()
; template <class Epi, bool ALIGN_EPI = PG8_ALIGN>
; __device__ __forceinline__ void gemm_phase(LAS unsigned char* lds, const Gemm g, const StaticOrder& S, const Epi& E) {
;     ...
;         for (int t = 0; t < nt; t += 2) {
;             const bool last = (t == nt - 2);
;             const char* a1 = cA + (size_t)(t + 1) * kstep;
;             const char* a2 = last ? nA : cA + (size_t)(t + 2) * kstep; const char* b2 = last ? nB : cB + (size_t)(t + 2) * kstep;
;             const char* a3 = a2 + kstep; const char* b3 = b2 + kstep;
;             PG8_LDB(B0, 0, 0); PG8_LDB(B1, 0, 1); PG8_SCHED; PG8_LDA(At, 0, 0); PG8_STAGE(PG8_SA(1, 1), a1 + hstepA, voffA);
;             PG8_WAIT_V(8); PG8_WAIT_L(0); PG8_BAR; PG8_MMA(0, 0, At, B0); PG8_MMA(0, 1, At, B1); PG8_BAR; PG8_SCHED;
;             PG8_LDA(At, 0, 1); PG8_STAGE(PG8_SB(0, 0), b2, voffB); PG8_STAGE(PG8_SB(0, 1), b2 + hstepB, voffB); PG8_STAGE(PG8_SA(0, 0), a2, voffA);
;             PG8_WAIT_V(8); PG8_WAIT_L(0); PG8_BAR; PG8_MMA(1, 0, At, B0); PG8_MMA(1, 1, At, B1); PG8_BAR; PG8_SCHED;
;             PG8_LDB(B0, 1, 0); PG8_LDB(B1, 1, 1); PG8_SCHED; PG8_LDA(At, 1, 0); PG8_STAGE(PG8_SA(0, 1), a2 + hstepA, voffA);
;             PG8_WAIT_V(8); PG8_WAIT_L(0); PG8_BAR; PG8_MMA(0, 0, At, B0); PG8_MMA(0, 1, At, B1); PG8_BAR; PG8_SCHED;
;             PG8_LDA(At, 1, 1); PG8_STAGE(PG8_SB(1, 0), b3, voffB); PG8_STAGE(PG8_SB(1, 1), b3 + hstepB, voffB); PG8_STAGE(PG8_SA(1, 0), a3, voffA);
;             PG8_WAIT_V(8); PG8_WAIT_L(0); PG8_BAR; PG8_MMA(1, 0, At, B0); PG8_MMA(1, 1, At, B1); PG8_BAR; PG8_SCHED;
.LBB0_458:
	s_add_i32 s51, s38, 2
	s_add_u32 s20, s4, 0xfff80080
	s_addc_u32 s21, s5, -1
	s_add_i32 s22, 16, 0x10000
	s_cmp_eq_u32 s45, s38
	s_cselect_b32 s39, s17, s21
	s_cselect_b32 s38, s50, s20
	s_cselect_b32 s53, s25, s41
	s_cselect_b32 s52, s24, s40
	s_add_i32 s20, 16, 0x14000
	v_add_u32_e32 v154, s22, v139
	v_add_u32_e32 v170, s20, v139
	ds_read_b128 v[142:145], v154
	ds_read_b128 v[146:149], v154 offset:1024
	ds_read_b128 v[150:153], v154 offset:2048
	ds_read_b128 v[154:157], v154 offset:3072
	ds_read_b128 v[158:161], v170
	ds_read_b128 v[162:165], v170 offset:1024
	ds_read_b128 v[166:169], v170 offset:2048
	ds_read_b128 v[170:173], v170 offset:3072
	v_lshl_add_u64 v[174:175], s[4:5], 0, v[134:135]
	s_add_i32 m0, s29, 0xc000
	ds_read_b128 v[184:187], v141
	ds_read_b128 v[188:191], v141 offset:1024
	ds_read_b128 v[192:195], v141 offset:2048
	ds_read_b128 v[196:199], v141 offset:3072
	ds_read_b128 v[200:203], v141 offset:4096
	ds_read_b128 v[204:207], v141 offset:5120
	ds_read_b128 v[208:211], v141 offset:6144
	ds_read_b128 v[212:215], v141 offset:7168
	global_load_lds_dwordx4 v[174:175], off
	v_lshl_add_u64 v[174:175], s[4:5], 0, v[136:137]
	s_add_i32 m0, s29, 0xe000
	s_nop 0
	global_load_lds_dwordx4 v[174:175], off
	s_waitcnt vmcnt(8)
	s_waitcnt lgkmcnt(0)
	s_barrier
	s_setprio 1
	s_waitcnt lgkmcnt(0)
	v_mfma_f32_16x16x32_bf16 v[120:123], v[142:145], v[184:187], v[120:123]
	v_mfma_f32_16x16x32_bf16 v[124:127], v[150:153], v[184:187], v[124:127]
	v_mfma_f32_16x16x32_bf16 v[108:111], v[142:145], v[192:195], v[108:111]
	v_mfma_f32_16x16x32_bf16 v[104:107], v[150:153], v[192:195], v[104:107]
	v_mfma_f32_16x16x32_bf16 v[92:95], v[142:145], v[200:203], v[92:95]
	v_mfma_f32_16x16x32_bf16 v[88:91], v[150:153], v[200:203], v[88:91]
	v_mfma_f32_16x16x32_bf16 v[76:79], v[142:145], v[208:211], v[76:79]
	v_mfma_f32_16x16x32_bf16 v[72:75], v[150:153], v[208:211], v[72:75]
	v_mfma_f32_16x16x32_bf16 v[120:123], v[146:149], v[188:191], v[120:123]
	v_mfma_f32_16x16x32_bf16 v[124:127], v[154:157], v[188:191], v[124:127]
	v_mfma_f32_16x16x32_bf16 v[108:111], v[146:149], v[196:199], v[108:111]
	v_mfma_f32_16x16x32_bf16 v[104:107], v[154:157], v[196:199], v[104:107]
	v_mfma_f32_16x16x32_bf16 v[92:95], v[146:149], v[204:207], v[92:95]
	v_mfma_f32_16x16x32_bf16 v[88:91], v[154:157], v[204:207], v[88:91]
	v_mfma_f32_16x16x32_bf16 v[76:79], v[146:149], v[212:215], v[76:79]
	v_mfma_f32_16x16x32_bf16 v[72:75], v[154:157], v[212:215], v[72:75]
	v_mfma_f32_16x16x32_bf16 v[116:119], v[158:161], v[184:187], v[116:119]
	v_mfma_f32_16x16x32_bf16 v[112:115], v[166:169], v[184:187], v[112:115]
	v_mfma_f32_16x16x32_bf16 v[100:103], v[158:161], v[192:195], v[100:103]
	v_mfma_f32_16x16x32_bf16 v[96:99], v[166:169], v[192:195], v[96:99]
	v_mfma_f32_16x16x32_bf16 v[84:87], v[158:161], v[200:203], v[84:87]
	v_mfma_f32_16x16x32_bf16 v[80:83], v[166:169], v[200:203], v[80:83]
	v_mfma_f32_16x16x32_bf16 v[68:71], v[158:161], v[208:211], v[68:71]
	v_mfma_f32_16x16x32_bf16 v[64:67], v[166:169], v[208:211], v[64:67]
	v_mfma_f32_16x16x32_bf16 v[116:119], v[162:165], v[188:191], v[116:119]
	v_mfma_f32_16x16x32_bf16 v[112:115], v[170:173], v[188:191], v[112:115]
	v_mfma_f32_16x16x32_bf16 v[100:103], v[162:165], v[196:199], v[100:103]
	v_mfma_f32_16x16x32_bf16 v[96:99], v[170:173], v[196:199], v[96:99]
	v_mfma_f32_16x16x32_bf16 v[84:87], v[162:165], v[204:207], v[84:87]
	v_mfma_f32_16x16x32_bf16 v[80:83], v[170:173], v[204:207], v[80:83]
	v_mfma_f32_16x16x32_bf16 v[68:71], v[162:165], v[212:215], v[68:71]
	v_mfma_f32_16x16x32_bf16 v[64:67], v[170:173], v[212:215], v[64:67]
	s_setprio 0
	s_barrier
	s_add_i32 s21, s22, s18
	v_lshl_add_u64 v[174:175], s[52:53], 0, v[176:177]
	s_mov_b32 m0, s21
	ds_read_b128 v[184:187], v141 offset:16384
	ds_read_b128 v[188:191], v141 offset:17408
	ds_read_b128 v[192:195], v141 offset:18432
	ds_read_b128 v[196:199], v141 offset:19456
	ds_read_b128 v[200:203], v141 offset:20480
	ds_read_b128 v[204:207], v141 offset:21504
	ds_read_b128 v[208:211], v141 offset:22528
	ds_read_b128 v[212:215], v141 offset:23552
	global_load_lds_dwordx4 v[174:175], off
	s_add_i32 m0, s21, 0x2000
	v_lshl_add_u64 v[216:217], s[52:53], 0, v[128:129]
	s_add_u32 s52, s52, s6
	s_addc_u32 s53, s53, s7
	s_add_i32 s20, s20, s18
	global_load_lds_dwordx4 v[216:217], off
	v_lshl_add_u64 v[218:219], s[52:53], 0, v[176:177]
	s_mov_b32 m0, s20
	v_lshl_add_u64 v[220:221], s[52:53], 0, v[128:129]
	global_load_lds_dwordx4 v[218:219], off
	s_add_i32 m0, s20, 0x2000
	v_lshl_add_u64 v[222:223], s[38:39], 0, v[132:133]
	global_load_lds_dwordx4 v[220:221], off
	s_mov_b32 m0, s29
	v_lshl_add_u64 v[224:225], s[38:39], 0, v[130:131]
	global_load_lds_dwordx4 v[222:223], off
	s_mov_b32 m0, s30
	s_nop 0
	global_load_lds_dwordx4 v[224:225], off
	s_waitcnt vmcnt(8)
	s_waitcnt lgkmcnt(0)
	s_barrier
; #define PG8_STAGE(bufoff, gbase, voff) do { _Pragma("unroll") for (int _i = 0; _i < 2; ++_i) \
;         __builtin_amdgcn_global_load_lds((const unsigned*)((const char*)(gbase) + (voff)[_i]), (LAS unsigned*)(lds + (bufoff) + ldsw + _i * 8192), 16, 0, 0); } while (0)
; #define PG8_LDA(dst, b, h) do { _Pragma("unroll") for (int m = 0; m < 4; ++m) _Pragma("unroll") for (int k = 0; k < 2; ++k) dst[m][k] = *(const LAS bf16x8*)(lds + PG8_SA(b, h) + aoff + m * 2048 + k * 1024); } while (0)
; #define PG8_LDB(dst, b, h) do { _Pragma("unroll") for (int n = 0; n < 2; ++n) _Pragma("unroll") for (int k = 0; k < 2; ++k) dst[n][k] = *(const LAS bf16x8*)(lds + PG8_SB(b, h) + boff + n * 2048 + k * 1024); } while (0)
; #define PG8_MMA(ai, bj, At, Bt) do { __builtin_amdgcn_s_setprio(1); _Pragma("unroll") for (int m = 0; m < 4; ++m) _Pragma("unroll") for (int n = 0; n < 2; ++n) _Pragma("unroll") for (int k = 0; k < 2; ++k) \
;         acc[ai][bj][m][n] = __builtin_amdgcn_mfma_f32_16x16x32_bf16(Bt[n][k], At[m][k], acc[ai][bj][m][n], 0, 0, 0); __builtin_amdgcn_s_setprio(0); } while (0)
; #define PG8_WAIT_V(n) asm volatile("s_waitcnt vmcnt(" #n ")" ::: "memory")
; #define PG8_WAIT_L(n) asm volatile("s_waitcnt lgkmcnt(" #n ")" ::: "memory")
; #define PG8_BAR __builtin_amdgcn_s_barrier()
; #define PG8_SCHED __builtin_amdgcn_sched_barrier(0)
; template <class Epi, bool ALIGN_EPI = PG8_ALIGN>
; __device__ __forceinline__ void gemm_phase(LAS unsigned char* lds, const Gemm g, const StaticOrder& S, const Epi& E) {
;     ...
;             PG8_WAIT_V(8); PG8_WAIT_L(0); PG8_BAR; PG8_MMA(1, 0, At, B0); PG8_MMA(1, 1, At, B1); PG8_BAR; PG8_SCHED;
;             PG8_LDB(B0, 1, 0); PG8_LDB(B1, 1, 1); PG8_SCHED; PG8_LDA(At, 1, 0); PG8_STAGE(PG8_SA(0, 1), a2 + hstepA, voffA);
;             PG8_WAIT_V(8); PG8_WAIT_L(0); PG8_BAR; PG8_MMA(0, 0, At, B0); PG8_MMA(0, 1, At, B1); PG8_BAR; PG8_SCHED;
	s_setprio 1
	s_waitcnt lgkmcnt(0)
	v_mfma_f32_16x16x32_bf16 v[60:63], v[142:145], v[184:187], v[60:63]
	v_mfma_f32_16x16x32_bf16 v[56:59], v[150:153], v[184:187], v[56:59]
	v_mfma_f32_16x16x32_bf16 v[44:47], v[142:145], v[192:195], v[44:47]
	v_mfma_f32_16x16x32_bf16 v[40:43], v[150:153], v[192:195], v[40:43]
	v_mfma_f32_16x16x32_bf16 v[28:31], v[142:145], v[200:203], v[28:31]
	v_mfma_f32_16x16x32_bf16 v[24:27], v[150:153], v[200:203], v[24:27]
	v_mfma_f32_16x16x32_bf16 v[12:15], v[142:145], v[208:211], v[12:15]
	v_mfma_f32_16x16x32_bf16 v[8:11], v[150:153], v[208:211], v[8:11]
	v_mfma_f32_16x16x32_bf16 v[60:63], v[146:149], v[188:191], v[60:63]
	v_mfma_f32_16x16x32_bf16 v[56:59], v[154:157], v[188:191], v[56:59]
	v_mfma_f32_16x16x32_bf16 v[44:47], v[146:149], v[196:199], v[44:47]
	v_mfma_f32_16x16x32_bf16 v[40:43], v[154:157], v[196:199], v[40:43]
	v_mfma_f32_16x16x32_bf16 v[28:31], v[146:149], v[204:207], v[28:31]
	v_mfma_f32_16x16x32_bf16 v[24:27], v[154:157], v[204:207], v[24:27]
	v_mfma_f32_16x16x32_bf16 v[12:15], v[146:149], v[212:215], v[12:15]
	v_mfma_f32_16x16x32_bf16 v[8:11], v[154:157], v[212:215], v[8:11]
	v_mfma_f32_16x16x32_bf16 v[52:55], v[158:161], v[184:187], v[52:55]
	v_mfma_f32_16x16x32_bf16 v[48:51], v[166:169], v[184:187], v[48:51]
	v_mfma_f32_16x16x32_bf16 v[36:39], v[158:161], v[192:195], v[36:39]
	v_mfma_f32_16x16x32_bf16 v[32:35], v[166:169], v[192:195], v[32:35]
	v_mfma_f32_16x16x32_bf16 v[20:23], v[158:161], v[200:203], v[20:23]
	v_mfma_f32_16x16x32_bf16 v[16:19], v[166:169], v[200:203], v[16:19]
	v_mfma_f32_16x16x32_bf16 v[4:7], v[158:161], v[208:211], v[4:7]
	v_mfma_f32_16x16x32_bf16 v[0:3], v[166:169], v[208:211], v[0:3]
	v_mfma_f32_16x16x32_bf16 v[52:55], v[162:165], v[188:191], v[52:55]
	v_mfma_f32_16x16x32_bf16 v[48:51], v[170:173], v[188:191], v[48:51]
	v_mfma_f32_16x16x32_bf16 v[36:39], v[162:165], v[196:199], v[36:39]
	v_mfma_f32_16x16x32_bf16 v[32:35], v[170:173], v[196:199], v[32:35]
	v_mfma_f32_16x16x32_bf16 v[20:23], v[162:165], v[204:207], v[20:23]
	v_mfma_f32_16x16x32_bf16 v[16:19], v[170:173], v[204:207], v[16:19]
	v_mfma_f32_16x16x32_bf16 v[4:7], v[162:165], v[212:215], v[4:7]
	v_mfma_f32_16x16x32_bf16 v[0:3], v[170:173], v[212:215], v[0:3]
	s_setprio 0
	s_barrier
	s_add_i32 s20, 16, 0x18000
	s_add_i32 s21, 16, 0x1c000
	v_add_u32_e32 v154, s20, v139
	v_add_u32_e32 v170, s21, v139
	ds_read_b128 v[142:145], v154
	ds_read_b128 v[146:149], v154 offset:1024
	ds_read_b128 v[150:153], v154 offset:2048
	ds_read_b128 v[154:157], v154 offset:3072
	ds_read_b128 v[158:161], v170
	ds_read_b128 v[162:165], v170 offset:1024
	ds_read_b128 v[166:169], v170 offset:2048
	ds_read_b128 v[170:173], v170 offset:3072
	s_add_u32 s38, s38, 0x80000
	s_addc_u32 s39, s39, 0
	s_mov_b32 m0, s31
	v_lshl_add_u64 v[226:227], s[38:39], 0, v[132:133]
	ds_read_b128 v[184:187], v141 offset:32768
	ds_read_b128 v[188:191], v141 offset:33792
	ds_read_b128 v[192:195], v141 offset:34816
	ds_read_b128 v[196:199], v141 offset:35840
	ds_read_b128 v[200:203], v141 offset:36864
	ds_read_b128 v[204:207], v141 offset:37888
	ds_read_b128 v[208:211], v141 offset:38912
	ds_read_b128 v[212:215], v141 offset:39936
	global_load_lds_dwordx4 v[226:227], off
	v_lshl_add_u64 v[226:227], s[38:39], 0, v[130:131]
	s_mov_b32 m0, s42
	s_nop 0
	global_load_lds_dwordx4 v[226:227], off
	s_waitcnt vmcnt(8)
	s_waitcnt lgkmcnt(0)
	s_barrier
	s_setprio 1
	s_waitcnt lgkmcnt(0)
	v_mfma_f32_16x16x32_bf16 v[120:123], v[142:145], v[184:187], v[120:123]
	v_mfma_f32_16x16x32_bf16 v[124:127], v[150:153], v[184:187], v[124:127]
	v_mfma_f32_16x16x32_bf16 v[108:111], v[142:145], v[192:195], v[108:111]
	v_mfma_f32_16x16x32_bf16 v[104:107], v[150:153], v[192:195], v[104:107]
	v_mfma_f32_16x16x32_bf16 v[92:95], v[142:145], v[200:203], v[92:95]
	v_mfma_f32_16x16x32_bf16 v[88:91], v[150:153], v[200:203], v[88:91]
	v_mfma_f32_16x16x32_bf16 v[76:79], v[142:145], v[208:211], v[76:79]
	v_mfma_f32_16x16x32_bf16 v[72:75], v[150:153], v[208:211], v[72:75]
	v_mfma_f32_16x16x32_bf16 v[120:123], v[146:149], v[188:191], v[120:123]
	v_mfma_f32_16x16x32_bf16 v[124:127], v[154:157], v[188:191], v[124:127]
	v_mfma_f32_16x16x32_bf16 v[108:111], v[146:149], v[196:199], v[108:111]
	v_mfma_f32_16x16x32_bf16 v[104:107], v[154:157], v[196:199], v[104:107]
	v_mfma_f32_16x16x32_bf16 v[92:95], v[146:149], v[204:207], v[92:95]
	v_mfma_f32_16x16x32_bf16 v[88:91], v[154:157], v[204:207], v[88:91]
	v_mfma_f32_16x16x32_bf16 v[76:79], v[146:149], v[212:215], v[76:79]
	v_mfma_f32_16x16x32_bf16 v[72:75], v[154:157], v[212:215], v[72:75]
	v_mfma_f32_16x16x32_bf16 v[116:119], v[158:161], v[184:187], v[116:119]
	v_mfma_f32_16x16x32_bf16 v[112:115], v[166:169], v[184:187], v[112:115]
	v_mfma_f32_16x16x32_bf16 v[100:103], v[158:161], v[192:195], v[100:103]
	v_mfma_f32_16x16x32_bf16 v[96:99], v[166:169], v[192:195], v[96:99]
	v_mfma_f32_16x16x32_bf16 v[84:87], v[158:161], v[200:203], v[84:87]
	v_mfma_f32_16x16x32_bf16 v[80:83], v[166:169], v[200:203], v[80:83]
	v_mfma_f32_16x16x32_bf16 v[68:71], v[158:161], v[208:211], v[68:71]
	v_mfma_f32_16x16x32_bf16 v[64:67], v[166:169], v[208:211], v[64:67]
	v_mfma_f32_16x16x32_bf16 v[116:119], v[162:165], v[188:191], v[116:119]
	v_mfma_f32_16x16x32_bf16 v[112:115], v[170:173], v[188:191], v[112:115]
	v_mfma_f32_16x16x32_bf16 v[100:103], v[162:165], v[196:199], v[100:103]
	v_mfma_f32_16x16x32_bf16 v[96:99], v[170:173], v[196:199], v[96:99]
	v_mfma_f32_16x16x32_bf16 v[84:87], v[162:165], v[204:207], v[84:87]
	v_mfma_f32_16x16x32_bf16 v[80:83], v[170:173], v[204:207], v[80:83]
	v_mfma_f32_16x16x32_bf16 v[68:71], v[162:165], v[212:215], v[68:71]
	v_mfma_f32_16x16x32_bf16 v[64:67], v[170:173], v[212:215], v[64:67]
	s_setprio 0
	s_barrier
; #define PG8_STAGE(bufoff, gbase, voff) do { _Pragma("unroll") for (int _i = 0; _i < 2; ++_i) \
;         __builtin_amdgcn_global_load_lds((const unsigned*)((const char*)(gbase) + (voff)[_i]), (LAS unsigned*)(lds + (bufoff) + ldsw + _i * 8192), 16, 0, 0); } while (0)
; #define PG8_LDA(dst, b, h) do { _Pragma("unroll") for (int m = 0; m < 4; ++m) _Pragma("unroll") for (int k = 0; k < 2; ++k) dst[m][k] = *(const LAS bf16x8*)(lds + PG8_SA(b, h) + aoff + m * 2048 + k * 1024); } while (0)
; #define PG8_MMA(ai, bj, At, Bt) do { __builtin_amdgcn_s_setprio(1); _Pragma("unroll") for (int m = 0; m < 4; ++m) _Pragma("unroll") for (int n = 0; n < 2; ++n) _Pragma("unroll") for (int k = 0; k < 2; ++k) \
;         acc[ai][bj][m][n] = __builtin_amdgcn_mfma_f32_16x16x32_bf16(Bt[n][k], At[m][k], acc[ai][bj][m][n], 0, 0, 0); __builtin_amdgcn_s_setprio(0); } while (0)
; #define PG8_WAIT_V(n) asm volatile("s_waitcnt vmcnt(" #n ")" ::: "memory")
; #define PG8_WAIT_L(n) asm volatile("s_waitcnt lgkmcnt(" #n ")" ::: "memory")
; #define PG8_BAR __builtin_amdgcn_s_barrier()
; #define PG8_SCHED __builtin_amdgcn_sched_barrier(0)
; template <class Epi, bool ALIGN_EPI = PG8_ALIGN>
; __device__ __forceinline__ void gemm_phase(LAS unsigned char* lds, const Gemm g, const StaticOrder& S, const Epi& E) {
;     ...
;             PG8_LDA(At, 1, 1); PG8_STAGE(PG8_SB(1, 0), b3, voffB); PG8_STAGE(PG8_SB(1, 1), b3 + hstepB, voffB); PG8_STAGE(PG8_SA(1, 0), a3, voffA);
;             PG8_WAIT_V(8); PG8_WAIT_L(0); PG8_BAR; PG8_MMA(1, 0, At, B0); PG8_MMA(1, 1, At, B1); PG8_BAR; PG8_SCHED;
;         }
	s_add_i32 s20, s20, s18
	v_lshl_add_u64 v[174:175], v[174:175], 0, s[0:1]
	s_mov_b32 m0, s20
	ds_read_b128 v[184:187], v141 offset:49152
	ds_read_b128 v[188:191], v141 offset:50176
	ds_read_b128 v[192:195], v141 offset:51200
	ds_read_b128 v[196:199], v141 offset:52224
	ds_read_b128 v[200:203], v141 offset:53248
	ds_read_b128 v[204:207], v141 offset:54272
	ds_read_b128 v[208:211], v141 offset:55296
	ds_read_b128 v[212:215], v141 offset:56320
	global_load_lds_dwordx4 v[174:175], off
	v_lshl_add_u64 v[174:175], v[216:217], 0, s[0:1]
	s_add_i32 m0, s20, 0x2000
	s_add_i32 s20, s21, s18
	global_load_lds_dwordx4 v[174:175], off
	v_lshl_add_u64 v[174:175], v[218:219], 0, s[0:1]
	s_mov_b32 m0, s20
	s_nop 0
	global_load_lds_dwordx4 v[174:175], off
	v_lshl_add_u64 v[174:175], v[220:221], 0, s[0:1]
	s_add_i32 m0, s20, 0x2000
	s_nop 0
	global_load_lds_dwordx4 v[174:175], off
	v_lshl_add_u64 v[174:175], v[222:223], 0, s[0:1]
	s_mov_b32 m0, s34
	s_nop 0
	global_load_lds_dwordx4 v[174:175], off
	v_lshl_add_u64 v[174:175], v[224:225], 0, s[0:1]
	s_mov_b32 m0, s43
	s_nop 0
	global_load_lds_dwordx4 v[174:175], off
	s_waitcnt vmcnt(8)
	s_waitcnt lgkmcnt(0)
	s_barrier
	s_setprio 1
	s_waitcnt lgkmcnt(0)
	v_mfma_f32_16x16x32_bf16 v[60:63], v[142:145], v[184:187], v[60:63]
	v_mfma_f32_16x16x32_bf16 v[56:59], v[150:153], v[184:187], v[56:59]
	v_mfma_f32_16x16x32_bf16 v[44:47], v[142:145], v[192:195], v[44:47]
	v_mfma_f32_16x16x32_bf16 v[40:43], v[150:153], v[192:195], v[40:43]
	v_mfma_f32_16x16x32_bf16 v[28:31], v[142:145], v[200:203], v[28:31]
	v_mfma_f32_16x16x32_bf16 v[24:27], v[150:153], v[200:203], v[24:27]
	v_mfma_f32_16x16x32_bf16 v[12:15], v[142:145], v[208:211], v[12:15]
	v_mfma_f32_16x16x32_bf16 v[8:11], v[150:153], v[208:211], v[8:11]
	v_mfma_f32_16x16x32_bf16 v[60:63], v[146:149], v[188:191], v[60:63]
	v_mfma_f32_16x16x32_bf16 v[56:59], v[154:157], v[188:191], v[56:59]
	v_mfma_f32_16x16x32_bf16 v[44:47], v[146:149], v[196:199], v[44:47]
	v_mfma_f32_16x16x32_bf16 v[40:43], v[154:157], v[196:199], v[40:43]
	v_mfma_f32_16x16x32_bf16 v[28:31], v[146:149], v[204:207], v[28:31]
	v_mfma_f32_16x16x32_bf16 v[24:27], v[154:157], v[204:207], v[24:27]
	v_mfma_f32_16x16x32_bf16 v[12:15], v[146:149], v[212:215], v[12:15]
	v_mfma_f32_16x16x32_bf16 v[8:11], v[154:157], v[212:215], v[8:11]
	v_mfma_f32_16x16x32_bf16 v[52:55], v[158:161], v[184:187], v[52:55]
	v_mfma_f32_16x16x32_bf16 v[48:51], v[166:169], v[184:187], v[48:51]
	v_mfma_f32_16x16x32_bf16 v[36:39], v[158:161], v[192:195], v[36:39]
	v_mfma_f32_16x16x32_bf16 v[32:35], v[166:169], v[192:195], v[32:35]
	v_mfma_f32_16x16x32_bf16 v[20:23], v[158:161], v[200:203], v[20:23]
	v_mfma_f32_16x16x32_bf16 v[16:19], v[166:169], v[200:203], v[16:19]
	v_mfma_f32_16x16x32_bf16 v[4:7], v[158:161], v[208:211], v[4:7]
	v_mfma_f32_16x16x32_bf16 v[0:3], v[166:169], v[208:211], v[0:3]
	v_mfma_f32_16x16x32_bf16 v[52:55], v[162:165], v[188:191], v[52:55]
	v_mfma_f32_16x16x32_bf16 v[48:51], v[170:173], v[188:191], v[48:51]
	v_mfma_f32_16x16x32_bf16 v[36:39], v[162:165], v[196:199], v[36:39]
	v_mfma_f32_16x16x32_bf16 v[32:35], v[170:173], v[196:199], v[32:35]
	v_mfma_f32_16x16x32_bf16 v[20:23], v[162:165], v[204:207], v[20:23]
	v_mfma_f32_16x16x32_bf16 v[16:19], v[170:173], v[204:207], v[16:19]
	v_mfma_f32_16x16x32_bf16 v[4:7], v[162:165], v[212:215], v[4:7]
	v_mfma_f32_16x16x32_bf16 v[0:3], v[170:173], v[212:215], v[0:3]
	s_setprio 0
	s_barrier
	s_add_u32 s4, s4, 0x100
	s_addc_u32 s5, s5, 0
	s_add_u32 s40, s40, 0x100
	s_addc_u32 s41, s41, 0
	s_cmp_ge_i32 s51, s44
	s_mov_b32 s38, s51
	s_cbranch_scc0 .LBB0_458

; #define PG8_STAGE(bufoff, gbase, voff) do { _Pragma("unroll") for (int _i = 0; _i < 2; ++_i) \
;         __builtin_amdgcn_global_load_lds((const unsigned*)((const char*)(gbase) + (voff)[_i]), (LAS unsigned*)(lds + (bufoff) + ldsw + _i * 8192), 16, 0, 0); } while (0)
; #define PG8_LDA(dst, b, h) do { _Pragma("unroll") for (int m = 0; m < 4; ++m) _Pragma("unroll") for (int k = 0; k < 2; ++k) dst[m][k] = *(const LAS bf16x8*)(lds + PG8_SA(b, h) + aoff + m * 2048 + k * 1024); } while (0)
; #define PG8_LDB(dst, b, h) do { _Pragma("unroll") for (int n = 0; n < 2; ++n) _Pragma("unroll") for (int k = 0; k < 2; ++k) dst[n][k] = *(const LAS bf16x8*)(lds + PG8_SB(b, h) + boff + n * 2048 + k * 1024); } while (0)
; #define PG8_MMA(ai, bj, At, Bt) do { __builtin_amdgcn_s_setprio(1); _Pragma("unroll") for (int m = 0; m < 4; ++m) _Pragma("unroll") for (int n = 0; n < 2; ++n) _Pragma("unroll") for (int k = 0; k < 2; ++k) \
;         acc[ai][bj][m][n] = __builtin_amdgcn_mfma_f32_16x16x32_bf16(Bt[n][k], At[m][k], acc[ai][bj][m][n], 0, 0, 0); __builtin_amdgcn_s_setprio(0); } while (0)
; #define PG8_WAIT_V(n) asm volatile("s_waitcnt vmcnt(" #n ")" ::: "memory")
; #define PG8_WAIT_L(n) asm volatile("s_waitcnt lgkmcnt(" #n ")" ::: "memory")
; #define PG8_BAR __builtin_amdgcn_s_barrier()
; #define PG8_SCHED __builtin_amdgcn_sched_barrier(0)
; template <class Epi, bool ALIGN_EPI = PG8_ALIGN>
; __device__ __forceinline__ void gemm_phase(LAS unsigned char* lds, const Gemm g, const StaticOrder& S, const Epi& E) {
;     ...
;             const bool last = (t == nt - 2);
;             const char* a1 = cA + (size_t)(t + 1) * kstep;
;             const char* a2 = last ? nA : cA + (size_t)(t + 2) * kstep; const char* b2 = last ? nB : cB + (size_t)(t + 2) * kstep;
;             const char* a3 = a2 + kstep; const char* b3 = b2 + kstep;
;             PG8_LDB(B0, 0, 0); PG8_LDB(B1, 0, 1); PG8_SCHED; PG8_LDA(At, 0, 0); PG8_STAGE(PG8_SA(1, 1), a1 + hstepA, voffA);
;             PG8_WAIT_V(8); PG8_WAIT_L(0); PG8_BAR; PG8_MMA(0, 0, At, B0); PG8_MMA(0, 1, At, B1); PG8_BAR; PG8_SCHED;
;             PG8_LDA(At, 0, 1); PG8_STAGE(PG8_SB(0, 0), b2, voffB); PG8_STAGE(PG8_SB(0, 1), b2 + hstepB, voffB); PG8_STAGE(PG8_SA(0, 0), a2, voffA);
;             PG8_WAIT_V(8); PG8_WAIT_L(0); PG8_BAR; PG8_MMA(1, 0, At, B0); PG8_MMA(1, 1, At, B1); PG8_BAR; PG8_SCHED;
.LBB0_481:
	s_add_i32 s53, s38, 2
	s_add_u32 s20, s4, 0xffff0080
	s_addc_u32 s21, s5, -1
	s_add_i32 s22, 16, 0x10000
	s_cmp_eq_u32 s47, s38
	s_cselect_b32 s39, s17, s21
	s_cselect_b32 s38, s52, s20
	s_cselect_b32 s55, s25, s41
	s_cselect_b32 s54, s24, s40
	s_add_i32 s20, 16, 0x14000
	v_add_u32_e32 v154, s22, v139
	v_add_u32_e32 v170, s20, v139
	ds_read_b128 v[142:145], v154
	ds_read_b128 v[146:149], v154 offset:1024
	ds_read_b128 v[150:153], v154 offset:2048
	ds_read_b128 v[154:157], v154 offset:3072
	ds_read_b128 v[158:161], v170
	ds_read_b128 v[162:165], v170 offset:1024
	ds_read_b128 v[166:169], v170 offset:2048
	ds_read_b128 v[170:173], v170 offset:3072
	v_lshl_add_u64 v[174:175], s[4:5], 0, v[134:135]
	s_add_i32 m0, s26, 0xc000
	ds_read_b128 v[184:187], v141
	ds_read_b128 v[188:191], v141 offset:1024
	ds_read_b128 v[192:195], v141 offset:2048
	ds_read_b128 v[196:199], v141 offset:3072
	ds_read_b128 v[200:203], v141 offset:4096
	ds_read_b128 v[204:207], v141 offset:5120
	ds_read_b128 v[208:211], v141 offset:6144
	ds_read_b128 v[212:215], v141 offset:7168
	global_load_lds_dwordx4 v[174:175], off
	v_lshl_add_u64 v[174:175], s[4:5], 0, v[136:137]
	s_add_i32 m0, s26, 0xe000
	s_nop 0
	global_load_lds_dwordx4 v[174:175], off
	s_waitcnt vmcnt(8)
	s_waitcnt lgkmcnt(0)
	s_barrier
	s_setprio 1
	s_waitcnt lgkmcnt(0)
	v_mfma_f32_16x16x32_bf16 v[120:123], v[142:145], v[184:187], v[120:123]
	v_mfma_f32_16x16x32_bf16 v[124:127], v[150:153], v[184:187], v[124:127]
	v_mfma_f32_16x16x32_bf16 v[108:111], v[142:145], v[192:195], v[108:111]
	v_mfma_f32_16x16x32_bf16 v[104:107], v[150:153], v[192:195], v[104:107]
	v_mfma_f32_16x16x32_bf16 v[92:95], v[142:145], v[200:203], v[92:95]
	v_mfma_f32_16x16x32_bf16 v[88:91], v[150:153], v[200:203], v[88:91]
	v_mfma_f32_16x16x32_bf16 v[76:79], v[142:145], v[208:211], v[76:79]
	v_mfma_f32_16x16x32_bf16 v[72:75], v[150:153], v[208:211], v[72:75]
	v_mfma_f32_16x16x32_bf16 v[120:123], v[146:149], v[188:191], v[120:123]
	v_mfma_f32_16x16x32_bf16 v[124:127], v[154:157], v[188:191], v[124:127]
	v_mfma_f32_16x16x32_bf16 v[108:111], v[146:149], v[196:199], v[108:111]
	v_mfma_f32_16x16x32_bf16 v[104:107], v[154:157], v[196:199], v[104:107]
	v_mfma_f32_16x16x32_bf16 v[92:95], v[146:149], v[204:207], v[92:95]
	v_mfma_f32_16x16x32_bf16 v[88:91], v[154:157], v[204:207], v[88:91]
	v_mfma_f32_16x16x32_bf16 v[76:79], v[146:149], v[212:215], v[76:79]
	v_mfma_f32_16x16x32_bf16 v[72:75], v[154:157], v[212:215], v[72:75]
	v_mfma_f32_16x16x32_bf16 v[116:119], v[158:161], v[184:187], v[116:119]
	v_mfma_f32_16x16x32_bf16 v[112:115], v[166:169], v[184:187], v[112:115]
	v_mfma_f32_16x16x32_bf16 v[100:103], v[158:161], v[192:195], v[100:103]
	v_mfma_f32_16x16x32_bf16 v[96:99], v[166:169], v[192:195], v[96:99]
	v_mfma_f32_16x16x32_bf16 v[84:87], v[158:161], v[200:203], v[84:87]
	v_mfma_f32_16x16x32_bf16 v[80:83], v[166:169], v[200:203], v[80:83]
	v_mfma_f32_16x16x32_bf16 v[68:71], v[158:161], v[208:211], v[68:71]
	v_mfma_f32_16x16x32_bf16 v[64:67], v[166:169], v[208:211], v[64:67]
	v_mfma_f32_16x16x32_bf16 v[116:119], v[162:165], v[188:191], v[116:119]
	v_mfma_f32_16x16x32_bf16 v[112:115], v[170:173], v[188:191], v[112:115]
	v_mfma_f32_16x16x32_bf16 v[100:103], v[162:165], v[196:199], v[100:103]
	v_mfma_f32_16x16x32_bf16 v[96:99], v[170:173], v[196:199], v[96:99]
	v_mfma_f32_16x16x32_bf16 v[84:87], v[162:165], v[204:207], v[84:87]
	v_mfma_f32_16x16x32_bf16 v[80:83], v[170:173], v[204:207], v[80:83]
	v_mfma_f32_16x16x32_bf16 v[68:71], v[162:165], v[212:215], v[68:71]
	v_mfma_f32_16x16x32_bf16 v[64:67], v[170:173], v[212:215], v[64:67]
	s_setprio 0
	s_barrier
	s_add_i32 s21, s22, s42
	v_lshl_add_u64 v[174:175], s[54:55], 0, v[176:177]
	s_mov_b32 m0, s21
	ds_read_b128 v[184:187], v141 offset:16384
	ds_read_b128 v[188:191], v141 offset:17408
	ds_read_b128 v[192:195], v141 offset:18432
	ds_read_b128 v[196:199], v141 offset:19456
	ds_read_b128 v[200:203], v141 offset:20480
	ds_read_b128 v[204:207], v141 offset:21504
	ds_read_b128 v[208:211], v141 offset:22528
	ds_read_b128 v[212:215], v141 offset:23552
	global_load_lds_dwordx4 v[174:175], off
	s_add_i32 m0, s21, 0x2000
	v_lshl_add_u64 v[216:217], s[54:55], 0, v[128:129]
	s_add_u32 s54, s54, s6
	s_addc_u32 s55, s55, s7
	s_add_i32 s20, s20, s42
	global_load_lds_dwordx4 v[216:217], off
	v_lshl_add_u64 v[218:219], s[54:55], 0, v[176:177]
	s_mov_b32 m0, s20
	v_lshl_add_u64 v[220:221], s[54:55], 0, v[128:129]
	global_load_lds_dwordx4 v[218:219], off
	s_add_i32 m0, s20, 0x2000
	v_lshl_add_u64 v[222:223], s[38:39], 0, v[132:133]
	global_load_lds_dwordx4 v[220:221], off
	s_mov_b32 m0, s26
	v_lshl_add_u64 v[224:225], s[38:39], 0, v[130:131]
	global_load_lds_dwordx4 v[222:223], off
	s_mov_b32 m0, s27
	s_nop 0
	global_load_lds_dwordx4 v[224:225], off
	s_waitcnt vmcnt(8)
	s_waitcnt lgkmcnt(0)
	s_barrier
; #define PG8_STAGE(bufoff, gbase, voff) do { _Pragma("unroll") for (int _i = 0; _i < 2; ++_i) \
;         __builtin_amdgcn_global_load_lds((const unsigned*)((const char*)(gbase) + (voff)[_i]), (LAS unsigned*)(lds + (bufoff) + ldsw + _i * 8192), 16, 0, 0); } while (0)
; #define PG8_LDA(dst, b, h) do { _Pragma("unroll") for (int m = 0; m < 4; ++m) _Pragma("unroll") for (int k = 0; k < 2; ++k) dst[m][k] = *(const LAS bf16x8*)(lds + PG8_SA(b, h) + aoff + m * 2048 + k * 1024); } while (0)
; #define PG8_LDB(dst, b, h) do { _Pragma("unroll") for (int n = 0; n < 2; ++n) _Pragma("unroll") for (int k = 0; k < 2; ++k) dst[n][k] = *(const LAS bf16x8*)(lds + PG8_SB(b, h) + boff + n * 2048 + k * 1024); } while (0)
; #define PG8_MMA(ai, bj, At, Bt) do { __builtin_amdgcn_s_setprio(1); _Pragma("unroll") for (int m = 0; m < 4; ++m) _Pragma("unroll") for (int n = 0; n < 2; ++n) _Pragma("unroll") for (int k = 0; k < 2; ++k) \
;         acc[ai][bj][m][n] = __builtin_amdgcn_mfma_f32_16x16x32_bf16(Bt[n][k], At[m][k], acc[ai][bj][m][n], 0, 0, 0); __builtin_amdgcn_s_setprio(0); } while (0)
; #define PG8_WAIT_V(n) asm volatile("s_waitcnt vmcnt(" #n ")" ::: "memory")
; #define PG8_WAIT_L(n) asm volatile("s_waitcnt lgkmcnt(" #n ")" ::: "memory")
; #define PG8_BAR __builtin_amdgcn_s_barrier()
; #define PG8_SCHED __builtin_amdgcn_sched_barrier(0)
; template <class Epi, bool ALIGN_EPI = PG8_ALIGN>
; __device__ __forceinline__ void gemm_phase(LAS unsigned char* lds, const Gemm g, const StaticOrder& S, const Epi& E) {
;     ...
;             PG8_WAIT_V(8); PG8_WAIT_L(0); PG8_BAR; PG8_MMA(1, 0, At, B0); PG8_MMA(1, 1, At, B1); PG8_BAR; PG8_SCHED;
;             PG8_LDB(B0, 1, 0); PG8_LDB(B1, 1, 1); PG8_SCHED; PG8_LDA(At, 1, 0); PG8_STAGE(PG8_SA(0, 1), a2 + hstepA, voffA);
;             PG8_WAIT_V(8); PG8_WAIT_L(0); PG8_BAR; PG8_MMA(0, 0, At, B0); PG8_MMA(0, 1, At, B1); PG8_BAR; PG8_SCHED;
	s_setprio 1
	s_waitcnt lgkmcnt(0)
	v_mfma_f32_16x16x32_bf16 v[60:63], v[142:145], v[184:187], v[60:63]
	v_mfma_f32_16x16x32_bf16 v[56:59], v[150:153], v[184:187], v[56:59]
	v_mfma_f32_16x16x32_bf16 v[44:47], v[142:145], v[192:195], v[44:47]
	v_mfma_f32_16x16x32_bf16 v[40:43], v[150:153], v[192:195], v[40:43]
	v_mfma_f32_16x16x32_bf16 v[28:31], v[142:145], v[200:203], v[28:31]
	v_mfma_f32_16x16x32_bf16 v[24:27], v[150:153], v[200:203], v[24:27]
	v_mfma_f32_16x16x32_bf16 v[12:15], v[142:145], v[208:211], v[12:15]
	v_mfma_f32_16x16x32_bf16 v[8:11], v[150:153], v[208:211], v[8:11]
	v_mfma_f32_16x16x32_bf16 v[60:63], v[146:149], v[188:191], v[60:63]
	v_mfma_f32_16x16x32_bf16 v[56:59], v[154:157], v[188:191], v[56:59]
	v_mfma_f32_16x16x32_bf16 v[44:47], v[146:149], v[196:199], v[44:47]
	v_mfma_f32_16x16x32_bf16 v[40:43], v[154:157], v[196:199], v[40:43]
	v_mfma_f32_16x16x32_bf16 v[28:31], v[146:149], v[204:207], v[28:31]
	v_mfma_f32_16x16x32_bf16 v[24:27], v[154:157], v[204:207], v[24:27]
	v_mfma_f32_16x16x32_bf16 v[12:15], v[146:149], v[212:215], v[12:15]
	v_mfma_f32_16x16x32_bf16 v[8:11], v[154:157], v[212:215], v[8:11]
	v_mfma_f32_16x16x32_bf16 v[52:55], v[158:161], v[184:187], v[52:55]
	v_mfma_f32_16x16x32_bf16 v[48:51], v[166:169], v[184:187], v[48:51]
	v_mfma_f32_16x16x32_bf16 v[36:39], v[158:161], v[192:195], v[36:39]
	v_mfma_f32_16x16x32_bf16 v[32:35], v[166:169], v[192:195], v[32:35]
	v_mfma_f32_16x16x32_bf16 v[20:23], v[158:161], v[200:203], v[20:23]
	v_mfma_f32_16x16x32_bf16 v[16:19], v[166:169], v[200:203], v[16:19]
	v_mfma_f32_16x16x32_bf16 v[4:7], v[158:161], v[208:211], v[4:7]
	v_mfma_f32_16x16x32_bf16 v[0:3], v[166:169], v[208:211], v[0:3]
	v_mfma_f32_16x16x32_bf16 v[52:55], v[162:165], v[188:191], v[52:55]
	v_mfma_f32_16x16x32_bf16 v[48:51], v[170:173], v[188:191], v[48:51]
	v_mfma_f32_16x16x32_bf16 v[36:39], v[162:165], v[196:199], v[36:39]
	v_mfma_f32_16x16x32_bf16 v[32:35], v[170:173], v[196:199], v[32:35]
	v_mfma_f32_16x16x32_bf16 v[20:23], v[162:165], v[204:207], v[20:23]
	v_mfma_f32_16x16x32_bf16 v[16:19], v[170:173], v[204:207], v[16:19]
	v_mfma_f32_16x16x32_bf16 v[4:7], v[162:165], v[212:215], v[4:7]
	v_mfma_f32_16x16x32_bf16 v[0:3], v[170:173], v[212:215], v[0:3]
	s_setprio 0
	s_barrier
	s_add_i32 s20, 16, 0x18000
	s_add_i32 s21, 16, 0x1c000
	v_add_u32_e32 v154, s20, v139
	v_add_u32_e32 v170, s21, v139
	ds_read_b128 v[142:145], v154
	ds_read_b128 v[146:149], v154 offset:1024
	ds_read_b128 v[150:153], v154 offset:2048
	ds_read_b128 v[154:157], v154 offset:3072
	ds_read_b128 v[158:161], v170
	ds_read_b128 v[162:165], v170 offset:1024
	ds_read_b128 v[166:169], v170 offset:2048
	ds_read_b128 v[170:173], v170 offset:3072
	s_add_u32 s38, s38, 0x10000
	s_addc_u32 s39, s39, 0
	s_mov_b32 m0, s43
	v_lshl_add_u64 v[226:227], s[38:39], 0, v[132:133]
	ds_read_b128 v[184:187], v141 offset:32768
	ds_read_b128 v[188:191], v141 offset:33792
	ds_read_b128 v[192:195], v141 offset:34816
	ds_read_b128 v[196:199], v141 offset:35840
	ds_read_b128 v[200:203], v141 offset:36864
	ds_read_b128 v[204:207], v141 offset:37888
	ds_read_b128 v[208:211], v141 offset:38912
	ds_read_b128 v[212:215], v141 offset:39936
	global_load_lds_dwordx4 v[226:227], off
	v_lshl_add_u64 v[226:227], s[38:39], 0, v[130:131]
	s_mov_b32 m0, s44
	s_nop 0
	global_load_lds_dwordx4 v[226:227], off
	s_waitcnt vmcnt(8)
	s_waitcnt lgkmcnt(0)
	s_barrier
	s_setprio 1
	s_waitcnt lgkmcnt(0)
	v_mfma_f32_16x16x32_bf16 v[120:123], v[142:145], v[184:187], v[120:123]
	v_mfma_f32_16x16x32_bf16 v[124:127], v[150:153], v[184:187], v[124:127]
	v_mfma_f32_16x16x32_bf16 v[108:111], v[142:145], v[192:195], v[108:111]
	v_mfma_f32_16x16x32_bf16 v[104:107], v[150:153], v[192:195], v[104:107]
	v_mfma_f32_16x16x32_bf16 v[92:95], v[142:145], v[200:203], v[92:95]
	v_mfma_f32_16x16x32_bf16 v[88:91], v[150:153], v[200:203], v[88:91]
	v_mfma_f32_16x16x32_bf16 v[76:79], v[142:145], v[208:211], v[76:79]
	v_mfma_f32_16x16x32_bf16 v[72:75], v[150:153], v[208:211], v[72:75]
	v_mfma_f32_16x16x32_bf16 v[120:123], v[146:149], v[188:191], v[120:123]
	v_mfma_f32_16x16x32_bf16 v[124:127], v[154:157], v[188:191], v[124:127]
	v_mfma_f32_16x16x32_bf16 v[108:111], v[146:149], v[196:199], v[108:111]
	v_mfma_f32_16x16x32_bf16 v[104:107], v[154:157], v[196:199], v[104:107]
	v_mfma_f32_16x16x32_bf16 v[92:95], v[146:149], v[204:207], v[92:95]
	v_mfma_f32_16x16x32_bf16 v[88:91], v[154:157], v[204:207], v[88:91]
	v_mfma_f32_16x16x32_bf16 v[76:79], v[146:149], v[212:215], v[76:79]
	v_mfma_f32_16x16x32_bf16 v[72:75], v[154:157], v[212:215], v[72:75]
	v_mfma_f32_16x16x32_bf16 v[116:119], v[158:161], v[184:187], v[116:119]
	v_mfma_f32_16x16x32_bf16 v[112:115], v[166:169], v[184:187], v[112:115]
	v_mfma_f32_16x16x32_bf16 v[100:103], v[158:161], v[192:195], v[100:103]
	v_mfma_f32_16x16x32_bf16 v[96:99], v[166:169], v[192:195], v[96:99]
	v_mfma_f32_16x16x32_bf16 v[84:87], v[158:161], v[200:203], v[84:87]
	v_mfma_f32_16x16x32_bf16 v[80:83], v[166:169], v[200:203], v[80:83]
	v_mfma_f32_16x16x32_bf16 v[68:71], v[158:161], v[208:211], v[68:71]
	v_mfma_f32_16x16x32_bf16 v[64:67], v[166:169], v[208:211], v[64:67]
	v_mfma_f32_16x16x32_bf16 v[116:119], v[162:165], v[188:191], v[116:119]
	v_mfma_f32_16x16x32_bf16 v[112:115], v[170:173], v[188:191], v[112:115]
	v_mfma_f32_16x16x32_bf16 v[100:103], v[162:165], v[196:199], v[100:103]
	v_mfma_f32_16x16x32_bf16 v[96:99], v[170:173], v[196:199], v[96:99]
	v_mfma_f32_16x16x32_bf16 v[84:87], v[162:165], v[204:207], v[84:87]
	v_mfma_f32_16x16x32_bf16 v[80:83], v[170:173], v[204:207], v[80:83]
	v_mfma_f32_16x16x32_bf16 v[68:71], v[162:165], v[212:215], v[68:71]
	v_mfma_f32_16x16x32_bf16 v[64:67], v[170:173], v[212:215], v[64:67]
	s_setprio 0
	s_barrier
; #define PG8_STAGE(bufoff, gbase, voff) do { _Pragma("unroll") for (int _i = 0; _i < 2; ++_i) \
;         __builtin_amdgcn_global_load_lds((const unsigned*)((const char*)(gbase) + (voff)[_i]), (LAS unsigned*)(lds + (bufoff) + ldsw + _i * 8192), 16, 0, 0); } while (0)
; #define PG8_LDA(dst, b, h) do { _Pragma("unroll") for (int m = 0; m < 4; ++m) _Pragma("unroll") for (int k = 0; k < 2; ++k) dst[m][k] = *(const LAS bf16x8*)(lds + PG8_SA(b, h) + aoff + m * 2048 + k * 1024); } while (0)
; #define PG8_MMA(ai, bj, At, Bt) do { __builtin_amdgcn_s_setprio(1); _Pragma("unroll") for (int m = 0; m < 4; ++m) _Pragma("unroll") for (int n = 0; n < 2; ++n) _Pragma("unroll") for (int k = 0; k < 2; ++k) \
;         acc[ai][bj][m][n] = __builtin_amdgcn_mfma_f32_16x16x32_bf16(Bt[n][k], At[m][k], acc[ai][bj][m][n], 0, 0, 0); __builtin_amdgcn_s_setprio(0); } while (0)
; #define PG8_WAIT_V(n) asm volatile("s_waitcnt vmcnt(" #n ")" ::: "memory")
; #define PG8_WAIT_L(n) asm volatile("s_waitcnt lgkmcnt(" #n ")" ::: "memory")
; #define PG8_BAR __builtin_amdgcn_s_barrier()
; #define PG8_SCHED __builtin_amdgcn_sched_barrier(0)
; template <class Epi, bool ALIGN_EPI = PG8_ALIGN>
; __device__ __forceinline__ void gemm_phase(LAS unsigned char* lds, const Gemm g, const StaticOrder& S, const Epi& E) {
;     ...
;             PG8_LDA(At, 1, 1); PG8_STAGE(PG8_SB(1, 0), b3, voffB); PG8_STAGE(PG8_SB(1, 1), b3 + hstepB, voffB); PG8_STAGE(PG8_SA(1, 0), a3, voffA);
;             PG8_WAIT_V(8); PG8_WAIT_L(0); PG8_BAR; PG8_MMA(1, 0, At, B0); PG8_MMA(1, 1, At, B1); PG8_BAR; PG8_SCHED;
;         }
	s_add_i32 s20, s20, s42
	v_lshl_add_u64 v[174:175], v[174:175], 0, s[0:1]
	s_mov_b32 m0, s20
	ds_read_b128 v[184:187], v141 offset:49152
	ds_read_b128 v[188:191], v141 offset:50176
	ds_read_b128 v[192:195], v141 offset:51200
	ds_read_b128 v[196:199], v141 offset:52224
	ds_read_b128 v[200:203], v141 offset:53248
	ds_read_b128 v[204:207], v141 offset:54272
	ds_read_b128 v[208:211], v141 offset:55296
	ds_read_b128 v[212:215], v141 offset:56320
	global_load_lds_dwordx4 v[174:175], off
	v_lshl_add_u64 v[174:175], v[216:217], 0, s[0:1]
	s_add_i32 m0, s20, 0x2000
	s_add_i32 s20, s21, s42
	global_load_lds_dwordx4 v[174:175], off
	v_lshl_add_u64 v[174:175], v[218:219], 0, s[0:1]
	s_mov_b32 m0, s20
	s_nop 0
	global_load_lds_dwordx4 v[174:175], off
	v_lshl_add_u64 v[174:175], v[220:221], 0, s[0:1]
	s_add_i32 m0, s20, 0x2000
	s_nop 0
	global_load_lds_dwordx4 v[174:175], off
	v_lshl_add_u64 v[174:175], v[222:223], 0, s[0:1]
	s_mov_b32 m0, s45
	s_nop 0
	global_load_lds_dwordx4 v[174:175], off
	v_lshl_add_u64 v[174:175], v[224:225], 0, s[0:1]
	s_mov_b32 m0, s46
	s_nop 0
	global_load_lds_dwordx4 v[174:175], off
	s_waitcnt vmcnt(8)
	s_waitcnt lgkmcnt(0)
	s_barrier
	s_setprio 1
	s_waitcnt lgkmcnt(0)
	v_mfma_f32_16x16x32_bf16 v[60:63], v[142:145], v[184:187], v[60:63]
	v_mfma_f32_16x16x32_bf16 v[56:59], v[150:153], v[184:187], v[56:59]
	v_mfma_f32_16x16x32_bf16 v[44:47], v[142:145], v[192:195], v[44:47]
	v_mfma_f32_16x16x32_bf16 v[40:43], v[150:153], v[192:195], v[40:43]
	v_mfma_f32_16x16x32_bf16 v[28:31], v[142:145], v[200:203], v[28:31]
	v_mfma_f32_16x16x32_bf16 v[24:27], v[150:153], v[200:203], v[24:27]
	v_mfma_f32_16x16x32_bf16 v[12:15], v[142:145], v[208:211], v[12:15]
	v_mfma_f32_16x16x32_bf16 v[8:11], v[150:153], v[208:211], v[8:11]
	v_mfma_f32_16x16x32_bf16 v[60:63], v[146:149], v[188:191], v[60:63]
	v_mfma_f32_16x16x32_bf16 v[56:59], v[154:157], v[188:191], v[56:59]
	v_mfma_f32_16x16x32_bf16 v[44:47], v[146:149], v[196:199], v[44:47]
	v_mfma_f32_16x16x32_bf16 v[40:43], v[154:157], v[196:199], v[40:43]
	v_mfma_f32_16x16x32_bf16 v[28:31], v[146:149], v[204:207], v[28:31]
	v_mfma_f32_16x16x32_bf16 v[24:27], v[154:157], v[204:207], v[24:27]
	v_mfma_f32_16x16x32_bf16 v[12:15], v[146:149], v[212:215], v[12:15]
	v_mfma_f32_16x16x32_bf16 v[8:11], v[154:157], v[212:215], v[8:11]
	v_mfma_f32_16x16x32_bf16 v[52:55], v[158:161], v[184:187], v[52:55]
	v_mfma_f32_16x16x32_bf16 v[48:51], v[166:169], v[184:187], v[48:51]
	v_mfma_f32_16x16x32_bf16 v[36:39], v[158:161], v[192:195], v[36:39]
	v_mfma_f32_16x16x32_bf16 v[32:35], v[166:169], v[192:195], v[32:35]
	v_mfma_f32_16x16x32_bf16 v[20:23], v[158:161], v[200:203], v[20:23]
	v_mfma_f32_16x16x32_bf16 v[16:19], v[166:169], v[200:203], v[16:19]
	v_mfma_f32_16x16x32_bf16 v[4:7], v[158:161], v[208:211], v[4:7]
	v_mfma_f32_16x16x32_bf16 v[0:3], v[166:169], v[208:211], v[0:3]
	v_mfma_f32_16x16x32_bf16 v[52:55], v[162:165], v[188:191], v[52:55]
	v_mfma_f32_16x16x32_bf16 v[48:51], v[170:173], v[188:191], v[48:51]
	v_mfma_f32_16x16x32_bf16 v[36:39], v[162:165], v[196:199], v[36:39]
	v_mfma_f32_16x16x32_bf16 v[32:35], v[170:173], v[196:199], v[32:35]
	v_mfma_f32_16x16x32_bf16 v[20:23], v[162:165], v[204:207], v[20:23]
	v_mfma_f32_16x16x32_bf16 v[16:19], v[170:173], v[204:207], v[16:19]
	v_mfma_f32_16x16x32_bf16 v[4:7], v[162:165], v[212:215], v[4:7]
	v_mfma_f32_16x16x32_bf16 v[0:3], v[170:173], v[212:215], v[0:3]
	s_setprio 0
	s_barrier
	s_add_u32 s4, s4, 0x100
	s_addc_u32 s5, s5, 0
	s_add_u32 s40, s40, 0x100
	s_addc_u32 s41, s41, 0
	s_cmp_ge_i32 s53, s34
	s_mov_b32 s38, s53
	s_cbranch_scc0 .LBB0_481

; #define PG8_STAGE(bufoff, gbase, voff) do { _Pragma("unroll") for (int _i = 0; _i < 2; ++_i) \
;         __builtin_amdgcn_global_load_lds((const unsigned*)((const char*)(gbase) + (voff)[_i]), (LAS unsigned*)(lds + (bufoff) + ldsw + _i * 8192), 16, 0, 0); } while (0)
; #define PG8_LDA(dst, b, h) do { _Pragma("unroll") for (int m = 0; m < 4; ++m) _Pragma("unroll") for (int k = 0; k < 2; ++k) dst[m][k] = *(const LAS bf16x8*)(lds + PG8_SA(b, h) + aoff + m * 2048 + k * 1024); } while (0)
; #define PG8_LDB(dst, b, h) do { _Pragma("unroll") for (int n = 0; n < 2; ++n) _Pragma("unroll") for (int k = 0; k < 2; ++k) dst[n][k] = *(const LAS bf16x8*)(lds + PG8_SB(b, h) + boff + n * 2048 + k * 1024); } while (0)
; #define PG8_MMA(ai, bj, At, Bt) do { __builtin_amdgcn_s_setprio(1); _Pragma("unroll") for (int m = 0; m < 4; ++m) _Pragma("unroll") for (int n = 0; n < 2; ++n) _Pragma("unroll") for (int k = 0; k < 2; ++k) \
;         acc[ai][bj][m][n] = __builtin_amdgcn_mfma_f32_16x16x32_bf16(Bt[n][k], At[m][k], acc[ai][bj][m][n], 0, 0, 0); __builtin_amdgcn_s_setprio(0); } while (0)
; #define PG8_WAIT_V(n) asm volatile("s_waitcnt vmcnt(" #n ")" ::: "memory")
; #define PG8_WAIT_L(n) asm volatile("s_waitcnt lgkmcnt(" #n ")" ::: "memory")
; #define PG8_BAR __builtin_amdgcn_s_barrier()
; #define PG8_SCHED __builtin_amdgcn_sched_barrier(0)
; template <class Epi, bool ALIGN_EPI = PG8_ALIGN>
; __device__ __forceinline__ void gemm_phase(LAS unsigned char* lds, const Gemm g, const StaticOrder& S, const Epi& E) {
;     ...
;             const bool last = (t == nt - 2);
;             const char* a1 = cA + (size_t)(t + 1) * kstep;
;             const char* a2 = last ? nA : cA + (size_t)(t + 2) * kstep; const char* b2 = last ? nB : cB + (size_t)(t + 2) * kstep;
;             const char* a3 = a2 + kstep; const char* b3 = b2 + kstep;
;             PG8_LDB(B0, 0, 0); PG8_LDB(B1, 0, 1); PG8_SCHED; PG8_LDA(At, 0, 0); PG8_STAGE(PG8_SA(1, 1), a1 + hstepA, voffA);
;             PG8_WAIT_V(8); PG8_WAIT_L(0); PG8_BAR; PG8_MMA(0, 0, At, B0); PG8_MMA(0, 1, At, B1); PG8_BAR; PG8_SCHED;
;             PG8_LDA(At, 0, 1); PG8_STAGE(PG8_SB(0, 0), b2, voffB); PG8_STAGE(PG8_SB(0, 1), b2 + hstepB, voffB); PG8_STAGE(PG8_SA(0, 0), a2, voffA);
;             PG8_WAIT_V(8); PG8_WAIT_L(0); PG8_BAR; PG8_MMA(1, 0, At, B0); PG8_MMA(1, 1, At, B1); PG8_BAR; PG8_SCHED;
.LBB0_642:
	s_add_i32 s53, s38, 2
	s_add_u32 s36, s24, 0x100
	s_addc_u32 s37, s25, 0
	s_add_i32 s20, 16, 0x10000
	s_cmp_eq_u32 s48, s38
	s_cselect_b32 s39, s3, s37
	s_cselect_b32 s38, s2, s36
	v_add_u32_e32 v142, s20, v149
	s_cselect_b32 s55, s17, s52
	s_cselect_b32 s54, s16, s51
	s_add_i32 s21, 16, 0x14000
	ds_read_b128 v[138:141], v142
	ds_read_b128 v[152:155], v142 offset:1024
	ds_read_b128 v[156:159], v142 offset:2048
	ds_read_b128 v[160:163], v142 offset:3072
	v_add_u32_e32 v142, s21, v149
	ds_read_b128 v[164:167], v142
	ds_read_b128 v[168:171], v142 offset:1024
	ds_read_b128 v[172:175], v142 offset:2048
	ds_read_b128 v[184:187], v142 offset:3072
	v_lshl_add_u64 v[142:143], s[24:25], 0, v[134:135]
	s_add_i32 m0, s31, 0xc000
	ds_read_b128 v[188:191], v151
	ds_read_b128 v[192:195], v151 offset:1024
	ds_read_b128 v[196:199], v151 offset:2048
	ds_read_b128 v[200:203], v151 offset:3072
	ds_read_b128 v[204:207], v151 offset:4096
	ds_read_b128 v[208:211], v151 offset:5120
	ds_read_b128 v[212:215], v151 offset:6144
	ds_read_b128 v[216:219], v151 offset:7168
	global_load_lds_dwordx4 v[142:143], off
	v_lshl_add_u64 v[142:143], s[24:25], 0, v[136:137]
	s_add_i32 m0, s31, 0xe000
	s_nop 0
	global_load_lds_dwordx4 v[142:143], off
	s_waitcnt vmcnt(8)
	s_waitcnt lgkmcnt(0)
	s_barrier
	s_setprio 1
	s_waitcnt lgkmcnt(0)
	v_mfma_f32_16x16x32_bf16 v[120:123], v[138:141], v[188:191], v[120:123]
	v_mfma_f32_16x16x32_bf16 v[124:127], v[156:159], v[188:191], v[124:127]
	v_mfma_f32_16x16x32_bf16 v[108:111], v[138:141], v[196:199], v[108:111]
	v_mfma_f32_16x16x32_bf16 v[104:107], v[156:159], v[196:199], v[104:107]
	v_mfma_f32_16x16x32_bf16 v[92:95], v[138:141], v[204:207], v[92:95]
	v_mfma_f32_16x16x32_bf16 v[88:91], v[156:159], v[204:207], v[88:91]
	v_mfma_f32_16x16x32_bf16 v[76:79], v[138:141], v[212:215], v[76:79]
	v_mfma_f32_16x16x32_bf16 v[72:75], v[156:159], v[212:215], v[72:75]
	v_mfma_f32_16x16x32_bf16 v[120:123], v[152:155], v[192:195], v[120:123]
	v_mfma_f32_16x16x32_bf16 v[124:127], v[160:163], v[192:195], v[124:127]
	v_mfma_f32_16x16x32_bf16 v[108:111], v[152:155], v[200:203], v[108:111]
	v_mfma_f32_16x16x32_bf16 v[104:107], v[160:163], v[200:203], v[104:107]
	v_mfma_f32_16x16x32_bf16 v[92:95], v[152:155], v[208:211], v[92:95]
	v_mfma_f32_16x16x32_bf16 v[88:91], v[160:163], v[208:211], v[88:91]
	v_mfma_f32_16x16x32_bf16 v[76:79], v[152:155], v[216:219], v[76:79]
	v_mfma_f32_16x16x32_bf16 v[72:75], v[160:163], v[216:219], v[72:75]
	v_mfma_f32_16x16x32_bf16 v[116:119], v[164:167], v[188:191], v[116:119]
	v_mfma_f32_16x16x32_bf16 v[112:115], v[172:175], v[188:191], v[112:115]
	v_mfma_f32_16x16x32_bf16 v[100:103], v[164:167], v[196:199], v[100:103]
	v_mfma_f32_16x16x32_bf16 v[96:99], v[172:175], v[196:199], v[96:99]
	v_mfma_f32_16x16x32_bf16 v[84:87], v[164:167], v[204:207], v[84:87]
	v_mfma_f32_16x16x32_bf16 v[80:83], v[172:175], v[204:207], v[80:83]
	v_mfma_f32_16x16x32_bf16 v[68:71], v[164:167], v[212:215], v[68:71]
	v_mfma_f32_16x16x32_bf16 v[64:67], v[172:175], v[212:215], v[64:67]
	v_mfma_f32_16x16x32_bf16 v[116:119], v[168:171], v[192:195], v[116:119]
	v_mfma_f32_16x16x32_bf16 v[112:115], v[184:187], v[192:195], v[112:115]
	v_mfma_f32_16x16x32_bf16 v[100:103], v[168:171], v[200:203], v[100:103]
	v_mfma_f32_16x16x32_bf16 v[96:99], v[184:187], v[200:203], v[96:99]
	v_mfma_f32_16x16x32_bf16 v[84:87], v[168:171], v[208:211], v[84:87]
	v_mfma_f32_16x16x32_bf16 v[80:83], v[184:187], v[208:211], v[80:83]
	v_mfma_f32_16x16x32_bf16 v[68:71], v[168:171], v[216:219], v[68:71]
	v_mfma_f32_16x16x32_bf16 v[64:67], v[184:187], v[216:219], v[64:67]
	s_setprio 0
	s_barrier
	s_add_i32 s20, s20, s30
	v_lshl_add_u64 v[142:143], s[54:55], 0, v[176:177]
	s_mov_b32 m0, s20
	ds_read_b128 v[188:191], v151 offset:16384
	ds_read_b128 v[192:195], v151 offset:17408
	ds_read_b128 v[196:199], v151 offset:18432
	ds_read_b128 v[200:203], v151 offset:19456
	ds_read_b128 v[204:207], v151 offset:20480
	ds_read_b128 v[208:211], v151 offset:21504
	ds_read_b128 v[212:215], v151 offset:22528
	ds_read_b128 v[216:219], v151 offset:23552
	global_load_lds_dwordx4 v[142:143], off
	s_add_i32 m0, s20, 0x2000
	s_add_u32 s24, s54, s6
	v_lshl_add_u64 v[146:147], s[54:55], 0, v[128:129]
	s_addc_u32 s25, s55, s7
	s_add_i32 s20, s21, s30
	global_load_lds_dwordx4 v[146:147], off
	v_lshl_add_u64 v[220:221], s[24:25], 0, v[176:177]
	s_mov_b32 m0, s20
	v_lshl_add_u64 v[222:223], s[24:25], 0, v[128:129]
	global_load_lds_dwordx4 v[220:221], off
	s_add_i32 m0, s20, 0x2000
	v_lshl_add_u64 v[224:225], s[38:39], 0, v[132:133]
	global_load_lds_dwordx4 v[222:223], off
	s_mov_b32 m0, s31
	v_lshl_add_u64 v[226:227], s[38:39], 0, v[130:131]
	global_load_lds_dwordx4 v[224:225], off
	s_mov_b32 m0, s40
	s_nop 0
	global_load_lds_dwordx4 v[226:227], off
	s_waitcnt vmcnt(8)
	s_waitcnt lgkmcnt(0)
	s_barrier
; #define PG8_STAGE(bufoff, gbase, voff) do { _Pragma("unroll") for (int _i = 0; _i < 2; ++_i) \
;         __builtin_amdgcn_global_load_lds((const unsigned*)((const char*)(gbase) + (voff)[_i]), (LAS unsigned*)(lds + (bufoff) + ldsw + _i * 8192), 16, 0, 0); } while (0)
; #define PG8_LDA(dst, b, h) do { _Pragma("unroll") for (int m = 0; m < 4; ++m) _Pragma("unroll") for (int k = 0; k < 2; ++k) dst[m][k] = *(const LAS bf16x8*)(lds + PG8_SA(b, h) + aoff + m * 2048 + k * 1024); } while (0)
; #define PG8_LDB(dst, b, h) do { _Pragma("unroll") for (int n = 0; n < 2; ++n) _Pragma("unroll") for (int k = 0; k < 2; ++k) dst[n][k] = *(const LAS bf16x8*)(lds + PG8_SB(b, h) + boff + n * 2048 + k * 1024); } while (0)
; #define PG8_MMA(ai, bj, At, Bt) do { __builtin_amdgcn_s_setprio(1); _Pragma("unroll") for (int m = 0; m < 4; ++m) _Pragma("unroll") for (int n = 0; n < 2; ++n) _Pragma("unroll") for (int k = 0; k < 2; ++k) \
;         acc[ai][bj][m][n] = __builtin_amdgcn_mfma_f32_16x16x32_bf16(Bt[n][k], At[m][k], acc[ai][bj][m][n], 0, 0, 0); __builtin_amdgcn_s_setprio(0); } while (0)
; #define PG8_WAIT_V(n) asm volatile("s_waitcnt vmcnt(" #n ")" ::: "memory")
; #define PG8_WAIT_L(n) asm volatile("s_waitcnt lgkmcnt(" #n ")" ::: "memory")
; #define PG8_BAR __builtin_amdgcn_s_barrier()
; #define PG8_SCHED __builtin_amdgcn_sched_barrier(0)
; template <class Epi, bool ALIGN_EPI = PG8_ALIGN>
; __device__ __forceinline__ void gemm_phase(LAS unsigned char* lds, const Gemm g, const StaticOrder& S, const Epi& E) {
;     ...
;             PG8_WAIT_V(8); PG8_WAIT_L(0); PG8_BAR; PG8_MMA(1, 0, At, B0); PG8_MMA(1, 1, At, B1); PG8_BAR; PG8_SCHED;
;             PG8_LDB(B0, 1, 0); PG8_LDB(B1, 1, 1); PG8_SCHED; PG8_LDA(At, 1, 0); PG8_STAGE(PG8_SA(0, 1), a2 + hstepA, voffA);
;             PG8_WAIT_V(8); PG8_WAIT_L(0); PG8_BAR; PG8_MMA(0, 0, At, B0); PG8_MMA(0, 1, At, B1); PG8_BAR; PG8_SCHED;
	s_setprio 1
	s_waitcnt lgkmcnt(0)
	v_mfma_f32_16x16x32_bf16 v[60:63], v[138:141], v[188:191], v[60:63]
	v_mfma_f32_16x16x32_bf16 v[56:59], v[156:159], v[188:191], v[56:59]
	v_mfma_f32_16x16x32_bf16 v[44:47], v[138:141], v[196:199], v[44:47]
	v_mfma_f32_16x16x32_bf16 v[40:43], v[156:159], v[196:199], v[40:43]
	v_mfma_f32_16x16x32_bf16 v[28:31], v[138:141], v[204:207], v[28:31]
	v_mfma_f32_16x16x32_bf16 v[24:27], v[156:159], v[204:207], v[24:27]
	v_mfma_f32_16x16x32_bf16 v[12:15], v[138:141], v[212:215], v[12:15]
	v_mfma_f32_16x16x32_bf16 v[8:11], v[156:159], v[212:215], v[8:11]
	v_mfma_f32_16x16x32_bf16 v[60:63], v[152:155], v[192:195], v[60:63]
	v_mfma_f32_16x16x32_bf16 v[56:59], v[160:163], v[192:195], v[56:59]
	v_mfma_f32_16x16x32_bf16 v[44:47], v[152:155], v[200:203], v[44:47]
	v_mfma_f32_16x16x32_bf16 v[40:43], v[160:163], v[200:203], v[40:43]
	v_mfma_f32_16x16x32_bf16 v[28:31], v[152:155], v[208:211], v[28:31]
	v_mfma_f32_16x16x32_bf16 v[24:27], v[160:163], v[208:211], v[24:27]
	v_mfma_f32_16x16x32_bf16 v[12:15], v[152:155], v[216:219], v[12:15]
	v_mfma_f32_16x16x32_bf16 v[8:11], v[160:163], v[216:219], v[8:11]
	v_mfma_f32_16x16x32_bf16 v[52:55], v[164:167], v[188:191], v[52:55]
	v_mfma_f32_16x16x32_bf16 v[48:51], v[172:175], v[188:191], v[48:51]
	v_mfma_f32_16x16x32_bf16 v[36:39], v[164:167], v[196:199], v[36:39]
	v_mfma_f32_16x16x32_bf16 v[32:35], v[172:175], v[196:199], v[32:35]
	v_mfma_f32_16x16x32_bf16 v[20:23], v[164:167], v[204:207], v[20:23]
	v_mfma_f32_16x16x32_bf16 v[16:19], v[172:175], v[204:207], v[16:19]
	v_mfma_f32_16x16x32_bf16 v[4:7], v[164:167], v[212:215], v[4:7]
	v_mfma_f32_16x16x32_bf16 v[0:3], v[172:175], v[212:215], v[0:3]
	v_mfma_f32_16x16x32_bf16 v[52:55], v[168:171], v[192:195], v[52:55]
	v_mfma_f32_16x16x32_bf16 v[48:51], v[184:187], v[192:195], v[48:51]
	v_mfma_f32_16x16x32_bf16 v[36:39], v[168:171], v[200:203], v[36:39]
	v_mfma_f32_16x16x32_bf16 v[32:35], v[184:187], v[200:203], v[32:35]
	v_mfma_f32_16x16x32_bf16 v[20:23], v[168:171], v[208:211], v[20:23]
	v_mfma_f32_16x16x32_bf16 v[16:19], v[184:187], v[208:211], v[16:19]
	v_mfma_f32_16x16x32_bf16 v[4:7], v[168:171], v[216:219], v[4:7]
	v_mfma_f32_16x16x32_bf16 v[0:3], v[184:187], v[216:219], v[0:3]
	s_setprio 0
	s_barrier
	s_add_i32 s20, 16, 0x18000
	v_add_u32_e32 v144, s20, v149
	s_add_i32 s21, 16, 0x1c000
	ds_read_b128 v[138:141], v144
	ds_read_b128 v[152:155], v144 offset:1024
	ds_read_b128 v[156:159], v144 offset:2048
	ds_read_b128 v[160:163], v144 offset:3072
	v_add_u32_e32 v144, s21, v149
	ds_read_b128 v[164:167], v144
	ds_read_b128 v[168:171], v144 offset:1024
	ds_read_b128 v[172:175], v144 offset:2048
	ds_read_b128 v[184:187], v144 offset:3072
	s_add_u32 s24, s38, 0x110000
	s_addc_u32 s25, s39, 0
	s_mov_b32 m0, s41
	v_lshl_add_u64 v[228:229], s[24:25], 0, v[132:133]
	ds_read_b128 v[188:191], v151 offset:32768
	ds_read_b128 v[192:195], v151 offset:33792
	ds_read_b128 v[196:199], v151 offset:34816
	ds_read_b128 v[200:203], v151 offset:35840
	ds_read_b128 v[204:207], v151 offset:36864
	ds_read_b128 v[208:211], v151 offset:37888
	ds_read_b128 v[212:215], v151 offset:38912
	ds_read_b128 v[216:219], v151 offset:39936
	global_load_lds_dwordx4 v[228:229], off
	v_lshl_add_u64 v[228:229], s[24:25], 0, v[130:131]
	s_mov_b32 m0, s44
	s_nop 0
	global_load_lds_dwordx4 v[228:229], off
	s_waitcnt vmcnt(8)
	s_waitcnt lgkmcnt(0)
	s_barrier
	s_setprio 1
	s_waitcnt lgkmcnt(0)
	v_mfma_f32_16x16x32_bf16 v[120:123], v[138:141], v[188:191], v[120:123]
	v_mfma_f32_16x16x32_bf16 v[124:127], v[156:159], v[188:191], v[124:127]
	v_mfma_f32_16x16x32_bf16 v[108:111], v[138:141], v[196:199], v[108:111]
	v_mfma_f32_16x16x32_bf16 v[104:107], v[156:159], v[196:199], v[104:107]
	v_mfma_f32_16x16x32_bf16 v[92:95], v[138:141], v[204:207], v[92:95]
	v_mfma_f32_16x16x32_bf16 v[88:91], v[156:159], v[204:207], v[88:91]
	v_mfma_f32_16x16x32_bf16 v[76:79], v[138:141], v[212:215], v[76:79]
	v_mfma_f32_16x16x32_bf16 v[72:75], v[156:159], v[212:215], v[72:75]
	v_mfma_f32_16x16x32_bf16 v[120:123], v[152:155], v[192:195], v[120:123]
	v_mfma_f32_16x16x32_bf16 v[124:127], v[160:163], v[192:195], v[124:127]
	v_mfma_f32_16x16x32_bf16 v[108:111], v[152:155], v[200:203], v[108:111]
	v_mfma_f32_16x16x32_bf16 v[104:107], v[160:163], v[200:203], v[104:107]
	v_mfma_f32_16x16x32_bf16 v[92:95], v[152:155], v[208:211], v[92:95]
	v_mfma_f32_16x16x32_bf16 v[88:91], v[160:163], v[208:211], v[88:91]
	v_mfma_f32_16x16x32_bf16 v[76:79], v[152:155], v[216:219], v[76:79]
	v_mfma_f32_16x16x32_bf16 v[72:75], v[160:163], v[216:219], v[72:75]
	v_mfma_f32_16x16x32_bf16 v[116:119], v[164:167], v[188:191], v[116:119]
	v_mfma_f32_16x16x32_bf16 v[112:115], v[172:175], v[188:191], v[112:115]
	v_mfma_f32_16x16x32_bf16 v[100:103], v[164:167], v[196:199], v[100:103]
	v_mfma_f32_16x16x32_bf16 v[96:99], v[172:175], v[196:199], v[96:99]
	v_mfma_f32_16x16x32_bf16 v[84:87], v[164:167], v[204:207], v[84:87]
	v_mfma_f32_16x16x32_bf16 v[80:83], v[172:175], v[204:207], v[80:83]
	v_mfma_f32_16x16x32_bf16 v[68:71], v[164:167], v[212:215], v[68:71]
	v_mfma_f32_16x16x32_bf16 v[64:67], v[172:175], v[212:215], v[64:67]
	v_mfma_f32_16x16x32_bf16 v[116:119], v[168:171], v[192:195], v[116:119]
	v_mfma_f32_16x16x32_bf16 v[112:115], v[184:187], v[192:195], v[112:115]
	v_mfma_f32_16x16x32_bf16 v[100:103], v[168:171], v[200:203], v[100:103]
	v_mfma_f32_16x16x32_bf16 v[96:99], v[184:187], v[200:203], v[96:99]
	v_mfma_f32_16x16x32_bf16 v[84:87], v[168:171], v[208:211], v[84:87]
	v_mfma_f32_16x16x32_bf16 v[80:83], v[184:187], v[208:211], v[80:83]
	v_mfma_f32_16x16x32_bf16 v[68:71], v[168:171], v[216:219], v[68:71]
	v_mfma_f32_16x16x32_bf16 v[64:67], v[184:187], v[216:219], v[64:67]
	s_setprio 0
	s_barrier
; #define PG8_STAGE(bufoff, gbase, voff) do { _Pragma("unroll") for (int _i = 0; _i < 2; ++_i) \
;         __builtin_amdgcn_global_load_lds((const unsigned*)((const char*)(gbase) + (voff)[_i]), (LAS unsigned*)(lds + (bufoff) + ldsw + _i * 8192), 16, 0, 0); } while (0)
; #define PG8_LDA(dst, b, h) do { _Pragma("unroll") for (int m = 0; m < 4; ++m) _Pragma("unroll") for (int k = 0; k < 2; ++k) dst[m][k] = *(const LAS bf16x8*)(lds + PG8_SA(b, h) + aoff + m * 2048 + k * 1024); } while (0)
; #define PG8_MMA(ai, bj, At, Bt) do { __builtin_amdgcn_s_setprio(1); _Pragma("unroll") for (int m = 0; m < 4; ++m) _Pragma("unroll") for (int n = 0; n < 2; ++n) _Pragma("unroll") for (int k = 0; k < 2; ++k) \
;         acc[ai][bj][m][n] = __builtin_amdgcn_mfma_f32_16x16x32_bf16(Bt[n][k], At[m][k], acc[ai][bj][m][n], 0, 0, 0); __builtin_amdgcn_s_setprio(0); } while (0)
; #define PG8_WAIT_V(n) asm volatile("s_waitcnt vmcnt(" #n ")" ::: "memory")
; #define PG8_WAIT_L(n) asm volatile("s_waitcnt lgkmcnt(" #n ")" ::: "memory")
; #define PG8_BAR __builtin_amdgcn_s_barrier()
; #define PG8_SCHED __builtin_amdgcn_sched_barrier(0)
; template <class Epi, bool ALIGN_EPI = PG8_ALIGN>
; __device__ __forceinline__ void gemm_phase(LAS unsigned char* lds, const Gemm g, const StaticOrder& S, const Epi& E) {
;     ...
;             PG8_LDA(At, 1, 1); PG8_STAGE(PG8_SB(1, 0), b3, voffB); PG8_STAGE(PG8_SB(1, 1), b3 + hstepB, voffB); PG8_STAGE(PG8_SA(1, 0), a3, voffA);
;             PG8_WAIT_V(8); PG8_WAIT_L(0); PG8_BAR; PG8_MMA(1, 0, At, B0); PG8_MMA(1, 1, At, B1); PG8_BAR; PG8_SCHED;
;         }
	s_add_i32 s20, s20, s30
	v_lshl_add_u64 v[142:143], v[142:143], 0, s[0:1]
	s_mov_b32 m0, s20
	ds_read_b128 v[188:191], v151 offset:49152
	ds_read_b128 v[192:195], v151 offset:50176
	ds_read_b128 v[196:199], v151 offset:51200
	ds_read_b128 v[200:203], v151 offset:52224
	ds_read_b128 v[204:207], v151 offset:53248
	ds_read_b128 v[208:211], v151 offset:54272
	ds_read_b128 v[212:215], v151 offset:55296
	ds_read_b128 v[216:219], v151 offset:56320
	global_load_lds_dwordx4 v[142:143], off
	v_lshl_add_u64 v[142:143], v[146:147], 0, s[0:1]
	s_add_i32 m0, s20, 0x2000
	s_add_i32 s20, s21, s30
	global_load_lds_dwordx4 v[142:143], off
	v_lshl_add_u64 v[142:143], v[220:221], 0, s[0:1]
	s_mov_b32 m0, s20
	s_nop 0
	global_load_lds_dwordx4 v[142:143], off
	v_lshl_add_u64 v[142:143], v[222:223], 0, s[0:1]
	s_add_i32 m0, s20, 0x2000
	s_nop 0
	global_load_lds_dwordx4 v[142:143], off
	v_lshl_add_u64 v[142:143], v[224:225], 0, s[0:1]
	s_mov_b32 m0, s45
	s_nop 0
	global_load_lds_dwordx4 v[142:143], off
	v_lshl_add_u64 v[142:143], v[226:227], 0, s[0:1]
	s_mov_b32 m0, s46
	s_nop 0
	global_load_lds_dwordx4 v[142:143], off
	s_waitcnt vmcnt(8)
	s_waitcnt lgkmcnt(0)
	s_barrier
	s_setprio 1
	s_waitcnt lgkmcnt(0)
	v_mfma_f32_16x16x32_bf16 v[60:63], v[138:141], v[188:191], v[60:63]
	v_mfma_f32_16x16x32_bf16 v[56:59], v[156:159], v[188:191], v[56:59]
	v_mfma_f32_16x16x32_bf16 v[44:47], v[138:141], v[196:199], v[44:47]
	v_mfma_f32_16x16x32_bf16 v[40:43], v[156:159], v[196:199], v[40:43]
	v_mfma_f32_16x16x32_bf16 v[28:31], v[138:141], v[204:207], v[28:31]
	v_mfma_f32_16x16x32_bf16 v[24:27], v[156:159], v[204:207], v[24:27]
	v_mfma_f32_16x16x32_bf16 v[12:15], v[138:141], v[212:215], v[12:15]
	v_mfma_f32_16x16x32_bf16 v[8:11], v[156:159], v[212:215], v[8:11]
	v_mfma_f32_16x16x32_bf16 v[60:63], v[152:155], v[192:195], v[60:63]
	v_mfma_f32_16x16x32_bf16 v[56:59], v[160:163], v[192:195], v[56:59]
	v_mfma_f32_16x16x32_bf16 v[44:47], v[152:155], v[200:203], v[44:47]
	v_mfma_f32_16x16x32_bf16 v[40:43], v[160:163], v[200:203], v[40:43]
	v_mfma_f32_16x16x32_bf16 v[28:31], v[152:155], v[208:211], v[28:31]
	v_mfma_f32_16x16x32_bf16 v[24:27], v[160:163], v[208:211], v[24:27]
	v_mfma_f32_16x16x32_bf16 v[12:15], v[152:155], v[216:219], v[12:15]
	v_mfma_f32_16x16x32_bf16 v[8:11], v[160:163], v[216:219], v[8:11]
	v_mfma_f32_16x16x32_bf16 v[52:55], v[164:167], v[188:191], v[52:55]
	v_mfma_f32_16x16x32_bf16 v[48:51], v[172:175], v[188:191], v[48:51]
	v_mfma_f32_16x16x32_bf16 v[36:39], v[164:167], v[196:199], v[36:39]
	v_mfma_f32_16x16x32_bf16 v[32:35], v[172:175], v[196:199], v[32:35]
	v_mfma_f32_16x16x32_bf16 v[20:23], v[164:167], v[204:207], v[20:23]
	v_mfma_f32_16x16x32_bf16 v[16:19], v[172:175], v[204:207], v[16:19]
	v_mfma_f32_16x16x32_bf16 v[4:7], v[164:167], v[212:215], v[4:7]
	v_mfma_f32_16x16x32_bf16 v[0:3], v[172:175], v[212:215], v[0:3]
	v_mfma_f32_16x16x32_bf16 v[52:55], v[168:171], v[192:195], v[52:55]
	v_mfma_f32_16x16x32_bf16 v[48:51], v[184:187], v[192:195], v[48:51]
	v_mfma_f32_16x16x32_bf16 v[36:39], v[168:171], v[200:203], v[36:39]
	v_mfma_f32_16x16x32_bf16 v[32:35], v[184:187], v[200:203], v[32:35]
	v_mfma_f32_16x16x32_bf16 v[20:23], v[168:171], v[208:211], v[20:23]
	v_mfma_f32_16x16x32_bf16 v[16:19], v[184:187], v[208:211], v[16:19]
	v_mfma_f32_16x16x32_bf16 v[4:7], v[168:171], v[216:219], v[4:7]
	v_mfma_f32_16x16x32_bf16 v[0:3], v[184:187], v[216:219], v[0:3]
	s_setprio 0
	s_barrier
	s_add_u32 s51, s51, 0x100
	s_addc_u32 s52, s52, 0
	s_cmp_ge_i32 s53, s47
	s_mov_b64 s[24:25], s[36:37]
	s_mov_b32 s38, s53
	s_cbranch_scc0 .LBB0_642

; #define PG8_STAGE(bufoff, gbase, voff) do { _Pragma("unroll") for (int _i = 0; _i < 2; ++_i) \
;         __builtin_amdgcn_global_load_lds((const unsigned*)((const char*)(gbase) + (voff)[_i]), (LAS unsigned*)(lds + (bufoff) + ldsw + _i * 8192), 16, 0, 0); } while (0)
; #define PG8_LDA(dst, b, h) do { _Pragma("unroll") for (int m = 0; m < 4; ++m) _Pragma("unroll") for (int k = 0; k < 2; ++k) dst[m][k] = *(const LAS bf16x8*)(lds + PG8_SA(b, h) + aoff + m * 2048 + k * 1024); } while (0)
; #define PG8_LDB(dst, b, h) do { _Pragma("unroll") for (int n = 0; n < 2; ++n) _Pragma("unroll") for (int k = 0; k < 2; ++k) dst[n][k] = *(const LAS bf16x8*)(lds + PG8_SB(b, h) + boff + n * 2048 + k * 1024); } while (0)
; #define PG8_MMA(ai, bj, At, Bt) do { __builtin_amdgcn_s_setprio(1); _Pragma("unroll") for (int m = 0; m < 4; ++m) _Pragma("unroll") for (int n = 0; n < 2; ++n) _Pragma("unroll") for (int k = 0; k < 2; ++k) \
;         acc[ai][bj][m][n] = __builtin_amdgcn_mfma_f32_16x16x32_bf16(Bt[n][k], At[m][k], acc[ai][bj][m][n], 0, 0, 0); __builtin_amdgcn_s_setprio(0); } while (0)
; #define PG8_WAIT_V(n) asm volatile("s_waitcnt vmcnt(" #n ")" ::: "memory")
; #define PG8_WAIT_L(n) asm volatile("s_waitcnt lgkmcnt(" #n ")" ::: "memory")
; #define PG8_BAR __builtin_amdgcn_s_barrier()
; #define PG8_SCHED __builtin_amdgcn_sched_barrier(0)
; template <class Epi, bool ALIGN_EPI = PG8_ALIGN>
; __device__ __forceinline__ void gemm_phase(LAS unsigned char* lds, const Gemm g, const StaticOrder& S, const Epi& E) {
;     ...
;             const bool last = (t == nt - 2);
;             const char* a1 = cA + (size_t)(t + 1) * kstep;
;             const char* a2 = last ? nA : cA + (size_t)(t + 2) * kstep; const char* b2 = last ? nB : cB + (size_t)(t + 2) * kstep;
;             const char* a3 = a2 + kstep; const char* b3 = b2 + kstep;
;             PG8_LDB(B0, 0, 0); PG8_LDB(B1, 0, 1); PG8_SCHED; PG8_LDA(At, 0, 0); PG8_STAGE(PG8_SA(1, 1), a1 + hstepA, voffA);
;             PG8_WAIT_V(8); PG8_WAIT_L(0); PG8_BAR; PG8_MMA(0, 0, At, B0); PG8_MMA(0, 1, At, B1); PG8_BAR; PG8_SCHED;
;             PG8_LDA(At, 0, 1); PG8_STAGE(PG8_SB(0, 0), b2, voffB); PG8_STAGE(PG8_SB(0, 1), b2 + hstepB, voffB); PG8_STAGE(PG8_SA(0, 0), a2, voffA);
;             PG8_WAIT_V(8); PG8_WAIT_L(0); PG8_BAR; PG8_MMA(1, 0, At, B0); PG8_MMA(1, 1, At, B1); PG8_BAR; PG8_SCHED;
.LBB0_663:
	s_add_i32 s53, s38, 2
	s_add_u32 s36, s24, 0x100
	s_addc_u32 s37, s25, 0
	s_add_i32 s20, 16, 0x10000
	s_cmp_eq_u32 s48, s38
	s_cselect_b32 s39, s3, s37
	s_cselect_b32 s38, s2, s36
	v_add_u32_e32 v138, s20, v143
	s_cselect_b32 s55, s17, s52
	s_cselect_b32 s54, s16, s34
	s_add_i32 s21, 16, 0x14000
	ds_read_b128 v[152:155], v138
	ds_read_b128 v[156:159], v138 offset:1024
	ds_read_b128 v[160:163], v138 offset:2048
	ds_read_b128 v[164:167], v138 offset:3072
	v_add_u32_e32 v138, s21, v143
	ds_read_b128 v[168:171], v138
	ds_read_b128 v[172:175], v138 offset:1024
	ds_read_b128 v[184:187], v138 offset:2048
	ds_read_b128 v[188:191], v138 offset:3072
	v_lshl_add_u64 v[140:141], s[24:25], 0, v[134:135]
	s_add_i32 m0, s31, 0xc000
	ds_read_b128 v[192:195], v151
	ds_read_b128 v[196:199], v151 offset:1024
	ds_read_b128 v[200:203], v151 offset:2048
	ds_read_b128 v[204:207], v151 offset:3072
	ds_read_b128 v[208:211], v151 offset:4096
	ds_read_b128 v[212:215], v151 offset:5120
	ds_read_b128 v[216:219], v151 offset:6144
	ds_read_b128 v[220:223], v151 offset:7168
	global_load_lds_dwordx4 v[140:141], off
	v_lshl_add_u64 v[140:141], s[24:25], 0, v[136:137]
	s_add_i32 m0, s31, 0xe000
	s_nop 0
	global_load_lds_dwordx4 v[140:141], off
	s_waitcnt vmcnt(8)
	s_waitcnt lgkmcnt(0)
	s_barrier
	s_setprio 1
	s_waitcnt lgkmcnt(0)
	v_mfma_f32_16x16x32_bf16 v[120:123], v[152:155], v[192:195], v[120:123]
	v_mfma_f32_16x16x32_bf16 v[124:127], v[160:163], v[192:195], v[124:127]
	v_mfma_f32_16x16x32_bf16 v[108:111], v[152:155], v[200:203], v[108:111]
	v_mfma_f32_16x16x32_bf16 v[104:107], v[160:163], v[200:203], v[104:107]
	v_mfma_f32_16x16x32_bf16 v[92:95], v[152:155], v[208:211], v[92:95]
	v_mfma_f32_16x16x32_bf16 v[88:91], v[160:163], v[208:211], v[88:91]
	v_mfma_f32_16x16x32_bf16 v[76:79], v[152:155], v[216:219], v[76:79]
	v_mfma_f32_16x16x32_bf16 v[72:75], v[160:163], v[216:219], v[72:75]
	v_mfma_f32_16x16x32_bf16 v[120:123], v[156:159], v[196:199], v[120:123]
	v_mfma_f32_16x16x32_bf16 v[124:127], v[164:167], v[196:199], v[124:127]
	v_mfma_f32_16x16x32_bf16 v[108:111], v[156:159], v[204:207], v[108:111]
	v_mfma_f32_16x16x32_bf16 v[104:107], v[164:167], v[204:207], v[104:107]
	v_mfma_f32_16x16x32_bf16 v[92:95], v[156:159], v[212:215], v[92:95]
	v_mfma_f32_16x16x32_bf16 v[88:91], v[164:167], v[212:215], v[88:91]
	v_mfma_f32_16x16x32_bf16 v[76:79], v[156:159], v[220:223], v[76:79]
	v_mfma_f32_16x16x32_bf16 v[72:75], v[164:167], v[220:223], v[72:75]
	v_mfma_f32_16x16x32_bf16 v[116:119], v[168:171], v[192:195], v[116:119]
	v_mfma_f32_16x16x32_bf16 v[112:115], v[184:187], v[192:195], v[112:115]
	v_mfma_f32_16x16x32_bf16 v[100:103], v[168:171], v[200:203], v[100:103]
	v_mfma_f32_16x16x32_bf16 v[96:99], v[184:187], v[200:203], v[96:99]
	v_mfma_f32_16x16x32_bf16 v[84:87], v[168:171], v[208:211], v[84:87]
	v_mfma_f32_16x16x32_bf16 v[80:83], v[184:187], v[208:211], v[80:83]
	v_mfma_f32_16x16x32_bf16 v[68:71], v[168:171], v[216:219], v[68:71]
	v_mfma_f32_16x16x32_bf16 v[64:67], v[184:187], v[216:219], v[64:67]
	v_mfma_f32_16x16x32_bf16 v[116:119], v[172:175], v[196:199], v[116:119]
	v_mfma_f32_16x16x32_bf16 v[112:115], v[188:191], v[196:199], v[112:115]
	v_mfma_f32_16x16x32_bf16 v[100:103], v[172:175], v[204:207], v[100:103]
	v_mfma_f32_16x16x32_bf16 v[96:99], v[188:191], v[204:207], v[96:99]
	v_mfma_f32_16x16x32_bf16 v[84:87], v[172:175], v[212:215], v[84:87]
	v_mfma_f32_16x16x32_bf16 v[80:83], v[188:191], v[212:215], v[80:83]
	v_mfma_f32_16x16x32_bf16 v[68:71], v[172:175], v[220:223], v[68:71]
	v_mfma_f32_16x16x32_bf16 v[64:67], v[188:191], v[220:223], v[64:67]
	s_setprio 0
	s_barrier
	s_add_i32 s20, s20, s30
	v_lshl_add_u64 v[140:141], s[54:55], 0, v[176:177]
	s_mov_b32 m0, s20
	ds_read_b128 v[192:195], v151 offset:16384
	ds_read_b128 v[196:199], v151 offset:17408
	ds_read_b128 v[200:203], v151 offset:18432
	ds_read_b128 v[204:207], v151 offset:19456
	ds_read_b128 v[208:211], v151 offset:20480
	ds_read_b128 v[212:215], v151 offset:21504
	ds_read_b128 v[216:219], v151 offset:22528
	ds_read_b128 v[220:223], v151 offset:23552
	global_load_lds_dwordx4 v[140:141], off
	s_add_i32 m0, s20, 0x2000
	s_add_u32 s24, s54, s6
	v_lshl_add_u64 v[144:145], s[54:55], 0, v[128:129]
	s_addc_u32 s25, s55, s7
	s_add_i32 s20, s21, s30
	global_load_lds_dwordx4 v[144:145], off
	v_lshl_add_u64 v[148:149], s[24:25], 0, v[176:177]
	s_mov_b32 m0, s20
	v_lshl_add_u64 v[224:225], s[24:25], 0, v[128:129]
	global_load_lds_dwordx4 v[148:149], off
	s_add_i32 m0, s20, 0x2000
	v_lshl_add_u64 v[226:227], s[38:39], 0, v[132:133]
	global_load_lds_dwordx4 v[224:225], off
	s_mov_b32 m0, s31
	v_lshl_add_u64 v[228:229], s[38:39], 0, v[130:131]
	global_load_lds_dwordx4 v[226:227], off
	s_mov_b32 m0, s40
	s_nop 0
	global_load_lds_dwordx4 v[228:229], off
	s_waitcnt vmcnt(8)
	s_waitcnt lgkmcnt(0)
	s_barrier
; #define PG8_STAGE(bufoff, gbase, voff) do { _Pragma("unroll") for (int _i = 0; _i < 2; ++_i) \
;         __builtin_amdgcn_global_load_lds((const unsigned*)((const char*)(gbase) + (voff)[_i]), (LAS unsigned*)(lds + (bufoff) + ldsw + _i * 8192), 16, 0, 0); } while (0)
; #define PG8_LDA(dst, b, h) do { _Pragma("unroll") for (int m = 0; m < 4; ++m) _Pragma("unroll") for (int k = 0; k < 2; ++k) dst[m][k] = *(const LAS bf16x8*)(lds + PG8_SA(b, h) + aoff + m * 2048 + k * 1024); } while (0)
; #define PG8_LDB(dst, b, h) do { _Pragma("unroll") for (int n = 0; n < 2; ++n) _Pragma("unroll") for (int k = 0; k < 2; ++k) dst[n][k] = *(const LAS bf16x8*)(lds + PG8_SB(b, h) + boff + n * 2048 + k * 1024); } while (0)
; #define PG8_MMA(ai, bj, At, Bt) do { __builtin_amdgcn_s_setprio(1); _Pragma("unroll") for (int m = 0; m < 4; ++m) _Pragma("unroll") for (int n = 0; n < 2; ++n) _Pragma("unroll") for (int k = 0; k < 2; ++k) \
;         acc[ai][bj][m][n] = __builtin_amdgcn_mfma_f32_16x16x32_bf16(Bt[n][k], At[m][k], acc[ai][bj][m][n], 0, 0, 0); __builtin_amdgcn_s_setprio(0); } while (0)
; #define PG8_WAIT_V(n) asm volatile("s_waitcnt vmcnt(" #n ")" ::: "memory")
; #define PG8_WAIT_L(n) asm volatile("s_waitcnt lgkmcnt(" #n ")" ::: "memory")
; #define PG8_BAR __builtin_amdgcn_s_barrier()
; #define PG8_SCHED __builtin_amdgcn_sched_barrier(0)
; template <class Epi, bool ALIGN_EPI = PG8_ALIGN>
; __device__ __forceinline__ void gemm_phase(LAS unsigned char* lds, const Gemm g, const StaticOrder& S, const Epi& E) {
;     ...
;             PG8_WAIT_V(8); PG8_WAIT_L(0); PG8_BAR; PG8_MMA(1, 0, At, B0); PG8_MMA(1, 1, At, B1); PG8_BAR; PG8_SCHED;
;             PG8_LDB(B0, 1, 0); PG8_LDB(B1, 1, 1); PG8_SCHED; PG8_LDA(At, 1, 0); PG8_STAGE(PG8_SA(0, 1), a2 + hstepA, voffA);
;             PG8_WAIT_V(8); PG8_WAIT_L(0); PG8_BAR; PG8_MMA(0, 0, At, B0); PG8_MMA(0, 1, At, B1); PG8_BAR; PG8_SCHED;
	s_setprio 1
	s_waitcnt lgkmcnt(0)
	v_mfma_f32_16x16x32_bf16 v[60:63], v[152:155], v[192:195], v[60:63]
	v_mfma_f32_16x16x32_bf16 v[56:59], v[160:163], v[192:195], v[56:59]
	v_mfma_f32_16x16x32_bf16 v[44:47], v[152:155], v[200:203], v[44:47]
	v_mfma_f32_16x16x32_bf16 v[40:43], v[160:163], v[200:203], v[40:43]
	v_mfma_f32_16x16x32_bf16 v[28:31], v[152:155], v[208:211], v[28:31]
	v_mfma_f32_16x16x32_bf16 v[24:27], v[160:163], v[208:211], v[24:27]
	v_mfma_f32_16x16x32_bf16 v[12:15], v[152:155], v[216:219], v[12:15]
	v_mfma_f32_16x16x32_bf16 v[8:11], v[160:163], v[216:219], v[8:11]
	v_mfma_f32_16x16x32_bf16 v[60:63], v[156:159], v[196:199], v[60:63]
	v_mfma_f32_16x16x32_bf16 v[56:59], v[164:167], v[196:199], v[56:59]
	v_mfma_f32_16x16x32_bf16 v[44:47], v[156:159], v[204:207], v[44:47]
	v_mfma_f32_16x16x32_bf16 v[40:43], v[164:167], v[204:207], v[40:43]
	v_mfma_f32_16x16x32_bf16 v[28:31], v[156:159], v[212:215], v[28:31]
	v_mfma_f32_16x16x32_bf16 v[24:27], v[164:167], v[212:215], v[24:27]
	v_mfma_f32_16x16x32_bf16 v[12:15], v[156:159], v[220:223], v[12:15]
	v_mfma_f32_16x16x32_bf16 v[8:11], v[164:167], v[220:223], v[8:11]
	v_mfma_f32_16x16x32_bf16 v[52:55], v[168:171], v[192:195], v[52:55]
	v_mfma_f32_16x16x32_bf16 v[48:51], v[184:187], v[192:195], v[48:51]
	v_mfma_f32_16x16x32_bf16 v[36:39], v[168:171], v[200:203], v[36:39]
	v_mfma_f32_16x16x32_bf16 v[32:35], v[184:187], v[200:203], v[32:35]
	v_mfma_f32_16x16x32_bf16 v[20:23], v[168:171], v[208:211], v[20:23]
	v_mfma_f32_16x16x32_bf16 v[16:19], v[184:187], v[208:211], v[16:19]
	v_mfma_f32_16x16x32_bf16 v[4:7], v[168:171], v[216:219], v[4:7]
	v_mfma_f32_16x16x32_bf16 v[0:3], v[184:187], v[216:219], v[0:3]
	v_mfma_f32_16x16x32_bf16 v[52:55], v[172:175], v[196:199], v[52:55]
	v_mfma_f32_16x16x32_bf16 v[48:51], v[188:191], v[196:199], v[48:51]
	v_mfma_f32_16x16x32_bf16 v[36:39], v[172:175], v[204:207], v[36:39]
	v_mfma_f32_16x16x32_bf16 v[32:35], v[188:191], v[204:207], v[32:35]
	v_mfma_f32_16x16x32_bf16 v[20:23], v[172:175], v[212:215], v[20:23]
	v_mfma_f32_16x16x32_bf16 v[16:19], v[188:191], v[212:215], v[16:19]
	v_mfma_f32_16x16x32_bf16 v[4:7], v[172:175], v[220:223], v[4:7]
	v_mfma_f32_16x16x32_bf16 v[0:3], v[188:191], v[220:223], v[0:3]
	s_setprio 0
	s_barrier
	s_add_i32 s20, 16, 0x18000
	v_add_u32_e32 v138, s20, v143
	s_add_i32 s21, 16, 0x1c000
	ds_read_b128 v[152:155], v138
	ds_read_b128 v[156:159], v138 offset:1024
	ds_read_b128 v[160:163], v138 offset:2048
	ds_read_b128 v[164:167], v138 offset:3072
	v_add_u32_e32 v138, s21, v143
	ds_read_b128 v[168:171], v138
	ds_read_b128 v[172:175], v138 offset:1024
	ds_read_b128 v[184:187], v138 offset:2048
	ds_read_b128 v[188:191], v138 offset:3072
	s_add_u32 s24, s38, 0x110000
	s_addc_u32 s25, s39, 0
	s_mov_b32 m0, s41
	v_lshl_add_u64 v[230:231], s[24:25], 0, v[132:133]
	ds_read_b128 v[192:195], v151 offset:32768
	ds_read_b128 v[196:199], v151 offset:33792
	ds_read_b128 v[200:203], v151 offset:34816
	ds_read_b128 v[204:207], v151 offset:35840
	ds_read_b128 v[208:211], v151 offset:36864
	ds_read_b128 v[212:215], v151 offset:37888
	ds_read_b128 v[216:219], v151 offset:38912
	ds_read_b128 v[220:223], v151 offset:39936
	global_load_lds_dwordx4 v[230:231], off
	v_lshl_add_u64 v[230:231], s[24:25], 0, v[130:131]
	s_mov_b32 m0, s44
	s_nop 0
	global_load_lds_dwordx4 v[230:231], off
	s_waitcnt vmcnt(8)
	s_waitcnt lgkmcnt(0)
	s_barrier
	s_setprio 1
	s_waitcnt lgkmcnt(0)
	v_mfma_f32_16x16x32_bf16 v[120:123], v[152:155], v[192:195], v[120:123]
	v_mfma_f32_16x16x32_bf16 v[124:127], v[160:163], v[192:195], v[124:127]
	v_mfma_f32_16x16x32_bf16 v[108:111], v[152:155], v[200:203], v[108:111]
	v_mfma_f32_16x16x32_bf16 v[104:107], v[160:163], v[200:203], v[104:107]
	v_mfma_f32_16x16x32_bf16 v[92:95], v[152:155], v[208:211], v[92:95]
	v_mfma_f32_16x16x32_bf16 v[88:91], v[160:163], v[208:211], v[88:91]
	v_mfma_f32_16x16x32_bf16 v[76:79], v[152:155], v[216:219], v[76:79]
	v_mfma_f32_16x16x32_bf16 v[72:75], v[160:163], v[216:219], v[72:75]
	v_mfma_f32_16x16x32_bf16 v[120:123], v[156:159], v[196:199], v[120:123]
	v_mfma_f32_16x16x32_bf16 v[124:127], v[164:167], v[196:199], v[124:127]
	v_mfma_f32_16x16x32_bf16 v[108:111], v[156:159], v[204:207], v[108:111]
	v_mfma_f32_16x16x32_bf16 v[104:107], v[164:167], v[204:207], v[104:107]
	v_mfma_f32_16x16x32_bf16 v[92:95], v[156:159], v[212:215], v[92:95]
	v_mfma_f32_16x16x32_bf16 v[88:91], v[164:167], v[212:215], v[88:91]
	v_mfma_f32_16x16x32_bf16 v[76:79], v[156:159], v[220:223], v[76:79]
	v_mfma_f32_16x16x32_bf16 v[72:75], v[164:167], v[220:223], v[72:75]
	v_mfma_f32_16x16x32_bf16 v[116:119], v[168:171], v[192:195], v[116:119]
	v_mfma_f32_16x16x32_bf16 v[112:115], v[184:187], v[192:195], v[112:115]
	v_mfma_f32_16x16x32_bf16 v[100:103], v[168:171], v[200:203], v[100:103]
	v_mfma_f32_16x16x32_bf16 v[96:99], v[184:187], v[200:203], v[96:99]
	v_mfma_f32_16x16x32_bf16 v[84:87], v[168:171], v[208:211], v[84:87]
	v_mfma_f32_16x16x32_bf16 v[80:83], v[184:187], v[208:211], v[80:83]
	v_mfma_f32_16x16x32_bf16 v[68:71], v[168:171], v[216:219], v[68:71]
	v_mfma_f32_16x16x32_bf16 v[64:67], v[184:187], v[216:219], v[64:67]
	v_mfma_f32_16x16x32_bf16 v[116:119], v[172:175], v[196:199], v[116:119]
	v_mfma_f32_16x16x32_bf16 v[112:115], v[188:191], v[196:199], v[112:115]
	v_mfma_f32_16x16x32_bf16 v[100:103], v[172:175], v[204:207], v[100:103]
	v_mfma_f32_16x16x32_bf16 v[96:99], v[188:191], v[204:207], v[96:99]
	v_mfma_f32_16x16x32_bf16 v[84:87], v[172:175], v[212:215], v[84:87]
	v_mfma_f32_16x16x32_bf16 v[80:83], v[188:191], v[212:215], v[80:83]
	v_mfma_f32_16x16x32_bf16 v[68:71], v[172:175], v[220:223], v[68:71]
	v_mfma_f32_16x16x32_bf16 v[64:67], v[188:191], v[220:223], v[64:67]
	s_setprio 0
	s_barrier
; #define PG8_STAGE(bufoff, gbase, voff) do { _Pragma("unroll") for (int _i = 0; _i < 2; ++_i) \
;         __builtin_amdgcn_global_load_lds((const unsigned*)((const char*)(gbase) + (voff)[_i]), (LAS unsigned*)(lds + (bufoff) + ldsw + _i * 8192), 16, 0, 0); } while (0)
; #define PG8_LDA(dst, b, h) do { _Pragma("unroll") for (int m = 0; m < 4; ++m) _Pragma("unroll") for (int k = 0; k < 2; ++k) dst[m][k] = *(const LAS bf16x8*)(lds + PG8_SA(b, h) + aoff + m * 2048 + k * 1024); } while (0)
; #define PG8_MMA(ai, bj, At, Bt) do { __builtin_amdgcn_s_setprio(1); _Pragma("unroll") for (int m = 0; m < 4; ++m) _Pragma("unroll") for (int n = 0; n < 2; ++n) _Pragma("unroll") for (int k = 0; k < 2; ++k) \
;         acc[ai][bj][m][n] = __builtin_amdgcn_mfma_f32_16x16x32_bf16(Bt[n][k], At[m][k], acc[ai][bj][m][n], 0, 0, 0); __builtin_amdgcn_s_setprio(0); } while (0)
; #define PG8_WAIT_V(n) asm volatile("s_waitcnt vmcnt(" #n ")" ::: "memory")
; #define PG8_WAIT_L(n) asm volatile("s_waitcnt lgkmcnt(" #n ")" ::: "memory")
; #define PG8_BAR __builtin_amdgcn_s_barrier()
; #define PG8_SCHED __builtin_amdgcn_sched_barrier(0)
; template <class Epi, bool ALIGN_EPI = PG8_ALIGN>
; __device__ __forceinline__ void gemm_phase(LAS unsigned char* lds, const Gemm g, const StaticOrder& S, const Epi& E) {
;     ...
;             PG8_LDA(At, 1, 1); PG8_STAGE(PG8_SB(1, 0), b3, voffB); PG8_STAGE(PG8_SB(1, 1), b3 + hstepB, voffB); PG8_STAGE(PG8_SA(1, 0), a3, voffA);
;             PG8_WAIT_V(8); PG8_WAIT_L(0); PG8_BAR; PG8_MMA(1, 0, At, B0); PG8_MMA(1, 1, At, B1); PG8_BAR; PG8_SCHED;
;         }
	s_add_i32 s20, s20, s30
	v_lshl_add_u64 v[140:141], v[140:141], 0, s[0:1]
	s_mov_b32 m0, s20
	ds_read_b128 v[192:195], v151 offset:49152
	ds_read_b128 v[196:199], v151 offset:50176
	ds_read_b128 v[200:203], v151 offset:51200
	ds_read_b128 v[204:207], v151 offset:52224
	ds_read_b128 v[208:211], v151 offset:53248
	ds_read_b128 v[212:215], v151 offset:54272
	ds_read_b128 v[216:219], v151 offset:55296
	ds_read_b128 v[220:223], v151 offset:56320
	global_load_lds_dwordx4 v[140:141], off
	v_lshl_add_u64 v[140:141], v[144:145], 0, s[0:1]
	s_add_i32 m0, s20, 0x2000
	s_add_i32 s20, s21, s30
	global_load_lds_dwordx4 v[140:141], off
	v_lshl_add_u64 v[140:141], v[148:149], 0, s[0:1]
	s_mov_b32 m0, s20
	s_nop 0
	global_load_lds_dwordx4 v[140:141], off
	v_lshl_add_u64 v[140:141], v[224:225], 0, s[0:1]
	s_add_i32 m0, s20, 0x2000
	s_nop 0
	global_load_lds_dwordx4 v[140:141], off
	v_lshl_add_u64 v[140:141], v[226:227], 0, s[0:1]
	s_mov_b32 m0, s45
	s_nop 0
	global_load_lds_dwordx4 v[140:141], off
	v_lshl_add_u64 v[140:141], v[228:229], 0, s[0:1]
	s_mov_b32 m0, s46
	s_nop 0
	global_load_lds_dwordx4 v[140:141], off
	s_waitcnt vmcnt(8)
	s_waitcnt lgkmcnt(0)
	s_barrier
	s_setprio 1
	s_waitcnt lgkmcnt(0)
	v_mfma_f32_16x16x32_bf16 v[60:63], v[152:155], v[192:195], v[60:63]
	v_mfma_f32_16x16x32_bf16 v[56:59], v[160:163], v[192:195], v[56:59]
	v_mfma_f32_16x16x32_bf16 v[44:47], v[152:155], v[200:203], v[44:47]
	v_mfma_f32_16x16x32_bf16 v[40:43], v[160:163], v[200:203], v[40:43]
	v_mfma_f32_16x16x32_bf16 v[28:31], v[152:155], v[208:211], v[28:31]
	v_mfma_f32_16x16x32_bf16 v[24:27], v[160:163], v[208:211], v[24:27]
	v_mfma_f32_16x16x32_bf16 v[12:15], v[152:155], v[216:219], v[12:15]
	v_mfma_f32_16x16x32_bf16 v[8:11], v[160:163], v[216:219], v[8:11]
	v_mfma_f32_16x16x32_bf16 v[60:63], v[156:159], v[196:199], v[60:63]
	v_mfma_f32_16x16x32_bf16 v[56:59], v[164:167], v[196:199], v[56:59]
	v_mfma_f32_16x16x32_bf16 v[44:47], v[156:159], v[204:207], v[44:47]
	v_mfma_f32_16x16x32_bf16 v[40:43], v[164:167], v[204:207], v[40:43]
	v_mfma_f32_16x16x32_bf16 v[28:31], v[156:159], v[212:215], v[28:31]
	v_mfma_f32_16x16x32_bf16 v[24:27], v[164:167], v[212:215], v[24:27]
	v_mfma_f32_16x16x32_bf16 v[12:15], v[156:159], v[220:223], v[12:15]
	v_mfma_f32_16x16x32_bf16 v[8:11], v[164:167], v[220:223], v[8:11]
	v_mfma_f32_16x16x32_bf16 v[52:55], v[168:171], v[192:195], v[52:55]
	v_mfma_f32_16x16x32_bf16 v[48:51], v[184:187], v[192:195], v[48:51]
	v_mfma_f32_16x16x32_bf16 v[36:39], v[168:171], v[200:203], v[36:39]
	v_mfma_f32_16x16x32_bf16 v[32:35], v[184:187], v[200:203], v[32:35]
	v_mfma_f32_16x16x32_bf16 v[20:23], v[168:171], v[208:211], v[20:23]
	v_mfma_f32_16x16x32_bf16 v[16:19], v[184:187], v[208:211], v[16:19]
	v_mfma_f32_16x16x32_bf16 v[4:7], v[168:171], v[216:219], v[4:7]
	v_mfma_f32_16x16x32_bf16 v[0:3], v[184:187], v[216:219], v[0:3]
	v_mfma_f32_16x16x32_bf16 v[52:55], v[172:175], v[196:199], v[52:55]
	v_mfma_f32_16x16x32_bf16 v[48:51], v[188:191], v[196:199], v[48:51]
	v_mfma_f32_16x16x32_bf16 v[36:39], v[172:175], v[204:207], v[36:39]
	v_mfma_f32_16x16x32_bf16 v[32:35], v[188:191], v[204:207], v[32:35]
	v_mfma_f32_16x16x32_bf16 v[20:23], v[172:175], v[212:215], v[20:23]
	v_mfma_f32_16x16x32_bf16 v[16:19], v[188:191], v[212:215], v[16:19]
	v_mfma_f32_16x16x32_bf16 v[4:7], v[172:175], v[220:223], v[4:7]
	v_mfma_f32_16x16x32_bf16 v[0:3], v[188:191], v[220:223], v[0:3]
	s_setprio 0
	s_barrier
	s_add_u32 s34, s34, 0x100
	s_addc_u32 s52, s52, 0
	s_cmp_ge_i32 s53, s47
	s_mov_b64 s[24:25], s[36:37]
	s_mov_b32 s38, s53
	s_cbranch_scc0 .LBB0_663

; #define PG8_STAGE(bufoff, gbase, voff) do { _Pragma("unroll") for (int _i = 0; _i < 2; ++_i) \
;         __builtin_amdgcn_global_load_lds((const unsigned*)((const char*)(gbase) + (voff)[_i]), (LAS unsigned*)(lds + (bufoff) + ldsw + _i * 8192), 16, 0, 0); } while (0)
; #define PG8_LDA(dst, b, h) do { _Pragma("unroll") for (int m = 0; m < 4; ++m) _Pragma("unroll") for (int k = 0; k < 2; ++k) dst[m][k] = *(const LAS bf16x8*)(lds + PG8_SA(b, h) + aoff + m * 2048 + k * 1024); } while (0)
; #define PG8_LDB(dst, b, h) do { _Pragma("unroll") for (int n = 0; n < 2; ++n) _Pragma("unroll") for (int k = 0; k < 2; ++k) dst[n][k] = *(const LAS bf16x8*)(lds + PG8_SB(b, h) + boff + n * 2048 + k * 1024); } while (0)
; #define PG8_MMA(ai, bj, At, Bt) do { __builtin_amdgcn_s_setprio(1); _Pragma("unroll") for (int m = 0; m < 4; ++m) _Pragma("unroll") for (int n = 0; n < 2; ++n) _Pragma("unroll") for (int k = 0; k < 2; ++k) \
;         acc[ai][bj][m][n] = __builtin_amdgcn_mfma_f32_16x16x32_bf16(Bt[n][k], At[m][k], acc[ai][bj][m][n], 0, 0, 0); __builtin_amdgcn_s_setprio(0); } while (0)
; #define PG8_WAIT_V(n) asm volatile("s_waitcnt vmcnt(" #n ")" ::: "memory")
; #define PG8_WAIT_L(n) asm volatile("s_waitcnt lgkmcnt(" #n ")" ::: "memory")
; #define PG8_BAR __builtin_amdgcn_s_barrier()
; #define PG8_SCHED __builtin_amdgcn_sched_barrier(0)
; template <class Epi, bool ALIGN_EPI = PG8_ALIGN>
; __device__ __forceinline__ void gemm_phase(LAS unsigned char* lds, const Gemm g, const StaticOrder& S, const Epi& E) {
;     ...
;             const bool last = (t == nt - 2);
;             const char* a1 = cA + (size_t)(t + 1) * kstep;
;             const char* a2 = last ? nA : cA + (size_t)(t + 2) * kstep; const char* b2 = last ? nB : cB + (size_t)(t + 2) * kstep;
;             const char* a3 = a2 + kstep; const char* b3 = b2 + kstep;
;             PG8_LDB(B0, 0, 0); PG8_LDB(B1, 0, 1); PG8_SCHED; PG8_LDA(At, 0, 0); PG8_STAGE(PG8_SA(1, 1), a1 + hstepA, voffA);
;             PG8_WAIT_V(8); PG8_WAIT_L(0); PG8_BAR; PG8_MMA(0, 0, At, B0); PG8_MMA(0, 1, At, B1); PG8_BAR; PG8_SCHED;
;             PG8_LDA(At, 0, 1); PG8_STAGE(PG8_SB(0, 0), b2, voffB); PG8_STAGE(PG8_SB(0, 1), b2 + hstepB, voffB); PG8_STAGE(PG8_SA(0, 0), a2, voffA);
;             PG8_WAIT_V(8); PG8_WAIT_L(0); PG8_BAR; PG8_MMA(1, 0, At, B0); PG8_MMA(1, 1, At, B1); PG8_BAR; PG8_SCHED;
.LBB0_901:
	s_add_i32 s53, s40, 2
	s_add_u32 s20, s4, 0xfff80080
	s_addc_u32 s21, s5, -1
	s_add_i32 s22, 16, 0x10000
	s_cmp_eq_u32 s47, s40
	s_cselect_b32 s41, s25, s21
	s_cselect_b32 s40, s52, s20
	s_cselect_b32 s21, s37, s43
	s_cselect_b32 s20, s36, s42
	s_add_i32 s23, 16, 0x14000
	v_add_u32_e32 v154, s22, v139
	v_add_u32_e32 v170, s23, v139
	ds_read_b128 v[142:145], v154
	ds_read_b128 v[146:149], v154 offset:1024
	ds_read_b128 v[150:153], v154 offset:2048
	ds_read_b128 v[154:157], v154 offset:3072
	ds_read_b128 v[158:161], v170
	ds_read_b128 v[162:165], v170 offset:1024
	ds_read_b128 v[166:169], v170 offset:2048
	ds_read_b128 v[170:173], v170 offset:3072
	v_lshl_add_u64 v[174:175], s[4:5], 0, v[134:135]
	s_add_i32 m0, s29, 0xc000
	ds_read_b128 v[184:187], v141
	ds_read_b128 v[188:191], v141 offset:1024
	ds_read_b128 v[192:195], v141 offset:2048
	ds_read_b128 v[196:199], v141 offset:3072
	ds_read_b128 v[200:203], v141 offset:4096
	ds_read_b128 v[204:207], v141 offset:5120
	ds_read_b128 v[208:211], v141 offset:6144
	ds_read_b128 v[212:215], v141 offset:7168
	global_load_lds_dwordx4 v[174:175], off
	v_lshl_add_u64 v[174:175], s[4:5], 0, v[136:137]
	s_add_i32 m0, s29, 0xe000
	s_nop 0
	global_load_lds_dwordx4 v[174:175], off
	s_waitcnt vmcnt(8)
	s_waitcnt lgkmcnt(0)
	s_barrier
	s_setprio 1
	s_waitcnt lgkmcnt(0)
	v_mfma_f32_16x16x32_bf16 v[120:123], v[142:145], v[184:187], v[120:123]
	v_mfma_f32_16x16x32_bf16 v[124:127], v[150:153], v[184:187], v[124:127]
	v_mfma_f32_16x16x32_bf16 v[108:111], v[142:145], v[192:195], v[108:111]
	v_mfma_f32_16x16x32_bf16 v[104:107], v[150:153], v[192:195], v[104:107]
	v_mfma_f32_16x16x32_bf16 v[92:95], v[142:145], v[200:203], v[92:95]
	v_mfma_f32_16x16x32_bf16 v[88:91], v[150:153], v[200:203], v[88:91]
	v_mfma_f32_16x16x32_bf16 v[76:79], v[142:145], v[208:211], v[76:79]
	v_mfma_f32_16x16x32_bf16 v[72:75], v[150:153], v[208:211], v[72:75]
	v_mfma_f32_16x16x32_bf16 v[120:123], v[146:149], v[188:191], v[120:123]
	v_mfma_f32_16x16x32_bf16 v[124:127], v[154:157], v[188:191], v[124:127]
	v_mfma_f32_16x16x32_bf16 v[108:111], v[146:149], v[196:199], v[108:111]
	v_mfma_f32_16x16x32_bf16 v[104:107], v[154:157], v[196:199], v[104:107]
	v_mfma_f32_16x16x32_bf16 v[92:95], v[146:149], v[204:207], v[92:95]
	v_mfma_f32_16x16x32_bf16 v[88:91], v[154:157], v[204:207], v[88:91]
	v_mfma_f32_16x16x32_bf16 v[76:79], v[146:149], v[212:215], v[76:79]
	v_mfma_f32_16x16x32_bf16 v[72:75], v[154:157], v[212:215], v[72:75]
	v_mfma_f32_16x16x32_bf16 v[116:119], v[158:161], v[184:187], v[116:119]
	v_mfma_f32_16x16x32_bf16 v[112:115], v[166:169], v[184:187], v[112:115]
	v_mfma_f32_16x16x32_bf16 v[100:103], v[158:161], v[192:195], v[100:103]
	v_mfma_f32_16x16x32_bf16 v[96:99], v[166:169], v[192:195], v[96:99]
	v_mfma_f32_16x16x32_bf16 v[84:87], v[158:161], v[200:203], v[84:87]
	v_mfma_f32_16x16x32_bf16 v[80:83], v[166:169], v[200:203], v[80:83]
	v_mfma_f32_16x16x32_bf16 v[68:71], v[158:161], v[208:211], v[68:71]
	v_mfma_f32_16x16x32_bf16 v[64:67], v[166:169], v[208:211], v[64:67]
	v_mfma_f32_16x16x32_bf16 v[116:119], v[162:165], v[188:191], v[116:119]
	v_mfma_f32_16x16x32_bf16 v[112:115], v[170:173], v[188:191], v[112:115]
	v_mfma_f32_16x16x32_bf16 v[100:103], v[162:165], v[196:199], v[100:103]
	v_mfma_f32_16x16x32_bf16 v[96:99], v[170:173], v[196:199], v[96:99]
	v_mfma_f32_16x16x32_bf16 v[84:87], v[162:165], v[204:207], v[84:87]
	v_mfma_f32_16x16x32_bf16 v[80:83], v[170:173], v[204:207], v[80:83]
	v_mfma_f32_16x16x32_bf16 v[68:71], v[162:165], v[212:215], v[68:71]
	v_mfma_f32_16x16x32_bf16 v[64:67], v[170:173], v[212:215], v[64:67]
	s_setprio 0
	s_barrier
	s_add_i32 s22, s22, s18
	v_lshl_add_u64 v[174:175], s[20:21], 0, v[176:177]
	s_mov_b32 m0, s22
	ds_read_b128 v[184:187], v141 offset:16384
	ds_read_b128 v[188:191], v141 offset:17408
	ds_read_b128 v[192:195], v141 offset:18432
	ds_read_b128 v[196:199], v141 offset:19456
	ds_read_b128 v[200:203], v141 offset:20480
	ds_read_b128 v[204:207], v141 offset:21504
	ds_read_b128 v[208:211], v141 offset:22528
	ds_read_b128 v[212:215], v141 offset:23552
	global_load_lds_dwordx4 v[174:175], off
	s_add_i32 m0, s22, 0x2000
	v_lshl_add_u64 v[180:181], s[20:21], 0, v[128:129]
	s_add_u32 s20, s20, s8
	s_addc_u32 s21, s21, s9
	s_add_i32 s22, s23, s18
	global_load_lds_dwordx4 v[180:181], off
	v_lshl_add_u64 v[182:183], s[20:21], 0, v[176:177]
	s_mov_b32 m0, s22
	v_lshl_add_u64 v[216:217], s[20:21], 0, v[128:129]
	global_load_lds_dwordx4 v[182:183], off
	s_add_i32 m0, s22, 0x2000
	v_lshl_add_u64 v[218:219], s[40:41], 0, v[132:133]
	global_load_lds_dwordx4 v[216:217], off
	s_mov_b32 m0, s29
	v_lshl_add_u64 v[220:221], s[40:41], 0, v[130:131]
	global_load_lds_dwordx4 v[218:219], off
	s_mov_b32 m0, s30
	s_nop 0
	global_load_lds_dwordx4 v[220:221], off
	s_waitcnt vmcnt(8)
	s_waitcnt lgkmcnt(0)
	s_barrier
; #define PG8_STAGE(bufoff, gbase, voff) do { _Pragma("unroll") for (int _i = 0; _i < 2; ++_i) \
;         __builtin_amdgcn_global_load_lds((const unsigned*)((const char*)(gbase) + (voff)[_i]), (LAS unsigned*)(lds + (bufoff) + ldsw + _i * 8192), 16, 0, 0); } while (0)
; #define PG8_LDA(dst, b, h) do { _Pragma("unroll") for (int m = 0; m < 4; ++m) _Pragma("unroll") for (int k = 0; k < 2; ++k) dst[m][k] = *(const LAS bf16x8*)(lds + PG8_SA(b, h) + aoff + m * 2048 + k * 1024); } while (0)
; #define PG8_LDB(dst, b, h) do { _Pragma("unroll") for (int n = 0; n < 2; ++n) _Pragma("unroll") for (int k = 0; k < 2; ++k) dst[n][k] = *(const LAS bf16x8*)(lds + PG8_SB(b, h) + boff + n * 2048 + k * 1024); } while (0)
; #define PG8_MMA(ai, bj, At, Bt) do { __builtin_amdgcn_s_setprio(1); _Pragma("unroll") for (int m = 0; m < 4; ++m) _Pragma("unroll") for (int n = 0; n < 2; ++n) _Pragma("unroll") for (int k = 0; k < 2; ++k) \
;         acc[ai][bj][m][n] = __builtin_amdgcn_mfma_f32_16x16x32_bf16(Bt[n][k], At[m][k], acc[ai][bj][m][n], 0, 0, 0); __builtin_amdgcn_s_setprio(0); } while (0)
; #define PG8_WAIT_V(n) asm volatile("s_waitcnt vmcnt(" #n ")" ::: "memory")
; #define PG8_WAIT_L(n) asm volatile("s_waitcnt lgkmcnt(" #n ")" ::: "memory")
; #define PG8_BAR __builtin_amdgcn_s_barrier()
; #define PG8_SCHED __builtin_amdgcn_sched_barrier(0)
; template <class Epi, bool ALIGN_EPI = PG8_ALIGN>
; __device__ __forceinline__ void gemm_phase(LAS unsigned char* lds, const Gemm g, const StaticOrder& S, const Epi& E) {
;     ...
;             PG8_WAIT_V(8); PG8_WAIT_L(0); PG8_BAR; PG8_MMA(1, 0, At, B0); PG8_MMA(1, 1, At, B1); PG8_BAR; PG8_SCHED;
;             PG8_LDB(B0, 1, 0); PG8_LDB(B1, 1, 1); PG8_SCHED; PG8_LDA(At, 1, 0); PG8_STAGE(PG8_SA(0, 1), a2 + hstepA, voffA);
;             PG8_WAIT_V(8); PG8_WAIT_L(0); PG8_BAR; PG8_MMA(0, 0, At, B0); PG8_MMA(0, 1, At, B1); PG8_BAR; PG8_SCHED;
	s_setprio 1
	s_waitcnt lgkmcnt(0)
	v_mfma_f32_16x16x32_bf16 v[60:63], v[142:145], v[184:187], v[60:63]
	v_mfma_f32_16x16x32_bf16 v[56:59], v[150:153], v[184:187], v[56:59]
	v_mfma_f32_16x16x32_bf16 v[44:47], v[142:145], v[192:195], v[44:47]
	v_mfma_f32_16x16x32_bf16 v[40:43], v[150:153], v[192:195], v[40:43]
	v_mfma_f32_16x16x32_bf16 v[28:31], v[142:145], v[200:203], v[28:31]
	v_mfma_f32_16x16x32_bf16 v[24:27], v[150:153], v[200:203], v[24:27]
	v_mfma_f32_16x16x32_bf16 v[12:15], v[142:145], v[208:211], v[12:15]
	v_mfma_f32_16x16x32_bf16 v[8:11], v[150:153], v[208:211], v[8:11]
	v_mfma_f32_16x16x32_bf16 v[60:63], v[146:149], v[188:191], v[60:63]
	v_mfma_f32_16x16x32_bf16 v[56:59], v[154:157], v[188:191], v[56:59]
	v_mfma_f32_16x16x32_bf16 v[44:47], v[146:149], v[196:199], v[44:47]
	v_mfma_f32_16x16x32_bf16 v[40:43], v[154:157], v[196:199], v[40:43]
	v_mfma_f32_16x16x32_bf16 v[28:31], v[146:149], v[204:207], v[28:31]
	v_mfma_f32_16x16x32_bf16 v[24:27], v[154:157], v[204:207], v[24:27]
	v_mfma_f32_16x16x32_bf16 v[12:15], v[146:149], v[212:215], v[12:15]
	v_mfma_f32_16x16x32_bf16 v[8:11], v[154:157], v[212:215], v[8:11]
	v_mfma_f32_16x16x32_bf16 v[52:55], v[158:161], v[184:187], v[52:55]
	v_mfma_f32_16x16x32_bf16 v[48:51], v[166:169], v[184:187], v[48:51]
	v_mfma_f32_16x16x32_bf16 v[36:39], v[158:161], v[192:195], v[36:39]
	v_mfma_f32_16x16x32_bf16 v[32:35], v[166:169], v[192:195], v[32:35]
	v_mfma_f32_16x16x32_bf16 v[20:23], v[158:161], v[200:203], v[20:23]
	v_mfma_f32_16x16x32_bf16 v[16:19], v[166:169], v[200:203], v[16:19]
	v_mfma_f32_16x16x32_bf16 v[4:7], v[158:161], v[208:211], v[4:7]
	v_mfma_f32_16x16x32_bf16 v[0:3], v[166:169], v[208:211], v[0:3]
	v_mfma_f32_16x16x32_bf16 v[52:55], v[162:165], v[188:191], v[52:55]
	v_mfma_f32_16x16x32_bf16 v[48:51], v[170:173], v[188:191], v[48:51]
	v_mfma_f32_16x16x32_bf16 v[36:39], v[162:165], v[196:199], v[36:39]
	v_mfma_f32_16x16x32_bf16 v[32:35], v[170:173], v[196:199], v[32:35]
	v_mfma_f32_16x16x32_bf16 v[20:23], v[162:165], v[204:207], v[20:23]
	v_mfma_f32_16x16x32_bf16 v[16:19], v[170:173], v[204:207], v[16:19]
	v_mfma_f32_16x16x32_bf16 v[4:7], v[162:165], v[212:215], v[4:7]
	v_mfma_f32_16x16x32_bf16 v[0:3], v[170:173], v[212:215], v[0:3]
	s_setprio 0
	s_barrier
	s_add_i32 s22, 16, 0x18000
	s_add_i32 s23, 16, 0x1c000
	v_add_u32_e32 v154, s22, v139
	v_add_u32_e32 v170, s23, v139
	ds_read_b128 v[142:145], v154
	ds_read_b128 v[146:149], v154 offset:1024
	ds_read_b128 v[150:153], v154 offset:2048
	ds_read_b128 v[154:157], v154 offset:3072
	ds_read_b128 v[158:161], v170
	ds_read_b128 v[162:165], v170 offset:1024
	ds_read_b128 v[166:169], v170 offset:2048
	ds_read_b128 v[170:173], v170 offset:3072
	s_add_u32 s20, s40, 0x80000
	s_addc_u32 s21, s41, 0
	s_mov_b32 m0, s31
	v_lshl_add_u64 v[222:223], s[20:21], 0, v[132:133]
	ds_read_b128 v[184:187], v141 offset:32768
	ds_read_b128 v[188:191], v141 offset:33792
	ds_read_b128 v[192:195], v141 offset:34816
	ds_read_b128 v[196:199], v141 offset:35840
	ds_read_b128 v[200:203], v141 offset:36864
	ds_read_b128 v[204:207], v141 offset:37888
	ds_read_b128 v[208:211], v141 offset:38912
	ds_read_b128 v[212:215], v141 offset:39936
	global_load_lds_dwordx4 v[222:223], off
	v_lshl_add_u64 v[222:223], s[20:21], 0, v[130:131]
	s_mov_b32 m0, s44
	s_nop 0
	global_load_lds_dwordx4 v[222:223], off
	s_waitcnt vmcnt(8)
	s_waitcnt lgkmcnt(0)
	s_barrier
	s_setprio 1
	s_waitcnt lgkmcnt(0)
	v_mfma_f32_16x16x32_bf16 v[120:123], v[142:145], v[184:187], v[120:123]
	v_mfma_f32_16x16x32_bf16 v[124:127], v[150:153], v[184:187], v[124:127]
	v_mfma_f32_16x16x32_bf16 v[108:111], v[142:145], v[192:195], v[108:111]
	v_mfma_f32_16x16x32_bf16 v[104:107], v[150:153], v[192:195], v[104:107]
	v_mfma_f32_16x16x32_bf16 v[92:95], v[142:145], v[200:203], v[92:95]
	v_mfma_f32_16x16x32_bf16 v[88:91], v[150:153], v[200:203], v[88:91]
	v_mfma_f32_16x16x32_bf16 v[76:79], v[142:145], v[208:211], v[76:79]
	v_mfma_f32_16x16x32_bf16 v[72:75], v[150:153], v[208:211], v[72:75]
	v_mfma_f32_16x16x32_bf16 v[120:123], v[146:149], v[188:191], v[120:123]
	v_mfma_f32_16x16x32_bf16 v[124:127], v[154:157], v[188:191], v[124:127]
	v_mfma_f32_16x16x32_bf16 v[108:111], v[146:149], v[196:199], v[108:111]
	v_mfma_f32_16x16x32_bf16 v[104:107], v[154:157], v[196:199], v[104:107]
	v_mfma_f32_16x16x32_bf16 v[92:95], v[146:149], v[204:207], v[92:95]
	v_mfma_f32_16x16x32_bf16 v[88:91], v[154:157], v[204:207], v[88:91]
	v_mfma_f32_16x16x32_bf16 v[76:79], v[146:149], v[212:215], v[76:79]
	v_mfma_f32_16x16x32_bf16 v[72:75], v[154:157], v[212:215], v[72:75]
	v_mfma_f32_16x16x32_bf16 v[116:119], v[158:161], v[184:187], v[116:119]
	v_mfma_f32_16x16x32_bf16 v[112:115], v[166:169], v[184:187], v[112:115]
	v_mfma_f32_16x16x32_bf16 v[100:103], v[158:161], v[192:195], v[100:103]
	v_mfma_f32_16x16x32_bf16 v[96:99], v[166:169], v[192:195], v[96:99]
	v_mfma_f32_16x16x32_bf16 v[84:87], v[158:161], v[200:203], v[84:87]
	v_mfma_f32_16x16x32_bf16 v[80:83], v[166:169], v[200:203], v[80:83]
	v_mfma_f32_16x16x32_bf16 v[68:71], v[158:161], v[208:211], v[68:71]
	v_mfma_f32_16x16x32_bf16 v[64:67], v[166:169], v[208:211], v[64:67]
	v_mfma_f32_16x16x32_bf16 v[116:119], v[162:165], v[188:191], v[116:119]
	v_mfma_f32_16x16x32_bf16 v[112:115], v[170:173], v[188:191], v[112:115]
	v_mfma_f32_16x16x32_bf16 v[100:103], v[162:165], v[196:199], v[100:103]
	v_mfma_f32_16x16x32_bf16 v[96:99], v[170:173], v[196:199], v[96:99]
	v_mfma_f32_16x16x32_bf16 v[84:87], v[162:165], v[204:207], v[84:87]
	v_mfma_f32_16x16x32_bf16 v[80:83], v[170:173], v[204:207], v[80:83]
	v_mfma_f32_16x16x32_bf16 v[68:71], v[162:165], v[212:215], v[68:71]
	v_mfma_f32_16x16x32_bf16 v[64:67], v[170:173], v[212:215], v[64:67]
	s_setprio 0
	s_barrier
; #define PG8_STAGE(bufoff, gbase, voff) do { _Pragma("unroll") for (int _i = 0; _i < 2; ++_i) \
;         __builtin_amdgcn_global_load_lds((const unsigned*)((const char*)(gbase) + (voff)[_i]), (LAS unsigned*)(lds + (bufoff) + ldsw + _i * 8192), 16, 0, 0); } while (0)
; #define PG8_LDA(dst, b, h) do { _Pragma("unroll") for (int m = 0; m < 4; ++m) _Pragma("unroll") for (int k = 0; k < 2; ++k) dst[m][k] = *(const LAS bf16x8*)(lds + PG8_SA(b, h) + aoff + m * 2048 + k * 1024); } while (0)
; #define PG8_MMA(ai, bj, At, Bt) do { __builtin_amdgcn_s_setprio(1); _Pragma("unroll") for (int m = 0; m < 4; ++m) _Pragma("unroll") for (int n = 0; n < 2; ++n) _Pragma("unroll") for (int k = 0; k < 2; ++k) \
;         acc[ai][bj][m][n] = __builtin_amdgcn_mfma_f32_16x16x32_bf16(Bt[n][k], At[m][k], acc[ai][bj][m][n], 0, 0, 0); __builtin_amdgcn_s_setprio(0); } while (0)
; #define PG8_WAIT_V(n) asm volatile("s_waitcnt vmcnt(" #n ")" ::: "memory")
; #define PG8_WAIT_L(n) asm volatile("s_waitcnt lgkmcnt(" #n ")" ::: "memory")
; #define PG8_BAR __builtin_amdgcn_s_barrier()
; #define PG8_SCHED __builtin_amdgcn_sched_barrier(0)
; template <class Epi, bool ALIGN_EPI = PG8_ALIGN>
; __device__ __forceinline__ void gemm_phase(LAS unsigned char* lds, const Gemm g, const StaticOrder& S, const Epi& E) {
;     ...
;             PG8_LDA(At, 1, 1); PG8_STAGE(PG8_SB(1, 0), b3, voffB); PG8_STAGE(PG8_SB(1, 1), b3 + hstepB, voffB); PG8_STAGE(PG8_SA(1, 0), a3, voffA);
;             PG8_WAIT_V(8); PG8_WAIT_L(0); PG8_BAR; PG8_MMA(1, 0, At, B0); PG8_MMA(1, 1, At, B1); PG8_BAR; PG8_SCHED;
;         }
	s_add_i32 s20, s22, s18
	v_lshl_add_u64 v[174:175], v[174:175], 0, s[0:1]
	s_mov_b32 m0, s20
	ds_read_b128 v[184:187], v141 offset:49152
	ds_read_b128 v[188:191], v141 offset:50176
	ds_read_b128 v[192:195], v141 offset:51200
	ds_read_b128 v[196:199], v141 offset:52224
	ds_read_b128 v[200:203], v141 offset:53248
	ds_read_b128 v[204:207], v141 offset:54272
	ds_read_b128 v[208:211], v141 offset:55296
	ds_read_b128 v[212:215], v141 offset:56320
	global_load_lds_dwordx4 v[174:175], off
	v_lshl_add_u64 v[174:175], v[180:181], 0, s[0:1]
	s_add_i32 m0, s20, 0x2000
	s_add_i32 s20, s23, s18
	global_load_lds_dwordx4 v[174:175], off
	v_lshl_add_u64 v[174:175], v[182:183], 0, s[0:1]
	s_mov_b32 m0, s20
	s_nop 0
	global_load_lds_dwordx4 v[174:175], off
	v_lshl_add_u64 v[174:175], v[216:217], 0, s[0:1]
	s_add_i32 m0, s20, 0x2000
	s_nop 0
	global_load_lds_dwordx4 v[174:175], off
	v_lshl_add_u64 v[174:175], v[218:219], 0, s[0:1]
	s_mov_b32 m0, s45
	s_nop 0
	global_load_lds_dwordx4 v[174:175], off
	v_lshl_add_u64 v[174:175], v[220:221], 0, s[0:1]
	s_mov_b32 m0, s46
	s_nop 0
	global_load_lds_dwordx4 v[174:175], off
	s_waitcnt vmcnt(8)
	s_waitcnt lgkmcnt(0)
	s_barrier
	s_setprio 1
	s_waitcnt lgkmcnt(0)
	v_mfma_f32_16x16x32_bf16 v[60:63], v[142:145], v[184:187], v[60:63]
	v_mfma_f32_16x16x32_bf16 v[56:59], v[150:153], v[184:187], v[56:59]
	v_mfma_f32_16x16x32_bf16 v[44:47], v[142:145], v[192:195], v[44:47]
	v_mfma_f32_16x16x32_bf16 v[40:43], v[150:153], v[192:195], v[40:43]
	v_mfma_f32_16x16x32_bf16 v[28:31], v[142:145], v[200:203], v[28:31]
	v_mfma_f32_16x16x32_bf16 v[24:27], v[150:153], v[200:203], v[24:27]
	v_mfma_f32_16x16x32_bf16 v[12:15], v[142:145], v[208:211], v[12:15]
	v_mfma_f32_16x16x32_bf16 v[8:11], v[150:153], v[208:211], v[8:11]
	v_mfma_f32_16x16x32_bf16 v[60:63], v[146:149], v[188:191], v[60:63]
	v_mfma_f32_16x16x32_bf16 v[56:59], v[154:157], v[188:191], v[56:59]
	v_mfma_f32_16x16x32_bf16 v[44:47], v[146:149], v[196:199], v[44:47]
	v_mfma_f32_16x16x32_bf16 v[40:43], v[154:157], v[196:199], v[40:43]
	v_mfma_f32_16x16x32_bf16 v[28:31], v[146:149], v[204:207], v[28:31]
	v_mfma_f32_16x16x32_bf16 v[24:27], v[154:157], v[204:207], v[24:27]
	v_mfma_f32_16x16x32_bf16 v[12:15], v[146:149], v[212:215], v[12:15]
	v_mfma_f32_16x16x32_bf16 v[8:11], v[154:157], v[212:215], v[8:11]
	v_mfma_f32_16x16x32_bf16 v[52:55], v[158:161], v[184:187], v[52:55]
	v_mfma_f32_16x16x32_bf16 v[48:51], v[166:169], v[184:187], v[48:51]
	v_mfma_f32_16x16x32_bf16 v[36:39], v[158:161], v[192:195], v[36:39]
	v_mfma_f32_16x16x32_bf16 v[32:35], v[166:169], v[192:195], v[32:35]
	v_mfma_f32_16x16x32_bf16 v[20:23], v[158:161], v[200:203], v[20:23]
	v_mfma_f32_16x16x32_bf16 v[16:19], v[166:169], v[200:203], v[16:19]
	v_mfma_f32_16x16x32_bf16 v[4:7], v[158:161], v[208:211], v[4:7]
	v_mfma_f32_16x16x32_bf16 v[0:3], v[166:169], v[208:211], v[0:3]
	v_mfma_f32_16x16x32_bf16 v[52:55], v[162:165], v[188:191], v[52:55]
	v_mfma_f32_16x16x32_bf16 v[48:51], v[170:173], v[188:191], v[48:51]
	v_mfma_f32_16x16x32_bf16 v[36:39], v[162:165], v[196:199], v[36:39]
	v_mfma_f32_16x16x32_bf16 v[32:35], v[170:173], v[196:199], v[32:35]
	v_mfma_f32_16x16x32_bf16 v[20:23], v[162:165], v[204:207], v[20:23]
	v_mfma_f32_16x16x32_bf16 v[16:19], v[170:173], v[204:207], v[16:19]
	v_mfma_f32_16x16x32_bf16 v[4:7], v[162:165], v[212:215], v[4:7]
	v_mfma_f32_16x16x32_bf16 v[0:3], v[170:173], v[212:215], v[0:3]
	s_setprio 0
	s_barrier
	s_add_u32 s4, s4, 0x100
	s_addc_u32 s5, s5, 0
	s_add_u32 s42, s42, 0x100
	s_addc_u32 s43, s43, 0
	s_cmp_ge_i32 s53, s34
	s_mov_b32 s40, s53
	s_cbranch_scc0 .LBB0_901

; #define PG8_STAGE(bufoff, gbase, voff) do { _Pragma("unroll") for (int _i = 0; _i < 2; ++_i) \
;         __builtin_amdgcn_global_load_lds((const unsigned*)((const char*)(gbase) + (voff)[_i]), (LAS unsigned*)(lds + (bufoff) + ldsw + _i * 8192), 16, 0, 0); } while (0)
; #define PG8_LDA(dst, b, h) do { _Pragma("unroll") for (int m = 0; m < 4; ++m) _Pragma("unroll") for (int k = 0; k < 2; ++k) dst[m][k] = *(const LAS bf16x8*)(lds + PG8_SA(b, h) + aoff + m * 2048 + k * 1024); } while (0)
; #define PG8_LDB(dst, b, h) do { _Pragma("unroll") for (int n = 0; n < 2; ++n) _Pragma("unroll") for (int k = 0; k < 2; ++k) dst[n][k] = *(const LAS bf16x8*)(lds + PG8_SB(b, h) + boff + n * 2048 + k * 1024); } while (0)
; #define PG8_MMA(ai, bj, At, Bt) do { __builtin_amdgcn_s_setprio(1); _Pragma("unroll") for (int m = 0; m < 4; ++m) _Pragma("unroll") for (int n = 0; n < 2; ++n) _Pragma("unroll") for (int k = 0; k < 2; ++k) \
;         acc[ai][bj][m][n] = __builtin_amdgcn_mfma_f32_16x16x32_bf16(Bt[n][k], At[m][k], acc[ai][bj][m][n], 0, 0, 0); __builtin_amdgcn_s_setprio(0); } while (0)
; #define PG8_WAIT_V(n) asm volatile("s_waitcnt vmcnt(" #n ")" ::: "memory")
; #define PG8_WAIT_L(n) asm volatile("s_waitcnt lgkmcnt(" #n ")" ::: "memory")
; #define PG8_BAR __builtin_amdgcn_s_barrier()
; #define PG8_SCHED __builtin_amdgcn_sched_barrier(0)
; template <class Epi, bool ALIGN_EPI = PG8_ALIGN>
; __device__ __forceinline__ void gemm_phase(LAS unsigned char* lds, const Gemm g, const StaticOrder& S, const Epi& E) {
;     ...
;             const bool last = (t == nt - 2);
;             const char* a1 = cA + (size_t)(t + 1) * kstep;
;             const char* a2 = last ? nA : cA + (size_t)(t + 2) * kstep; const char* b2 = last ? nB : cB + (size_t)(t + 2) * kstep;
;             const char* a3 = a2 + kstep; const char* b3 = b2 + kstep;
;             PG8_LDB(B0, 0, 0); PG8_LDB(B1, 0, 1); PG8_SCHED; PG8_LDA(At, 0, 0); PG8_STAGE(PG8_SA(1, 1), a1 + hstepA, voffA);
;             PG8_WAIT_V(8); PG8_WAIT_L(0); PG8_BAR; PG8_MMA(0, 0, At, B0); PG8_MMA(0, 1, At, B1); PG8_BAR; PG8_SCHED;
;             PG8_LDA(At, 0, 1); PG8_STAGE(PG8_SB(0, 0), b2, voffB); PG8_STAGE(PG8_SB(0, 1), b2 + hstepB, voffB); PG8_STAGE(PG8_SA(0, 0), a2, voffA);
;             PG8_WAIT_V(8); PG8_WAIT_L(0); PG8_BAR; PG8_MMA(1, 0, At, B0); PG8_MMA(1, 1, At, B1); PG8_BAR; PG8_SCHED;
.LBB0_1028:
	s_add_i32 s31, s24, 2
	s_add_u32 s20, s2, 0xfff80080
	s_addc_u32 s21, s3, -1
	s_add_i32 s22, 16, 0x10000
	s_cmp_eq_u32 s53, s24
	s_cselect_b32 s25, s17, s21
	s_cselect_b32 s24, s27, s20
	s_cselect_b32 s21, s39, s30
	s_cselect_b32 s20, s38, s29
	s_add_i32 s23, 16, 0x14000
	v_add_u32_e32 v140, s22, v220
	v_add_u32_e32 v156, s23, v220
	ds_read_b128 v[128:131], v140
	ds_read_b128 v[132:135], v140 offset:1024
	ds_read_b128 v[136:139], v140 offset:2048
	ds_read_b128 v[140:143], v140 offset:3072
	ds_read_b128 v[144:147], v156
	ds_read_b128 v[148:151], v156 offset:1024
	ds_read_b128 v[152:155], v156 offset:2048
	ds_read_b128 v[156:159], v156 offset:3072
	v_lshl_add_u64 v[180:181], s[2:3], 0, v[192:193]
	s_add_i32 m0, s47, 0xc000
	ds_read_b128 v[160:163], v223
	ds_read_b128 v[164:167], v223 offset:1024
	ds_read_b128 v[168:171], v223 offset:2048
	ds_read_b128 v[172:175], v223 offset:3072
	ds_read_b128 v[196:199], v223 offset:4096
	ds_read_b128 v[200:203], v223 offset:5120
	ds_read_b128 v[204:207], v223 offset:6144
	ds_read_b128 v[208:211], v223 offset:7168
	global_load_lds_dwordx4 v[180:181], off
	v_lshl_add_u64 v[180:181], s[2:3], 0, v[194:195]
	s_add_i32 m0, s47, 0xe000
	s_nop 0
	global_load_lds_dwordx4 v[180:181], off
	s_waitcnt vmcnt(8)
	s_waitcnt lgkmcnt(0)
	s_barrier
	s_setprio 1
	s_waitcnt lgkmcnt(0)
	v_mfma_f32_16x16x32_bf16 v[124:127], v[128:131], v[160:163], v[124:127]
	v_mfma_f32_16x16x32_bf16 v[116:119], v[136:139], v[160:163], v[116:119]
	v_mfma_f32_16x16x32_bf16 v[108:111], v[128:131], v[168:171], v[108:111]
	v_mfma_f32_16x16x32_bf16 v[100:103], v[136:139], v[168:171], v[100:103]
	v_mfma_f32_16x16x32_bf16 v[92:95], v[128:131], v[196:199], v[92:95]
	v_mfma_f32_16x16x32_bf16 v[84:87], v[136:139], v[196:199], v[84:87]
	v_mfma_f32_16x16x32_bf16 v[76:79], v[128:131], v[204:207], v[76:79]
	v_mfma_f32_16x16x32_bf16 v[68:71], v[136:139], v[204:207], v[68:71]
	v_mfma_f32_16x16x32_bf16 v[124:127], v[132:135], v[164:167], v[124:127]
	v_mfma_f32_16x16x32_bf16 v[116:119], v[140:143], v[164:167], v[116:119]
	v_mfma_f32_16x16x32_bf16 v[108:111], v[132:135], v[172:175], v[108:111]
	v_mfma_f32_16x16x32_bf16 v[100:103], v[140:143], v[172:175], v[100:103]
	v_mfma_f32_16x16x32_bf16 v[92:95], v[132:135], v[200:203], v[92:95]
	v_mfma_f32_16x16x32_bf16 v[84:87], v[140:143], v[200:203], v[84:87]
	v_mfma_f32_16x16x32_bf16 v[76:79], v[132:135], v[208:211], v[76:79]
	v_mfma_f32_16x16x32_bf16 v[68:71], v[140:143], v[208:211], v[68:71]
	v_mfma_f32_16x16x32_bf16 v[120:123], v[144:147], v[160:163], v[120:123]
	v_mfma_f32_16x16x32_bf16 v[112:115], v[152:155], v[160:163], v[112:115]
	v_mfma_f32_16x16x32_bf16 v[104:107], v[144:147], v[168:171], v[104:107]
	v_mfma_f32_16x16x32_bf16 v[96:99], v[152:155], v[168:171], v[96:99]
	v_mfma_f32_16x16x32_bf16 v[88:91], v[144:147], v[196:199], v[88:91]
	v_mfma_f32_16x16x32_bf16 v[80:83], v[152:155], v[196:199], v[80:83]
	v_mfma_f32_16x16x32_bf16 v[72:75], v[144:147], v[204:207], v[72:75]
	v_mfma_f32_16x16x32_bf16 v[64:67], v[152:155], v[204:207], v[64:67]
	v_mfma_f32_16x16x32_bf16 v[120:123], v[148:151], v[164:167], v[120:123]
	v_mfma_f32_16x16x32_bf16 v[112:115], v[156:159], v[164:167], v[112:115]
	v_mfma_f32_16x16x32_bf16 v[104:107], v[148:151], v[172:175], v[104:107]
	v_mfma_f32_16x16x32_bf16 v[96:99], v[156:159], v[172:175], v[96:99]
	v_mfma_f32_16x16x32_bf16 v[88:91], v[148:151], v[200:203], v[88:91]
	v_mfma_f32_16x16x32_bf16 v[80:83], v[156:159], v[200:203], v[80:83]
	v_mfma_f32_16x16x32_bf16 v[72:75], v[148:151], v[208:211], v[72:75]
	v_mfma_f32_16x16x32_bf16 v[64:67], v[156:159], v[208:211], v[64:67]
	s_setprio 0
	s_barrier
	s_add_i32 s22, s22, s46
	v_lshl_add_u64 v[180:181], s[20:21], 0, v[188:189]
	s_mov_b32 m0, s22
	ds_read_b128 v[160:163], v223 offset:16384
	ds_read_b128 v[164:167], v223 offset:17408
	ds_read_b128 v[168:171], v223 offset:18432
	ds_read_b128 v[172:175], v223 offset:19456
	ds_read_b128 v[196:199], v223 offset:20480
	ds_read_b128 v[200:203], v223 offset:21504
	ds_read_b128 v[204:207], v223 offset:22528
	ds_read_b128 v[208:211], v223 offset:23552
	global_load_lds_dwordx4 v[180:181], off
	s_add_i32 m0, s22, 0x2000
	v_lshl_add_u64 v[182:183], s[20:21], 0, v[184:185]
	s_add_u32 s20, s20, s4
	s_addc_u32 s21, s21, s5
	s_add_i32 s22, s23, s46
	global_load_lds_dwordx4 v[182:183], off
	v_lshl_add_u64 v[212:213], s[20:21], 0, v[188:189]
	s_mov_b32 m0, s22
	v_lshl_add_u64 v[214:215], s[20:21], 0, v[184:185]
	global_load_lds_dwordx4 v[212:213], off
	s_add_i32 m0, s22, 0x2000
	v_lshl_add_u64 v[216:217], s[24:25], 0, v[190:191]
	global_load_lds_dwordx4 v[214:215], off
	s_mov_b32 m0, s47
	v_lshl_add_u64 v[218:219], s[24:25], 0, v[186:187]
	global_load_lds_dwordx4 v[216:217], off
	s_mov_b32 m0, s48
	s_nop 0
	global_load_lds_dwordx4 v[218:219], off
	s_waitcnt vmcnt(8)
	s_waitcnt lgkmcnt(0)
	s_barrier
; #define PG8_STAGE(bufoff, gbase, voff) do { _Pragma("unroll") for (int _i = 0; _i < 2; ++_i) \
;         __builtin_amdgcn_global_load_lds((const unsigned*)((const char*)(gbase) + (voff)[_i]), (LAS unsigned*)(lds + (bufoff) + ldsw + _i * 8192), 16, 0, 0); } while (0)
; #define PG8_LDA(dst, b, h) do { _Pragma("unroll") for (int m = 0; m < 4; ++m) _Pragma("unroll") for (int k = 0; k < 2; ++k) dst[m][k] = *(const LAS bf16x8*)(lds + PG8_SA(b, h) + aoff + m * 2048 + k * 1024); } while (0)
; #define PG8_LDB(dst, b, h) do { _Pragma("unroll") for (int n = 0; n < 2; ++n) _Pragma("unroll") for (int k = 0; k < 2; ++k) dst[n][k] = *(const LAS bf16x8*)(lds + PG8_SB(b, h) + boff + n * 2048 + k * 1024); } while (0)
; #define PG8_MMA(ai, bj, At, Bt) do { __builtin_amdgcn_s_setprio(1); _Pragma("unroll") for (int m = 0; m < 4; ++m) _Pragma("unroll") for (int n = 0; n < 2; ++n) _Pragma("unroll") for (int k = 0; k < 2; ++k) \
;         acc[ai][bj][m][n] = __builtin_amdgcn_mfma_f32_16x16x32_bf16(Bt[n][k], At[m][k], acc[ai][bj][m][n], 0, 0, 0); __builtin_amdgcn_s_setprio(0); } while (0)
; #define PG8_WAIT_V(n) asm volatile("s_waitcnt vmcnt(" #n ")" ::: "memory")
; #define PG8_WAIT_L(n) asm volatile("s_waitcnt lgkmcnt(" #n ")" ::: "memory")
; #define PG8_BAR __builtin_amdgcn_s_barrier()
; #define PG8_SCHED __builtin_amdgcn_sched_barrier(0)
; template <class Epi, bool ALIGN_EPI = PG8_ALIGN>
; __device__ __forceinline__ void gemm_phase(LAS unsigned char* lds, const Gemm g, const StaticOrder& S, const Epi& E) {
;     ...
;             PG8_WAIT_V(8); PG8_WAIT_L(0); PG8_BAR; PG8_MMA(1, 0, At, B0); PG8_MMA(1, 1, At, B1); PG8_BAR; PG8_SCHED;
;             PG8_LDB(B0, 1, 0); PG8_LDB(B1, 1, 1); PG8_SCHED; PG8_LDA(At, 1, 0); PG8_STAGE(PG8_SA(0, 1), a2 + hstepA, voffA);
;             PG8_WAIT_V(8); PG8_WAIT_L(0); PG8_BAR; PG8_MMA(0, 0, At, B0); PG8_MMA(0, 1, At, B1); PG8_BAR; PG8_SCHED;
	s_setprio 1
	s_waitcnt lgkmcnt(0)
	v_mfma_f32_16x16x32_bf16 v[60:63], v[128:131], v[160:163], v[60:63]
	v_mfma_f32_16x16x32_bf16 v[52:55], v[136:139], v[160:163], v[52:55]
	v_mfma_f32_16x16x32_bf16 v[44:47], v[128:131], v[168:171], v[44:47]
	v_mfma_f32_16x16x32_bf16 v[36:39], v[136:139], v[168:171], v[36:39]
	v_mfma_f32_16x16x32_bf16 v[28:31], v[128:131], v[196:199], v[28:31]
	v_mfma_f32_16x16x32_bf16 v[20:23], v[136:139], v[196:199], v[20:23]
	v_mfma_f32_16x16x32_bf16 v[12:15], v[128:131], v[204:207], v[12:15]
	v_mfma_f32_16x16x32_bf16 v[4:7], v[136:139], v[204:207], v[4:7]
	v_mfma_f32_16x16x32_bf16 v[60:63], v[132:135], v[164:167], v[60:63]
	v_mfma_f32_16x16x32_bf16 v[52:55], v[140:143], v[164:167], v[52:55]
	v_mfma_f32_16x16x32_bf16 v[44:47], v[132:135], v[172:175], v[44:47]
	v_mfma_f32_16x16x32_bf16 v[36:39], v[140:143], v[172:175], v[36:39]
	v_mfma_f32_16x16x32_bf16 v[28:31], v[132:135], v[200:203], v[28:31]
	v_mfma_f32_16x16x32_bf16 v[20:23], v[140:143], v[200:203], v[20:23]
	v_mfma_f32_16x16x32_bf16 v[12:15], v[132:135], v[208:211], v[12:15]
	v_mfma_f32_16x16x32_bf16 v[4:7], v[140:143], v[208:211], v[4:7]
	v_mfma_f32_16x16x32_bf16 v[56:59], v[144:147], v[160:163], v[56:59]
	v_mfma_f32_16x16x32_bf16 v[48:51], v[152:155], v[160:163], v[48:51]
	v_mfma_f32_16x16x32_bf16 v[40:43], v[144:147], v[168:171], v[40:43]
	v_mfma_f32_16x16x32_bf16 v[32:35], v[152:155], v[168:171], v[32:35]
	v_mfma_f32_16x16x32_bf16 v[24:27], v[144:147], v[196:199], v[24:27]
	v_mfma_f32_16x16x32_bf16 v[16:19], v[152:155], v[196:199], v[16:19]
	v_mfma_f32_16x16x32_bf16 v[8:11], v[144:147], v[204:207], v[8:11]
	v_mfma_f32_16x16x32_bf16 v[0:3], v[152:155], v[204:207], v[0:3]
	v_mfma_f32_16x16x32_bf16 v[56:59], v[148:151], v[164:167], v[56:59]
	v_mfma_f32_16x16x32_bf16 v[48:51], v[156:159], v[164:167], v[48:51]
	v_mfma_f32_16x16x32_bf16 v[40:43], v[148:151], v[172:175], v[40:43]
	v_mfma_f32_16x16x32_bf16 v[32:35], v[156:159], v[172:175], v[32:35]
	v_mfma_f32_16x16x32_bf16 v[24:27], v[148:151], v[200:203], v[24:27]
	v_mfma_f32_16x16x32_bf16 v[16:19], v[156:159], v[200:203], v[16:19]
	v_mfma_f32_16x16x32_bf16 v[8:11], v[148:151], v[208:211], v[8:11]
	v_mfma_f32_16x16x32_bf16 v[0:3], v[156:159], v[208:211], v[0:3]
	s_setprio 0
	s_barrier
	s_add_i32 s22, 16, 0x18000
	s_add_i32 s23, 16, 0x1c000
	v_add_u32_e32 v140, s22, v220
	v_add_u32_e32 v156, s23, v220
	ds_read_b128 v[128:131], v140
	ds_read_b128 v[132:135], v140 offset:1024
	ds_read_b128 v[136:139], v140 offset:2048
	ds_read_b128 v[140:143], v140 offset:3072
	ds_read_b128 v[144:147], v156
	ds_read_b128 v[148:151], v156 offset:1024
	ds_read_b128 v[152:155], v156 offset:2048
	ds_read_b128 v[156:159], v156 offset:3072
	s_add_u32 s20, s24, 0x80000
	s_addc_u32 s21, s25, 0
	s_mov_b32 m0, s49
	v_lshl_add_u64 v[224:225], s[20:21], 0, v[190:191]
	ds_read_b128 v[160:163], v223 offset:32768
	ds_read_b128 v[164:167], v223 offset:33792
	ds_read_b128 v[168:171], v223 offset:34816
	ds_read_b128 v[172:175], v223 offset:35840
	ds_read_b128 v[196:199], v223 offset:36864
	ds_read_b128 v[200:203], v223 offset:37888
	ds_read_b128 v[204:207], v223 offset:38912
	ds_read_b128 v[208:211], v223 offset:39936
	global_load_lds_dwordx4 v[224:225], off
	v_lshl_add_u64 v[224:225], s[20:21], 0, v[186:187]
	s_mov_b32 m0, s50
	s_nop 0
	global_load_lds_dwordx4 v[224:225], off
	s_waitcnt vmcnt(8)
	s_waitcnt lgkmcnt(0)
	s_barrier
	s_setprio 1
	s_waitcnt lgkmcnt(0)
	v_mfma_f32_16x16x32_bf16 v[124:127], v[128:131], v[160:163], v[124:127]
	v_mfma_f32_16x16x32_bf16 v[116:119], v[136:139], v[160:163], v[116:119]
	v_mfma_f32_16x16x32_bf16 v[108:111], v[128:131], v[168:171], v[108:111]
	v_mfma_f32_16x16x32_bf16 v[100:103], v[136:139], v[168:171], v[100:103]
	v_mfma_f32_16x16x32_bf16 v[92:95], v[128:131], v[196:199], v[92:95]
	v_mfma_f32_16x16x32_bf16 v[84:87], v[136:139], v[196:199], v[84:87]
	v_mfma_f32_16x16x32_bf16 v[76:79], v[128:131], v[204:207], v[76:79]
	v_mfma_f32_16x16x32_bf16 v[68:71], v[136:139], v[204:207], v[68:71]
	v_mfma_f32_16x16x32_bf16 v[124:127], v[132:135], v[164:167], v[124:127]
	v_mfma_f32_16x16x32_bf16 v[116:119], v[140:143], v[164:167], v[116:119]
	v_mfma_f32_16x16x32_bf16 v[108:111], v[132:135], v[172:175], v[108:111]
	v_mfma_f32_16x16x32_bf16 v[100:103], v[140:143], v[172:175], v[100:103]
	v_mfma_f32_16x16x32_bf16 v[92:95], v[132:135], v[200:203], v[92:95]
	v_mfma_f32_16x16x32_bf16 v[84:87], v[140:143], v[200:203], v[84:87]
	v_mfma_f32_16x16x32_bf16 v[76:79], v[132:135], v[208:211], v[76:79]
	v_mfma_f32_16x16x32_bf16 v[68:71], v[140:143], v[208:211], v[68:71]
	v_mfma_f32_16x16x32_bf16 v[120:123], v[144:147], v[160:163], v[120:123]
	v_mfma_f32_16x16x32_bf16 v[112:115], v[152:155], v[160:163], v[112:115]
	v_mfma_f32_16x16x32_bf16 v[104:107], v[144:147], v[168:171], v[104:107]
	v_mfma_f32_16x16x32_bf16 v[96:99], v[152:155], v[168:171], v[96:99]
	v_mfma_f32_16x16x32_bf16 v[88:91], v[144:147], v[196:199], v[88:91]
	v_mfma_f32_16x16x32_bf16 v[80:83], v[152:155], v[196:199], v[80:83]
	v_mfma_f32_16x16x32_bf16 v[72:75], v[144:147], v[204:207], v[72:75]
	v_mfma_f32_16x16x32_bf16 v[64:67], v[152:155], v[204:207], v[64:67]
	v_mfma_f32_16x16x32_bf16 v[120:123], v[148:151], v[164:167], v[120:123]
	v_mfma_f32_16x16x32_bf16 v[112:115], v[156:159], v[164:167], v[112:115]
	v_mfma_f32_16x16x32_bf16 v[104:107], v[148:151], v[172:175], v[104:107]
	v_mfma_f32_16x16x32_bf16 v[96:99], v[156:159], v[172:175], v[96:99]
	v_mfma_f32_16x16x32_bf16 v[88:91], v[148:151], v[200:203], v[88:91]
	v_mfma_f32_16x16x32_bf16 v[80:83], v[156:159], v[200:203], v[80:83]
	v_mfma_f32_16x16x32_bf16 v[72:75], v[148:151], v[208:211], v[72:75]
	v_mfma_f32_16x16x32_bf16 v[64:67], v[156:159], v[208:211], v[64:67]
	s_setprio 0
	s_barrier
; #define PG8_STAGE(bufoff, gbase, voff) do { _Pragma("unroll") for (int _i = 0; _i < 2; ++_i) \
;         __builtin_amdgcn_global_load_lds((const unsigned*)((const char*)(gbase) + (voff)[_i]), (LAS unsigned*)(lds + (bufoff) + ldsw + _i * 8192), 16, 0, 0); } while (0)
; #define PG8_LDA(dst, b, h) do { _Pragma("unroll") for (int m = 0; m < 4; ++m) _Pragma("unroll") for (int k = 0; k < 2; ++k) dst[m][k] = *(const LAS bf16x8*)(lds + PG8_SA(b, h) + aoff + m * 2048 + k * 1024); } while (0)
; #define PG8_MMA(ai, bj, At, Bt) do { __builtin_amdgcn_s_setprio(1); _Pragma("unroll") for (int m = 0; m < 4; ++m) _Pragma("unroll") for (int n = 0; n < 2; ++n) _Pragma("unroll") for (int k = 0; k < 2; ++k) \
;         acc[ai][bj][m][n] = __builtin_amdgcn_mfma_f32_16x16x32_bf16(Bt[n][k], At[m][k], acc[ai][bj][m][n], 0, 0, 0); __builtin_amdgcn_s_setprio(0); } while (0)
; #define PG8_WAIT_V(n) asm volatile("s_waitcnt vmcnt(" #n ")" ::: "memory")
; #define PG8_WAIT_L(n) asm volatile("s_waitcnt lgkmcnt(" #n ")" ::: "memory")
; #define PG8_BAR __builtin_amdgcn_s_barrier()
; #define PG8_SCHED __builtin_amdgcn_sched_barrier(0)
; template <class Epi, bool ALIGN_EPI = PG8_ALIGN>
; __device__ __forceinline__ void gemm_phase(LAS unsigned char* lds, const Gemm g, const StaticOrder& S, const Epi& E) {
;     ...
;             PG8_LDA(At, 1, 1); PG8_STAGE(PG8_SB(1, 0), b3, voffB); PG8_STAGE(PG8_SB(1, 1), b3 + hstepB, voffB); PG8_STAGE(PG8_SA(1, 0), a3, voffA);
;             PG8_WAIT_V(8); PG8_WAIT_L(0); PG8_BAR; PG8_MMA(1, 0, At, B0); PG8_MMA(1, 1, At, B1); PG8_BAR; PG8_SCHED;
;         }
	s_add_i32 s20, s22, s46
	v_lshl_add_u64 v[180:181], v[180:181], 0, s[0:1]
	s_mov_b32 m0, s20
	ds_read_b128 v[160:163], v223 offset:49152
	ds_read_b128 v[164:167], v223 offset:50176
	ds_read_b128 v[168:171], v223 offset:51200
	ds_read_b128 v[172:175], v223 offset:52224
	ds_read_b128 v[196:199], v223 offset:53248
	ds_read_b128 v[200:203], v223 offset:54272
	ds_read_b128 v[204:207], v223 offset:55296
	ds_read_b128 v[208:211], v223 offset:56320
	global_load_lds_dwordx4 v[180:181], off
	v_lshl_add_u64 v[180:181], v[182:183], 0, s[0:1]
	s_add_i32 m0, s20, 0x2000
	s_add_i32 s20, s23, s46
	global_load_lds_dwordx4 v[180:181], off
	v_lshl_add_u64 v[180:181], v[212:213], 0, s[0:1]
	s_mov_b32 m0, s20
	s_nop 0
	global_load_lds_dwordx4 v[180:181], off
	v_lshl_add_u64 v[180:181], v[214:215], 0, s[0:1]
	s_add_i32 m0, s20, 0x2000
	s_nop 0
	global_load_lds_dwordx4 v[180:181], off
	v_lshl_add_u64 v[180:181], v[216:217], 0, s[0:1]
	s_mov_b32 m0, s18
	s_nop 0
	global_load_lds_dwordx4 v[180:181], off
	v_lshl_add_u64 v[180:181], v[218:219], 0, s[0:1]
	s_mov_b32 m0, s51
	s_nop 0
	global_load_lds_dwordx4 v[180:181], off
	s_waitcnt vmcnt(8)
	s_waitcnt lgkmcnt(0)
	s_barrier
	s_setprio 1
	s_waitcnt lgkmcnt(0)
	v_mfma_f32_16x16x32_bf16 v[60:63], v[128:131], v[160:163], v[60:63]
	v_mfma_f32_16x16x32_bf16 v[52:55], v[136:139], v[160:163], v[52:55]
	v_mfma_f32_16x16x32_bf16 v[44:47], v[128:131], v[168:171], v[44:47]
	v_mfma_f32_16x16x32_bf16 v[36:39], v[136:139], v[168:171], v[36:39]
	v_mfma_f32_16x16x32_bf16 v[28:31], v[128:131], v[196:199], v[28:31]
	v_mfma_f32_16x16x32_bf16 v[20:23], v[136:139], v[196:199], v[20:23]
	v_mfma_f32_16x16x32_bf16 v[12:15], v[128:131], v[204:207], v[12:15]
	v_mfma_f32_16x16x32_bf16 v[4:7], v[136:139], v[204:207], v[4:7]
	v_mfma_f32_16x16x32_bf16 v[60:63], v[132:135], v[164:167], v[60:63]
	v_mfma_f32_16x16x32_bf16 v[52:55], v[140:143], v[164:167], v[52:55]
	v_mfma_f32_16x16x32_bf16 v[44:47], v[132:135], v[172:175], v[44:47]
	v_mfma_f32_16x16x32_bf16 v[36:39], v[140:143], v[172:175], v[36:39]
	v_mfma_f32_16x16x32_bf16 v[28:31], v[132:135], v[200:203], v[28:31]
	v_mfma_f32_16x16x32_bf16 v[20:23], v[140:143], v[200:203], v[20:23]
	v_mfma_f32_16x16x32_bf16 v[12:15], v[132:135], v[208:211], v[12:15]
	v_mfma_f32_16x16x32_bf16 v[4:7], v[140:143], v[208:211], v[4:7]
	v_mfma_f32_16x16x32_bf16 v[56:59], v[144:147], v[160:163], v[56:59]
	v_mfma_f32_16x16x32_bf16 v[48:51], v[152:155], v[160:163], v[48:51]
	v_mfma_f32_16x16x32_bf16 v[40:43], v[144:147], v[168:171], v[40:43]
	v_mfma_f32_16x16x32_bf16 v[32:35], v[152:155], v[168:171], v[32:35]
	v_mfma_f32_16x16x32_bf16 v[24:27], v[144:147], v[196:199], v[24:27]
	v_mfma_f32_16x16x32_bf16 v[16:19], v[152:155], v[196:199], v[16:19]
	v_mfma_f32_16x16x32_bf16 v[8:11], v[144:147], v[204:207], v[8:11]
	v_mfma_f32_16x16x32_bf16 v[0:3], v[152:155], v[204:207], v[0:3]
	v_mfma_f32_16x16x32_bf16 v[56:59], v[148:151], v[164:167], v[56:59]
	v_mfma_f32_16x16x32_bf16 v[48:51], v[156:159], v[164:167], v[48:51]
	v_mfma_f32_16x16x32_bf16 v[40:43], v[148:151], v[172:175], v[40:43]
	v_mfma_f32_16x16x32_bf16 v[32:35], v[156:159], v[172:175], v[32:35]
	v_mfma_f32_16x16x32_bf16 v[24:27], v[148:151], v[200:203], v[24:27]
	v_mfma_f32_16x16x32_bf16 v[16:19], v[156:159], v[200:203], v[16:19]
	v_mfma_f32_16x16x32_bf16 v[8:11], v[148:151], v[208:211], v[8:11]
	v_mfma_f32_16x16x32_bf16 v[0:3], v[156:159], v[208:211], v[0:3]
	s_setprio 0
	s_barrier
	s_add_u32 s2, s2, 0x100
	s_addc_u32 s3, s3, 0
	s_add_u32 s29, s29, 0x100
	s_addc_u32 s30, s30, 0
	s_cmp_ge_i32 s31, s52
	s_mov_b32 s24, s31
	s_cbranch_scc0 .LBB0_1028

; #define PG8_STAGE(bufoff, gbase, voff) do { _Pragma("unroll") for (int _i = 0; _i < 2; ++_i) \
;         __builtin_amdgcn_global_load_lds((const unsigned*)((const char*)(gbase) + (voff)[_i]), (LAS unsigned*)(lds + (bufoff) + ldsw + _i * 8192), 16, 0, 0); } while (0)
; #define PG8_LDA(dst, b, h) do { _Pragma("unroll") for (int m = 0; m < 4; ++m) _Pragma("unroll") for (int k = 0; k < 2; ++k) dst[m][k] = *(const LAS bf16x8*)(lds + PG8_SA(b, h) + aoff + m * 2048 + k * 1024); } while (0)
; #define PG8_LDB(dst, b, h) do { _Pragma("unroll") for (int n = 0; n < 2; ++n) _Pragma("unroll") for (int k = 0; k < 2; ++k) dst[n][k] = *(const LAS bf16x8*)(lds + PG8_SB(b, h) + boff + n * 2048 + k * 1024); } while (0)
; #define PG8_MMA(ai, bj, At, Bt) do { __builtin_amdgcn_s_setprio(1); _Pragma("unroll") for (int m = 0; m < 4; ++m) _Pragma("unroll") for (int n = 0; n < 2; ++n) _Pragma("unroll") for (int k = 0; k < 2; ++k) \
;         acc[ai][bj][m][n] = __builtin_amdgcn_mfma_f32_16x16x32_bf16(Bt[n][k], At[m][k], acc[ai][bj][m][n], 0, 0, 0); __builtin_amdgcn_s_setprio(0); } while (0)
; #define PG8_WAIT_V(n) asm volatile("s_waitcnt vmcnt(" #n ")" ::: "memory")
; #define PG8_WAIT_L(n) asm volatile("s_waitcnt lgkmcnt(" #n ")" ::: "memory")
; #define PG8_BAR __builtin_amdgcn_s_barrier()
; #define PG8_SCHED __builtin_amdgcn_sched_barrier(0)
; template <class Epi, bool ALIGN_EPI = PG8_ALIGN>
; __device__ __forceinline__ void gemm_phase(LAS unsigned char* lds, const Gemm g, const StaticOrder& S, const Epi& E) {
;     ...
;             const bool last = (t == nt - 2);
;             const char* a1 = cA + (size_t)(t + 1) * kstep;
;             const char* a2 = last ? nA : cA + (size_t)(t + 2) * kstep; const char* b2 = last ? nB : cB + (size_t)(t + 2) * kstep;
;             const char* a3 = a2 + kstep; const char* b3 = b2 + kstep;
;             PG8_LDB(B0, 0, 0); PG8_LDB(B1, 0, 1); PG8_SCHED; PG8_LDA(At, 0, 0); PG8_STAGE(PG8_SA(1, 1), a1 + hstepA, voffA);
;             PG8_WAIT_V(8); PG8_WAIT_L(0); PG8_BAR; PG8_MMA(0, 0, At, B0); PG8_MMA(0, 1, At, B1); PG8_BAR; PG8_SCHED;
;             PG8_LDA(At, 0, 1); PG8_STAGE(PG8_SB(0, 0), b2, voffB); PG8_STAGE(PG8_SB(0, 1), b2 + hstepB, voffB); PG8_STAGE(PG8_SA(0, 0), a2, voffA);
;             PG8_WAIT_V(8); PG8_WAIT_L(0); PG8_BAR; PG8_MMA(1, 0, At, B0); PG8_MMA(1, 1, At, B1); PG8_BAR; PG8_SCHED;
.LBB0_1108:
	s_add_i32 s53, s40, 2
	s_add_u32 s36, s24, 0x100
	s_addc_u32 s37, s25, 0
	s_add_i32 s22, 16, 0x10000
	s_cmp_eq_u32 s27, s40
	s_cselect_b32 s41, s3, s37
	s_cselect_b32 s40, s2, s36
	s_cselect_b32 s21, s17, s52
	s_cselect_b32 s20, s16, s51
	s_add_i32 s23, 16, 0x14000
	v_add_u32_e32 v154, s22, v147
	v_add_u32_e32 v170, s23, v147
	ds_read_b128 v[138:141], v154
	ds_read_b128 v[142:145], v154 offset:1024
	ds_read_b128 v[150:153], v154 offset:2048
	ds_read_b128 v[154:157], v154 offset:3072
	ds_read_b128 v[158:161], v170
	ds_read_b128 v[162:165], v170 offset:1024
	ds_read_b128 v[166:169], v170 offset:2048
	ds_read_b128 v[170:173], v170 offset:3072
	v_lshl_add_u64 v[174:175], s[24:25], 0, v[134:135]
	s_add_i32 m0, s31, 0xc000
	ds_read_b128 v[184:187], v149
	ds_read_b128 v[188:191], v149 offset:1024
	ds_read_b128 v[192:195], v149 offset:2048
	ds_read_b128 v[196:199], v149 offset:3072
	ds_read_b128 v[200:203], v149 offset:4096
	ds_read_b128 v[204:207], v149 offset:5120
	ds_read_b128 v[208:211], v149 offset:6144
	ds_read_b128 v[212:215], v149 offset:7168
	global_load_lds_dwordx4 v[174:175], off
	v_lshl_add_u64 v[174:175], s[24:25], 0, v[136:137]
	s_add_i32 m0, s31, 0xe000
	s_nop 0
	global_load_lds_dwordx4 v[174:175], off
	s_waitcnt vmcnt(8)
	s_waitcnt lgkmcnt(0)
	s_barrier
	s_setprio 1
	s_waitcnt lgkmcnt(0)
	v_mfma_f32_16x16x32_bf16 v[124:127], v[138:141], v[184:187], v[124:127]
	v_mfma_f32_16x16x32_bf16 v[120:123], v[150:153], v[184:187], v[120:123]
	v_mfma_f32_16x16x32_bf16 v[116:119], v[138:141], v[192:195], v[116:119]
	v_mfma_f32_16x16x32_bf16 v[112:115], v[150:153], v[192:195], v[112:115]
	v_mfma_f32_16x16x32_bf16 v[104:107], v[138:141], v[200:203], v[104:107]
	v_mfma_f32_16x16x32_bf16 v[96:99], v[150:153], v[200:203], v[96:99]
	v_mfma_f32_16x16x32_bf16 v[88:91], v[138:141], v[208:211], v[88:91]
	v_mfma_f32_16x16x32_bf16 v[80:83], v[150:153], v[208:211], v[80:83]
	v_mfma_f32_16x16x32_bf16 v[124:127], v[142:145], v[188:191], v[124:127]
	v_mfma_f32_16x16x32_bf16 v[120:123], v[154:157], v[188:191], v[120:123]
	v_mfma_f32_16x16x32_bf16 v[116:119], v[142:145], v[196:199], v[116:119]
	v_mfma_f32_16x16x32_bf16 v[112:115], v[154:157], v[196:199], v[112:115]
	v_mfma_f32_16x16x32_bf16 v[104:107], v[142:145], v[204:207], v[104:107]
	v_mfma_f32_16x16x32_bf16 v[96:99], v[154:157], v[204:207], v[96:99]
	v_mfma_f32_16x16x32_bf16 v[88:91], v[142:145], v[212:215], v[88:91]
	v_mfma_f32_16x16x32_bf16 v[80:83], v[154:157], v[212:215], v[80:83]
	v_mfma_f32_16x16x32_bf16 v[108:111], v[158:161], v[184:187], v[108:111]
	v_mfma_f32_16x16x32_bf16 v[100:103], v[166:169], v[184:187], v[100:103]
	v_mfma_f32_16x16x32_bf16 v[92:95], v[158:161], v[192:195], v[92:95]
	v_mfma_f32_16x16x32_bf16 v[84:87], v[166:169], v[192:195], v[84:87]
	v_mfma_f32_16x16x32_bf16 v[76:79], v[158:161], v[200:203], v[76:79]
	v_mfma_f32_16x16x32_bf16 v[72:75], v[166:169], v[200:203], v[72:75]
	v_mfma_f32_16x16x32_bf16 v[68:71], v[158:161], v[208:211], v[68:71]
	v_mfma_f32_16x16x32_bf16 v[64:67], v[166:169], v[208:211], v[64:67]
	v_mfma_f32_16x16x32_bf16 v[108:111], v[162:165], v[188:191], v[108:111]
	v_mfma_f32_16x16x32_bf16 v[100:103], v[170:173], v[188:191], v[100:103]
	v_mfma_f32_16x16x32_bf16 v[92:95], v[162:165], v[196:199], v[92:95]
	v_mfma_f32_16x16x32_bf16 v[84:87], v[170:173], v[196:199], v[84:87]
	v_mfma_f32_16x16x32_bf16 v[76:79], v[162:165], v[204:207], v[76:79]
	v_mfma_f32_16x16x32_bf16 v[72:75], v[170:173], v[204:207], v[72:75]
	v_mfma_f32_16x16x32_bf16 v[68:71], v[162:165], v[212:215], v[68:71]
	v_mfma_f32_16x16x32_bf16 v[64:67], v[170:173], v[212:215], v[64:67]
	s_setprio 0
	s_barrier
	s_add_i32 s22, s22, s18
	v_lshl_add_u64 v[174:175], s[20:21], 0, v[176:177]
	s_mov_b32 m0, s22
	ds_read_b128 v[184:187], v149 offset:16384
	ds_read_b128 v[188:191], v149 offset:17408
	ds_read_b128 v[192:195], v149 offset:18432
	ds_read_b128 v[196:199], v149 offset:19456
	ds_read_b128 v[200:203], v149 offset:20480
	ds_read_b128 v[204:207], v149 offset:21504
	ds_read_b128 v[208:211], v149 offset:22528
	ds_read_b128 v[212:215], v149 offset:23552
	global_load_lds_dwordx4 v[174:175], off
	s_add_i32 m0, s22, 0x2000
	v_lshl_add_u64 v[180:181], s[20:21], 0, v[128:129]
	s_add_u32 s20, s20, s6
	s_addc_u32 s21, s21, s7
	s_add_i32 s22, s23, s18
	global_load_lds_dwordx4 v[180:181], off
	v_lshl_add_u64 v[182:183], s[20:21], 0, v[176:177]
	s_mov_b32 m0, s22
	v_lshl_add_u64 v[216:217], s[20:21], 0, v[128:129]
	global_load_lds_dwordx4 v[182:183], off
	s_add_i32 m0, s22, 0x2000
	v_lshl_add_u64 v[218:219], s[40:41], 0, v[132:133]
	global_load_lds_dwordx4 v[216:217], off
	s_mov_b32 m0, s31
	v_lshl_add_u64 v[220:221], s[40:41], 0, v[130:131]
	global_load_lds_dwordx4 v[218:219], off
	s_mov_b32 m0, s42
	s_nop 0
	global_load_lds_dwordx4 v[220:221], off
	s_waitcnt vmcnt(8)
	s_waitcnt lgkmcnt(0)
	s_barrier
; #define PG8_STAGE(bufoff, gbase, voff) do { _Pragma("unroll") for (int _i = 0; _i < 2; ++_i) \
;         __builtin_amdgcn_global_load_lds((const unsigned*)((const char*)(gbase) + (voff)[_i]), (LAS unsigned*)(lds + (bufoff) + ldsw + _i * 8192), 16, 0, 0); } while (0)
; #define PG8_LDA(dst, b, h) do { _Pragma("unroll") for (int m = 0; m < 4; ++m) _Pragma("unroll") for (int k = 0; k < 2; ++k) dst[m][k] = *(const LAS bf16x8*)(lds + PG8_SA(b, h) + aoff + m * 2048 + k * 1024); } while (0)
; #define PG8_LDB(dst, b, h) do { _Pragma("unroll") for (int n = 0; n < 2; ++n) _Pragma("unroll") for (int k = 0; k < 2; ++k) dst[n][k] = *(const LAS bf16x8*)(lds + PG8_SB(b, h) + boff + n * 2048 + k * 1024); } while (0)
; #define PG8_MMA(ai, bj, At, Bt) do { __builtin_amdgcn_s_setprio(1); _Pragma("unroll") for (int m = 0; m < 4; ++m) _Pragma("unroll") for (int n = 0; n < 2; ++n) _Pragma("unroll") for (int k = 0; k < 2; ++k) \
;         acc[ai][bj][m][n] = __builtin_amdgcn_mfma_f32_16x16x32_bf16(Bt[n][k], At[m][k], acc[ai][bj][m][n], 0, 0, 0); __builtin_amdgcn_s_setprio(0); } while (0)
; #define PG8_WAIT_V(n) asm volatile("s_waitcnt vmcnt(" #n ")" ::: "memory")
; #define PG8_WAIT_L(n) asm volatile("s_waitcnt lgkmcnt(" #n ")" ::: "memory")
; #define PG8_BAR __builtin_amdgcn_s_barrier()
; #define PG8_SCHED __builtin_amdgcn_sched_barrier(0)
; template <class Epi, bool ALIGN_EPI = PG8_ALIGN>
; __device__ __forceinline__ void gemm_phase(LAS unsigned char* lds, const Gemm g, const StaticOrder& S, const Epi& E) {
;     ...
;             PG8_WAIT_V(8); PG8_WAIT_L(0); PG8_BAR; PG8_MMA(1, 0, At, B0); PG8_MMA(1, 1, At, B1); PG8_BAR; PG8_SCHED;
;             PG8_LDB(B0, 1, 0); PG8_LDB(B1, 1, 1); PG8_SCHED; PG8_LDA(At, 1, 0); PG8_STAGE(PG8_SA(0, 1), a2 + hstepA, voffA);
;             PG8_WAIT_V(8); PG8_WAIT_L(0); PG8_BAR; PG8_MMA(0, 0, At, B0); PG8_MMA(0, 1, At, B1); PG8_BAR; PG8_SCHED;
	s_setprio 1
	s_waitcnt lgkmcnt(0)
	v_mfma_f32_16x16x32_bf16 v[60:63], v[138:141], v[184:187], v[60:63]
	v_mfma_f32_16x16x32_bf16 v[56:59], v[150:153], v[184:187], v[56:59]
	v_mfma_f32_16x16x32_bf16 v[52:55], v[138:141], v[192:195], v[52:55]
	v_mfma_f32_16x16x32_bf16 v[48:51], v[150:153], v[192:195], v[48:51]
	v_mfma_f32_16x16x32_bf16 v[40:43], v[138:141], v[200:203], v[40:43]
	v_mfma_f32_16x16x32_bf16 v[32:35], v[150:153], v[200:203], v[32:35]
	v_mfma_f32_16x16x32_bf16 v[24:27], v[138:141], v[208:211], v[24:27]
	v_mfma_f32_16x16x32_bf16 v[16:19], v[150:153], v[208:211], v[16:19]
	v_mfma_f32_16x16x32_bf16 v[60:63], v[142:145], v[188:191], v[60:63]
	v_mfma_f32_16x16x32_bf16 v[56:59], v[154:157], v[188:191], v[56:59]
	v_mfma_f32_16x16x32_bf16 v[52:55], v[142:145], v[196:199], v[52:55]
	v_mfma_f32_16x16x32_bf16 v[48:51], v[154:157], v[196:199], v[48:51]
	v_mfma_f32_16x16x32_bf16 v[40:43], v[142:145], v[204:207], v[40:43]
	v_mfma_f32_16x16x32_bf16 v[32:35], v[154:157], v[204:207], v[32:35]
	v_mfma_f32_16x16x32_bf16 v[24:27], v[142:145], v[212:215], v[24:27]
	v_mfma_f32_16x16x32_bf16 v[16:19], v[154:157], v[212:215], v[16:19]
	v_mfma_f32_16x16x32_bf16 v[44:47], v[158:161], v[184:187], v[44:47]
	v_mfma_f32_16x16x32_bf16 v[36:39], v[166:169], v[184:187], v[36:39]
	v_mfma_f32_16x16x32_bf16 v[28:31], v[158:161], v[192:195], v[28:31]
	v_mfma_f32_16x16x32_bf16 v[20:23], v[166:169], v[192:195], v[20:23]
	v_mfma_f32_16x16x32_bf16 v[12:15], v[158:161], v[200:203], v[12:15]
	v_mfma_f32_16x16x32_bf16 v[8:11], v[166:169], v[200:203], v[8:11]
	v_mfma_f32_16x16x32_bf16 v[4:7], v[158:161], v[208:211], v[4:7]
	v_mfma_f32_16x16x32_bf16 v[0:3], v[166:169], v[208:211], v[0:3]
	v_mfma_f32_16x16x32_bf16 v[44:47], v[162:165], v[188:191], v[44:47]
	v_mfma_f32_16x16x32_bf16 v[36:39], v[170:173], v[188:191], v[36:39]
	v_mfma_f32_16x16x32_bf16 v[28:31], v[162:165], v[196:199], v[28:31]
	v_mfma_f32_16x16x32_bf16 v[20:23], v[170:173], v[196:199], v[20:23]
	v_mfma_f32_16x16x32_bf16 v[12:15], v[162:165], v[204:207], v[12:15]
	v_mfma_f32_16x16x32_bf16 v[8:11], v[170:173], v[204:207], v[8:11]
	v_mfma_f32_16x16x32_bf16 v[4:7], v[162:165], v[212:215], v[4:7]
	v_mfma_f32_16x16x32_bf16 v[0:3], v[170:173], v[212:215], v[0:3]
	s_setprio 0
	s_barrier
	s_add_i32 s22, 16, 0x18000
	s_add_i32 s23, 16, 0x1c000
	v_add_u32_e32 v154, s22, v147
	v_add_u32_e32 v170, s23, v147
	ds_read_b128 v[138:141], v154
	ds_read_b128 v[142:145], v154 offset:1024
	ds_read_b128 v[150:153], v154 offset:2048
	ds_read_b128 v[154:157], v154 offset:3072
	ds_read_b128 v[158:161], v170
	ds_read_b128 v[162:165], v170 offset:1024
	ds_read_b128 v[166:169], v170 offset:2048
	ds_read_b128 v[170:173], v170 offset:3072
	s_add_u32 s20, s40, 0x160000
	s_addc_u32 s21, s41, 0
	s_mov_b32 m0, s43
	v_lshl_add_u64 v[222:223], s[20:21], 0, v[132:133]
	ds_read_b128 v[184:187], v149 offset:32768
	ds_read_b128 v[188:191], v149 offset:33792
	ds_read_b128 v[192:195], v149 offset:34816
	ds_read_b128 v[196:199], v149 offset:35840
	ds_read_b128 v[200:203], v149 offset:36864
	ds_read_b128 v[204:207], v149 offset:37888
	ds_read_b128 v[208:211], v149 offset:38912
	ds_read_b128 v[212:215], v149 offset:39936
	global_load_lds_dwordx4 v[222:223], off
	v_lshl_add_u64 v[222:223], s[20:21], 0, v[130:131]
	s_mov_b32 m0, s44
	s_nop 0
	global_load_lds_dwordx4 v[222:223], off
	s_waitcnt vmcnt(8)
	s_waitcnt lgkmcnt(0)
	s_barrier
	s_setprio 1
	s_waitcnt lgkmcnt(0)
	v_mfma_f32_16x16x32_bf16 v[124:127], v[138:141], v[184:187], v[124:127]
	v_mfma_f32_16x16x32_bf16 v[120:123], v[150:153], v[184:187], v[120:123]
	v_mfma_f32_16x16x32_bf16 v[116:119], v[138:141], v[192:195], v[116:119]
	v_mfma_f32_16x16x32_bf16 v[112:115], v[150:153], v[192:195], v[112:115]
	v_mfma_f32_16x16x32_bf16 v[104:107], v[138:141], v[200:203], v[104:107]
	v_mfma_f32_16x16x32_bf16 v[96:99], v[150:153], v[200:203], v[96:99]
	v_mfma_f32_16x16x32_bf16 v[88:91], v[138:141], v[208:211], v[88:91]
	v_mfma_f32_16x16x32_bf16 v[80:83], v[150:153], v[208:211], v[80:83]
	v_mfma_f32_16x16x32_bf16 v[124:127], v[142:145], v[188:191], v[124:127]
	v_mfma_f32_16x16x32_bf16 v[120:123], v[154:157], v[188:191], v[120:123]
	v_mfma_f32_16x16x32_bf16 v[116:119], v[142:145], v[196:199], v[116:119]
	v_mfma_f32_16x16x32_bf16 v[112:115], v[154:157], v[196:199], v[112:115]
	v_mfma_f32_16x16x32_bf16 v[104:107], v[142:145], v[204:207], v[104:107]
	v_mfma_f32_16x16x32_bf16 v[96:99], v[154:157], v[204:207], v[96:99]
	v_mfma_f32_16x16x32_bf16 v[88:91], v[142:145], v[212:215], v[88:91]
	v_mfma_f32_16x16x32_bf16 v[80:83], v[154:157], v[212:215], v[80:83]
	v_mfma_f32_16x16x32_bf16 v[108:111], v[158:161], v[184:187], v[108:111]
	v_mfma_f32_16x16x32_bf16 v[100:103], v[166:169], v[184:187], v[100:103]
	v_mfma_f32_16x16x32_bf16 v[92:95], v[158:161], v[192:195], v[92:95]
	v_mfma_f32_16x16x32_bf16 v[84:87], v[166:169], v[192:195], v[84:87]
	v_mfma_f32_16x16x32_bf16 v[76:79], v[158:161], v[200:203], v[76:79]
	v_mfma_f32_16x16x32_bf16 v[72:75], v[166:169], v[200:203], v[72:75]
	v_mfma_f32_16x16x32_bf16 v[68:71], v[158:161], v[208:211], v[68:71]
	v_mfma_f32_16x16x32_bf16 v[64:67], v[166:169], v[208:211], v[64:67]
	v_mfma_f32_16x16x32_bf16 v[108:111], v[162:165], v[188:191], v[108:111]
	v_mfma_f32_16x16x32_bf16 v[100:103], v[170:173], v[188:191], v[100:103]
	v_mfma_f32_16x16x32_bf16 v[92:95], v[162:165], v[196:199], v[92:95]
	v_mfma_f32_16x16x32_bf16 v[84:87], v[170:173], v[196:199], v[84:87]
	v_mfma_f32_16x16x32_bf16 v[76:79], v[162:165], v[204:207], v[76:79]
	v_mfma_f32_16x16x32_bf16 v[72:75], v[170:173], v[204:207], v[72:75]
	v_mfma_f32_16x16x32_bf16 v[68:71], v[162:165], v[212:215], v[68:71]
	v_mfma_f32_16x16x32_bf16 v[64:67], v[170:173], v[212:215], v[64:67]
	s_setprio 0
	s_barrier
; #define PG8_STAGE(bufoff, gbase, voff) do { _Pragma("unroll") for (int _i = 0; _i < 2; ++_i) \
;         __builtin_amdgcn_global_load_lds((const unsigned*)((const char*)(gbase) + (voff)[_i]), (LAS unsigned*)(lds + (bufoff) + ldsw + _i * 8192), 16, 0, 0); } while (0)
; #define PG8_LDA(dst, b, h) do { _Pragma("unroll") for (int m = 0; m < 4; ++m) _Pragma("unroll") for (int k = 0; k < 2; ++k) dst[m][k] = *(const LAS bf16x8*)(lds + PG8_SA(b, h) + aoff + m * 2048 + k * 1024); } while (0)
; #define PG8_MMA(ai, bj, At, Bt) do { __builtin_amdgcn_s_setprio(1); _Pragma("unroll") for (int m = 0; m < 4; ++m) _Pragma("unroll") for (int n = 0; n < 2; ++n) _Pragma("unroll") for (int k = 0; k < 2; ++k) \
;         acc[ai][bj][m][n] = __builtin_amdgcn_mfma_f32_16x16x32_bf16(Bt[n][k], At[m][k], acc[ai][bj][m][n], 0, 0, 0); __builtin_amdgcn_s_setprio(0); } while (0)
; #define PG8_WAIT_V(n) asm volatile("s_waitcnt vmcnt(" #n ")" ::: "memory")
; #define PG8_WAIT_L(n) asm volatile("s_waitcnt lgkmcnt(" #n ")" ::: "memory")
; #define PG8_BAR __builtin_amdgcn_s_barrier()
; #define PG8_SCHED __builtin_amdgcn_sched_barrier(0)
; template <class Epi, bool ALIGN_EPI = PG8_ALIGN>
; __device__ __forceinline__ void gemm_phase(LAS unsigned char* lds, const Gemm g, const StaticOrder& S, const Epi& E) {
;     ...
;             PG8_LDA(At, 1, 1); PG8_STAGE(PG8_SB(1, 0), b3, voffB); PG8_STAGE(PG8_SB(1, 1), b3 + hstepB, voffB); PG8_STAGE(PG8_SA(1, 0), a3, voffA);
;             PG8_WAIT_V(8); PG8_WAIT_L(0); PG8_BAR; PG8_MMA(1, 0, At, B0); PG8_MMA(1, 1, At, B1); PG8_BAR; PG8_SCHED;
;         }
	s_add_i32 s20, s22, s18
	v_lshl_add_u64 v[174:175], v[174:175], 0, s[0:1]
	s_mov_b32 m0, s20
	ds_read_b128 v[184:187], v149 offset:49152
	ds_read_b128 v[188:191], v149 offset:50176
	ds_read_b128 v[192:195], v149 offset:51200
	ds_read_b128 v[196:199], v149 offset:52224
	ds_read_b128 v[200:203], v149 offset:53248
	ds_read_b128 v[204:207], v149 offset:54272
	ds_read_b128 v[208:211], v149 offset:55296
	ds_read_b128 v[212:215], v149 offset:56320
	global_load_lds_dwordx4 v[174:175], off
	v_lshl_add_u64 v[174:175], v[180:181], 0, s[0:1]
	s_add_i32 m0, s20, 0x2000
	s_add_i32 s20, s23, s18
	global_load_lds_dwordx4 v[174:175], off
	v_lshl_add_u64 v[174:175], v[182:183], 0, s[0:1]
	s_mov_b32 m0, s20
	s_nop 0
	global_load_lds_dwordx4 v[174:175], off
	v_lshl_add_u64 v[174:175], v[216:217], 0, s[0:1]
	s_add_i32 m0, s20, 0x2000
	s_nop 0
	global_load_lds_dwordx4 v[174:175], off
	v_lshl_add_u64 v[174:175], v[218:219], 0, s[0:1]
	s_mov_b32 m0, s45
	s_nop 0
	global_load_lds_dwordx4 v[174:175], off
	v_lshl_add_u64 v[174:175], v[220:221], 0, s[0:1]
	s_mov_b32 m0, s46
	s_nop 0
	global_load_lds_dwordx4 v[174:175], off
	s_waitcnt vmcnt(8)
	s_waitcnt lgkmcnt(0)
	s_barrier
	s_setprio 1
	s_waitcnt lgkmcnt(0)
	v_mfma_f32_16x16x32_bf16 v[60:63], v[138:141], v[184:187], v[60:63]
	v_mfma_f32_16x16x32_bf16 v[56:59], v[150:153], v[184:187], v[56:59]
	v_mfma_f32_16x16x32_bf16 v[52:55], v[138:141], v[192:195], v[52:55]
	v_mfma_f32_16x16x32_bf16 v[48:51], v[150:153], v[192:195], v[48:51]
	v_mfma_f32_16x16x32_bf16 v[40:43], v[138:141], v[200:203], v[40:43]
	v_mfma_f32_16x16x32_bf16 v[32:35], v[150:153], v[200:203], v[32:35]
	v_mfma_f32_16x16x32_bf16 v[24:27], v[138:141], v[208:211], v[24:27]
	v_mfma_f32_16x16x32_bf16 v[16:19], v[150:153], v[208:211], v[16:19]
	v_mfma_f32_16x16x32_bf16 v[60:63], v[142:145], v[188:191], v[60:63]
	v_mfma_f32_16x16x32_bf16 v[56:59], v[154:157], v[188:191], v[56:59]
	v_mfma_f32_16x16x32_bf16 v[52:55], v[142:145], v[196:199], v[52:55]
	v_mfma_f32_16x16x32_bf16 v[48:51], v[154:157], v[196:199], v[48:51]
	v_mfma_f32_16x16x32_bf16 v[40:43], v[142:145], v[204:207], v[40:43]
	v_mfma_f32_16x16x32_bf16 v[32:35], v[154:157], v[204:207], v[32:35]
	v_mfma_f32_16x16x32_bf16 v[24:27], v[142:145], v[212:215], v[24:27]
	v_mfma_f32_16x16x32_bf16 v[16:19], v[154:157], v[212:215], v[16:19]
	v_mfma_f32_16x16x32_bf16 v[44:47], v[158:161], v[184:187], v[44:47]
	v_mfma_f32_16x16x32_bf16 v[36:39], v[166:169], v[184:187], v[36:39]
	v_mfma_f32_16x16x32_bf16 v[28:31], v[158:161], v[192:195], v[28:31]
	v_mfma_f32_16x16x32_bf16 v[20:23], v[166:169], v[192:195], v[20:23]
	v_mfma_f32_16x16x32_bf16 v[12:15], v[158:161], v[200:203], v[12:15]
	v_mfma_f32_16x16x32_bf16 v[8:11], v[166:169], v[200:203], v[8:11]
	v_mfma_f32_16x16x32_bf16 v[4:7], v[158:161], v[208:211], v[4:7]
	v_mfma_f32_16x16x32_bf16 v[0:3], v[166:169], v[208:211], v[0:3]
	v_mfma_f32_16x16x32_bf16 v[44:47], v[162:165], v[188:191], v[44:47]
	v_mfma_f32_16x16x32_bf16 v[36:39], v[170:173], v[188:191], v[36:39]
	v_mfma_f32_16x16x32_bf16 v[28:31], v[162:165], v[196:199], v[28:31]
	v_mfma_f32_16x16x32_bf16 v[20:23], v[170:173], v[196:199], v[20:23]
	v_mfma_f32_16x16x32_bf16 v[12:15], v[162:165], v[204:207], v[12:15]
	v_mfma_f32_16x16x32_bf16 v[8:11], v[170:173], v[204:207], v[8:11]
	v_mfma_f32_16x16x32_bf16 v[4:7], v[162:165], v[212:215], v[4:7]
	v_mfma_f32_16x16x32_bf16 v[0:3], v[170:173], v[212:215], v[0:3]
	s_setprio 0
	s_barrier
	s_add_u32 s51, s51, 0x100
	s_addc_u32 s52, s52, 0
	s_cmp_ge_i32 s53, s26
	s_mov_b64 s[24:25], s[36:37]
	s_mov_b32 s40, s53
	s_cbranch_scc0 .LBB0_1108
; __device__ __forceinline__ unsigned cvt_pk(float lo, float hi) { f32x2_t v = {lo, hi}; bf16x2_t b = __builtin_convertvector(v, bf16x2_t); return __builtin_bit_cast(unsigned, b); }
;     __device__ __forceinline__ void operator()(const f32x4 (&acc)[2][2][4][2], const Unit& u, int wr, int wc, int fr, int fq) const {
;     ...
;                 for (int bj = 0; bj < 2; ++bj) { const f32x4 v0 = acc[ai][bj][m][0] * sc, v1 = acc[ai][bj][m][1] * sc;
;                     u32x4 w; w.x = cvt_pk(v0[0], v0[1]); w.y = cvt_pk(v0[2], v0[3]); w.z = cvt_pk(v1[0], v1[1]); w.w = cvt_pk(v1[2], v1[3]);
	v_pk_mul_f32 v[126:127], v[126:127], 0.5 op_sel_hi:[1,0]
	v_pk_mul_f32 v[124:125], v[124:125], 0.5 op_sel_hi:[1,0]
	v_pk_mul_f32 v[122:123], v[122:123], 0.5 op_sel_hi:[1,0]
	v_pk_mul_f32 v[120:121], v[120:121], 0.5 op_sel_hi:[1,0]
	v_pk_mul_f32 v[138:139], v[110:111], 0.5 op_sel_hi:[1,0]
	v_pk_mul_f32 v[140:141], v[108:109], 0.5 op_sel_hi:[1,0]
	v_pk_mul_f32 v[142:143], v[102:103], 0.5 op_sel_hi:[1,0]
	v_pk_mul_f32 v[144:145], v[100:101], 0.5 op_sel_hi:[1,0]
	v_pk_mul_f32 v[100:101], v[118:119], 0.5 op_sel_hi:[1,0]
	v_pk_mul_f32 v[102:103], v[116:117], 0.5 op_sel_hi:[1,0]
	v_pk_mul_f32 v[108:109], v[114:115], 0.5 op_sel_hi:[1,0]
	v_pk_mul_f32 v[110:111], v[112:113], 0.5 op_sel_hi:[1,0]
	v_pk_mul_f32 v[112:113], v[94:95], 0.5 op_sel_hi:[1,0]
	v_pk_mul_f32 v[114:115], v[92:93], 0.5 op_sel_hi:[1,0]
	v_pk_mul_f32 v[116:117], v[86:87], 0.5 op_sel_hi:[1,0]
	v_pk_mul_f32 v[118:119], v[84:85], 0.5 op_sel_hi:[1,0]
	v_pk_mul_f32 v[84:85], v[106:107], 0.5 op_sel_hi:[1,0]
	v_pk_mul_f32 v[86:87], v[104:105], 0.5 op_sel_hi:[1,0]
	v_pk_mul_f32 v[92:93], v[98:99], 0.5 op_sel_hi:[1,0]
	v_pk_mul_f32 v[94:95], v[96:97], 0.5 op_sel_hi:[1,0]
	v_pk_mul_f32 v[96:97], v[78:79], 0.5 op_sel_hi:[1,0]
	v_pk_mul_f32 v[98:99], v[76:77], 0.5 op_sel_hi:[1,0]
	v_pk_mul_f32 v[104:105], v[74:75], 0.5 op_sel_hi:[1,0]
	v_pk_mul_f32 v[106:107], v[72:73], 0.5 op_sel_hi:[1,0]
	v_pk_mul_f32 v[72:73], v[90:91], 0.5 op_sel_hi:[1,0]
	v_pk_mul_f32 v[74:75], v[88:89], 0.5 op_sel_hi:[1,0]
	v_pk_mul_f32 v[76:77], v[82:83], 0.5 op_sel_hi:[1,0]
	v_pk_mul_f32 v[78:79], v[80:81], 0.5 op_sel_hi:[1,0]
	v_pk_mul_f32 v[70:71], v[70:71], 0.5 op_sel_hi:[1,0]
	v_pk_mul_f32 v[68:69], v[68:69], 0.5 op_sel_hi:[1,0]
	v_pk_mul_f32 v[66:67], v[66:67], 0.5 op_sel_hi:[1,0]
	v_pk_mul_f32 v[64:65], v[64:65], 0.5 op_sel_hi:[1,0]
	v_pk_mul_f32 v[62:63], v[62:63], 0.5 op_sel_hi:[1,0]
	v_pk_mul_f32 v[60:61], v[60:61], 0.5 op_sel_hi:[1,0]
	v_pk_mul_f32 v[58:59], v[58:59], 0.5 op_sel_hi:[1,0]
	v_pk_mul_f32 v[56:57], v[56:57], 0.5 op_sel_hi:[1,0]
	v_pk_mul_f32 v[80:81], v[46:47], 0.5 op_sel_hi:[1,0]
	v_pk_mul_f32 v[82:83], v[44:45], 0.5 op_sel_hi:[1,0]
	v_pk_mul_f32 v[88:89], v[38:39], 0.5 op_sel_hi:[1,0]
	v_pk_mul_f32 v[90:91], v[36:37], 0.5 op_sel_hi:[1,0]
	v_pk_mul_f32 v[36:37], v[54:55], 0.5 op_sel_hi:[1,0]
	v_pk_mul_f32 v[38:39], v[52:53], 0.5 op_sel_hi:[1,0]
	v_pk_mul_f32 v[44:45], v[50:51], 0.5 op_sel_hi:[1,0]
	v_pk_mul_f32 v[46:47], v[48:49], 0.5 op_sel_hi:[1,0]
	v_pk_mul_f32 v[48:49], v[30:31], 0.5 op_sel_hi:[1,0]
	v_pk_mul_f32 v[50:51], v[28:29], 0.5 op_sel_hi:[1,0]
	v_pk_mul_f32 v[52:53], v[22:23], 0.5 op_sel_hi:[1,0]
	v_pk_mul_f32 v[54:55], v[20:21], 0.5 op_sel_hi:[1,0]
	v_pk_mul_f32 v[20:21], v[42:43], 0.5 op_sel_hi:[1,0]
	v_pk_mul_f32 v[22:23], v[40:41], 0.5 op_sel_hi:[1,0]
	v_pk_mul_f32 v[28:29], v[34:35], 0.5 op_sel_hi:[1,0]
	v_pk_mul_f32 v[30:31], v[32:33], 0.5 op_sel_hi:[1,0]
	v_pk_mul_f32 v[32:33], v[14:15], 0.5 op_sel_hi:[1,0]
	v_pk_mul_f32 v[34:35], v[12:13], 0.5 op_sel_hi:[1,0]
	v_pk_mul_f32 v[40:41], v[10:11], 0.5 op_sel_hi:[1,0]
	v_pk_mul_f32 v[42:43], v[8:9], 0.5 op_sel_hi:[1,0]
	v_pk_mul_f32 v[8:9], v[26:27], 0.5 op_sel_hi:[1,0]
	v_pk_mul_f32 v[10:11], v[24:25], 0.5 op_sel_hi:[1,0]
	v_pk_mul_f32 v[12:13], v[18:19], 0.5 op_sel_hi:[1,0]
	v_pk_mul_f32 v[14:15], v[16:17], 0.5 op_sel_hi:[1,0]
	v_pk_mul_f32 v[6:7], v[6:7], 0.5 op_sel_hi:[1,0]
	v_pk_mul_f32 v[4:5], v[4:5], 0.5 op_sel_hi:[1,0]
	v_pk_mul_f32 v[2:3], v[2:3], 0.5 op_sel_hi:[1,0]
	v_pk_mul_f32 v[0:1], v[0:1], 0.5 op_sel_hi:[1,0]
